# fused prompt-row RMSNorm into out-proj/down epilogues (sibling row-sum exchange); norm phases sample rows only; mixA-Y barrier removed; P0 copies pipelined
# speedup vs baseline: 1.0978x; 1.0498x over previous
; #define INP(i) ((const float*)ld_ptr(pb, (i)))
; __global__ void __launch_bounds__(512, 2) hybrid_fwd(Params P) {
;     ...
;         { const float* ckp = INP(4); const float* cvp = INP(5); const float* scp = INP(8);
; #pragma unroll 4
;         for (int i = gt; i < DEPTH * NSB * 124 * 32; i += NGT) { const int c4 = i & 31, r = (i >> 5) % 124, lb = i / (32 * 124);
;             const size_t src = ((size_t)lb * 128 + r + 4) * 128 + c4 * 4, dst = ((size_t)lb * 128 + r) * 128 + c4 * 4;
;             *(f32x4*)(out + O_KS + dst) = *(const f32x4*)(ckp + src); *(f32x4*)(out + O_VS + dst) = *(const f32x4*)(cvp + src); }
; #pragma unroll 4
;         for (int i = gt; i < DEPTH * NSB * 26 * 64; i += NGT) { const int c4 = i & 63, r = (i >> 6) % 26, lb = i / (64 * 26);
;             *(f32x4*)(out + O_CS + ((size_t)lb * 30 + r) * 256 + c4 * 4) = *(const f32x4*)(scp + ((size_t)lb * 30 + r + 4) * 256 + c4 * 4); } }
.LBB0_56:
	s_or_b64 exec, exec, s[10:11]
	ds_read2_b64 v[0:3], v15 offset0:4 offset1:5
	ds_read_b64 v[4:5], v15 offset:64
	s_lshl_b32 s0, s26, 3
	s_add_i32 s0, s0, s25
	s_lshl_b32 s9, s24, 3
	v_lshlrev_b32_e32 v25, 4, v24
	s_waitcnt lgkmcnt(0)
	v_readfirstlane_b32 s30, v0
	v_readfirstlane_b32 s31, v1
	v_readfirstlane_b32 s32, v2
	v_readfirstlane_b32 s33, v3
	v_readfirstlane_b32 s40, v4
	v_readfirstlane_b32 s41, v5
	s_mov_b32 s57, 0x12bff
	s_mov_b32 s58, 0xf800
	s_mov_b32 s59, 0x7c00
	s_mov_b32 s46, 0x9d89d8a
	s_mov_b32 s47, 0x4210843
	s_mov_b32 s48, 0x7800
	s_mov_b32 s60, 0x10000
	s_mov_b32 s65, 0x1000
	s_mov_b32 s94, 0x800
	s_mov_b32 s35, 0x8898000
	s_mov_b32 s39, 0x4498000
	s_mov_b32 s1, 0x6498000
.Lcp_loop:
	s_min_u32 s2, s0, s57
	s_cmp_ge_u32 s2, s58
	s_cselect_b32 s3, s58, 0
	s_cselect_b32 s20, s46, s47
	s_cselect_b32 s21, 26, 62
	s_cselect_b32 s23, s48, s60
	s_cselect_b32 s29, s65, s94
	s_cselect_b32 s4, s40, s30
	s_cselect_b32 s5, s41, s31
	s_cselect_b32 s38, s35, s39
	s_cselect_b64 s[10:11], -1, 0
	s_cmp_ge_u32 s2, s59
	s_cselect_b64 s[44:45], -1, 0
	s_andn2_b64 s[44:45], s[44:45], s[10:11]
	s_cmp_lg_u64 s[44:45], 0
	s_cselect_b32 s3, s59, s3
	s_cselect_b32 s4, s32, s4
	s_cselect_b32 s5, s33, s5
	s_cselect_b32 s38, s1, s38
	s_sub_u32 s2, s2, s3
	s_mul_hi_u32 s3, s2, s20
	s_mul_i32 s21, s3, s21
	s_sub_u32 s2, s2, s21
	s_mul_i32 s3, s3, s23
	s_lshl_b32 s2, s2, 10
	s_add_u32 s2, s2, s3
	s_add_u32 s38, s38, s2
	s_add_u32 s66, s28, s38
	s_addc_u32 s67, s27, 0
	s_add_u32 s2, s2, s29
	s_add_u32 s4, s4, s2
	s_addc_u32 s5, s5, 0
	global_load_dwordx4 v[88:91], v25, s[4:5]
	s_add_u32 s0, s0, s9
	s_min_u32 s2, s0, s57
	s_cmp_ge_u32 s2, s58
	s_cselect_b32 s3, s58, 0
	s_cselect_b32 s20, s46, s47
	s_cselect_b32 s21, 26, 62
	s_cselect_b32 s23, s48, s60
	s_cselect_b32 s29, s65, s94
	s_cselect_b32 s4, s40, s30
	s_cselect_b32 s5, s41, s31
	s_cselect_b32 s38, s35, s39
	s_cselect_b64 s[10:11], -1, 0
	s_cmp_ge_u32 s2, s59
	s_cselect_b64 s[44:45], -1, 0
	s_andn2_b64 s[44:45], s[44:45], s[10:11]
	s_cmp_lg_u64 s[44:45], 0
	s_cselect_b32 s3, s59, s3
	s_cselect_b32 s4, s32, s4
	s_cselect_b32 s5, s33, s5
	s_cselect_b32 s38, s1, s38
	s_sub_u32 s2, s2, s3
	s_mul_hi_u32 s3, s2, s20
	s_mul_i32 s21, s3, s21
	s_sub_u32 s2, s2, s21
	s_mul_i32 s3, s3, s23
	s_lshl_b32 s2, s2, 10
	s_add_u32 s2, s2, s3
	s_add_u32 s38, s38, s2
	s_add_u32 s68, s28, s38
	s_addc_u32 s69, s27, 0
	s_add_u32 s2, s2, s29
	s_add_u32 s4, s4, s2
	s_addc_u32 s5, s5, 0
	global_load_dwordx4 v[92:95], v25, s[4:5]
	s_add_u32 s0, s0, s9
	s_min_u32 s2, s0, s57
	s_cmp_ge_u32 s2, s58
	s_cselect_b32 s3, s58, 0
	s_cselect_b32 s20, s46, s47
	s_cselect_b32 s21, 26, 62
	s_cselect_b32 s23, s48, s60
	s_cselect_b32 s29, s65, s94
	s_cselect_b32 s4, s40, s30
	s_cselect_b32 s5, s41, s31
	s_cselect_b32 s38, s35, s39
	s_cselect_b64 s[10:11], -1, 0
	s_cmp_ge_u32 s2, s59
	s_cselect_b64 s[44:45], -1, 0
	s_andn2_b64 s[44:45], s[44:45], s[10:11]
	s_cmp_lg_u64 s[44:45], 0
	s_cselect_b32 s3, s59, s3
	s_cselect_b32 s4, s32, s4
	s_cselect_b32 s5, s33, s5
	s_cselect_b32 s38, s1, s38
	s_sub_u32 s2, s2, s3
	s_mul_hi_u32 s3, s2, s20
	s_mul_i32 s21, s3, s21
	s_sub_u32 s2, s2, s21
	s_mul_i32 s3, s3, s23
	s_lshl_b32 s2, s2, 10
	s_add_u32 s2, s2, s3
	s_add_u32 s38, s38, s2
	s_add_u32 s70, s28, s38
	s_addc_u32 s71, s27, 0
	s_add_u32 s2, s2, s29
	s_add_u32 s4, s4, s2
	s_addc_u32 s5, s5, 0
	global_load_dwordx4 v[96:99], v25, s[4:5]
	s_add_u32 s0, s0, s9
	s_min_u32 s2, s0, s57
	s_cmp_ge_u32 s2, s58
	s_cselect_b32 s3, s58, 0
	s_cselect_b32 s20, s46, s47
	s_cselect_b32 s21, 26, 62
	s_cselect_b32 s23, s48, s60
	s_cselect_b32 s29, s65, s94
	s_cselect_b32 s4, s40, s30
	s_cselect_b32 s5, s41, s31
	s_cselect_b32 s38, s35, s39
	s_cselect_b64 s[10:11], -1, 0
	s_cmp_ge_u32 s2, s59
	s_cselect_b64 s[44:45], -1, 0
	s_andn2_b64 s[44:45], s[44:45], s[10:11]
	s_cmp_lg_u64 s[44:45], 0
	s_cselect_b32 s3, s59, s3
	s_cselect_b32 s4, s32, s4
	s_cselect_b32 s5, s33, s5
	s_cselect_b32 s38, s1, s38
	s_sub_u32 s2, s2, s3
	s_mul_hi_u32 s3, s2, s20
	s_mul_i32 s21, s3, s21
	s_sub_u32 s2, s2, s21
	s_mul_i32 s3, s3, s23
	s_lshl_b32 s2, s2, 10
	s_add_u32 s2, s2, s3
	s_add_u32 s38, s38, s2
	s_add_u32 s72, s28, s38
	s_addc_u32 s73, s27, 0
	s_add_u32 s2, s2, s29
	s_add_u32 s4, s4, s2
	s_addc_u32 s5, s5, 0
	global_load_dwordx4 v[100:103], v25, s[4:5]
	s_add_u32 s0, s0, s9
	s_min_u32 s2, s0, s57
	s_cmp_ge_u32 s2, s58
	s_cselect_b32 s3, s58, 0
	s_cselect_b32 s20, s46, s47
	s_cselect_b32 s21, 26, 62
	s_cselect_b32 s23, s48, s60
	s_cselect_b32 s29, s65, s94
	s_cselect_b32 s4, s40, s30
	s_cselect_b32 s5, s41, s31
	s_cselect_b32 s38, s35, s39
	s_cselect_b64 s[10:11], -1, 0
	s_cmp_ge_u32 s2, s59
	s_cselect_b64 s[44:45], -1, 0
	s_andn2_b64 s[44:45], s[44:45], s[10:11]
	s_cmp_lg_u64 s[44:45], 0
	s_cselect_b32 s3, s59, s3
	s_cselect_b32 s4, s32, s4
	s_cselect_b32 s5, s33, s5
	s_cselect_b32 s38, s1, s38
	s_sub_u32 s2, s2, s3
	s_mul_hi_u32 s3, s2, s20
	s_mul_i32 s21, s3, s21
	s_sub_u32 s2, s2, s21
	s_mul_i32 s3, s3, s23
	s_lshl_b32 s2, s2, 10
	s_add_u32 s2, s2, s3
	s_add_u32 s38, s38, s2
	s_add_u32 s74, s28, s38
	s_addc_u32 s75, s27, 0
	s_add_u32 s2, s2, s29
	s_add_u32 s4, s4, s2
	s_addc_u32 s5, s5, 0
	global_load_dwordx4 v[104:107], v25, s[4:5]
	s_add_u32 s0, s0, s9
	s_min_u32 s2, s0, s57
	s_cmp_ge_u32 s2, s58
	s_cselect_b32 s3, s58, 0
	s_cselect_b32 s20, s46, s47
	s_cselect_b32 s21, 26, 62
	s_cselect_b32 s23, s48, s60
	s_cselect_b32 s29, s65, s94
	s_cselect_b32 s4, s40, s30
	s_cselect_b32 s5, s41, s31
	s_cselect_b32 s38, s35, s39
	s_cselect_b64 s[10:11], -1, 0
	s_cmp_ge_u32 s2, s59
	s_cselect_b64 s[44:45], -1, 0
	s_andn2_b64 s[44:45], s[44:45], s[10:11]
	s_cmp_lg_u64 s[44:45], 0
; #define INP(i) ((const float*)ld_ptr(pb, (i)))
; __global__ void __launch_bounds__(512, 2) hybrid_fwd(Params P) {
;     ...
;         { const float* ckp = INP(4); const float* cvp = INP(5); const float* scp = INP(8);
; #pragma unroll 4
;         for (int i = gt; i < DEPTH * NSB * 124 * 32; i += NGT) { const int c4 = i & 31, r = (i >> 5) % 124, lb = i / (32 * 124);
;             const size_t src = ((size_t)lb * 128 + r + 4) * 128 + c4 * 4, dst = ((size_t)lb * 128 + r) * 128 + c4 * 4;
;             *(f32x4*)(out + O_KS + dst) = *(const f32x4*)(ckp + src); *(f32x4*)(out + O_VS + dst) = *(const f32x4*)(cvp + src); }
; #pragma unroll 4
;         for (int i = gt; i < DEPTH * NSB * 26 * 64; i += NGT) { const int c4 = i & 63, r = (i >> 6) % 26, lb = i / (64 * 26);
;             *(f32x4*)(out + O_CS + ((size_t)lb * 30 + r) * 256 + c4 * 4) = *(const f32x4*)(scp + ((size_t)lb * 30 + r + 4) * 256 + c4 * 4); } }
	s_cselect_b32 s3, s59, s3
	s_cselect_b32 s4, s32, s4
	s_cselect_b32 s5, s33, s5
	s_cselect_b32 s38, s1, s38
	s_sub_u32 s2, s2, s3
	s_mul_hi_u32 s3, s2, s20
	s_mul_i32 s21, s3, s21
	s_sub_u32 s2, s2, s21
	s_mul_i32 s3, s3, s23
	s_lshl_b32 s2, s2, 10
	s_add_u32 s2, s2, s3
	s_add_u32 s38, s38, s2
	s_add_u32 s76, s28, s38
	s_addc_u32 s77, s27, 0
	s_add_u32 s2, s2, s29
	s_add_u32 s4, s4, s2
	s_addc_u32 s5, s5, 0
	global_load_dwordx4 v[108:111], v25, s[4:5]
	s_add_u32 s0, s0, s9
	s_min_u32 s2, s0, s57
	s_cmp_ge_u32 s2, s58
	s_cselect_b32 s3, s58, 0
	s_cselect_b32 s20, s46, s47
	s_cselect_b32 s21, 26, 62
	s_cselect_b32 s23, s48, s60
	s_cselect_b32 s29, s65, s94
	s_cselect_b32 s4, s40, s30
	s_cselect_b32 s5, s41, s31
	s_cselect_b32 s38, s35, s39
	s_cselect_b64 s[10:11], -1, 0
	s_cmp_ge_u32 s2, s59
	s_cselect_b64 s[44:45], -1, 0
	s_andn2_b64 s[44:45], s[44:45], s[10:11]
	s_cmp_lg_u64 s[44:45], 0
	s_cselect_b32 s3, s59, s3
	s_cselect_b32 s4, s32, s4
	s_cselect_b32 s5, s33, s5
	s_cselect_b32 s38, s1, s38
	s_sub_u32 s2, s2, s3
	s_mul_hi_u32 s3, s2, s20
	s_mul_i32 s21, s3, s21
	s_sub_u32 s2, s2, s21
	s_mul_i32 s3, s3, s23
	s_lshl_b32 s2, s2, 10
	s_add_u32 s2, s2, s3
	s_add_u32 s38, s38, s2
	s_add_u32 s80, s28, s38
	s_addc_u32 s81, s27, 0
	s_add_u32 s2, s2, s29
	s_add_u32 s4, s4, s2
	s_addc_u32 s5, s5, 0
	global_load_dwordx4 v[112:115], v25, s[4:5]
	s_add_u32 s0, s0, s9
	s_min_u32 s2, s0, s57
	s_cmp_ge_u32 s2, s58
	s_cselect_b32 s3, s58, 0
	s_cselect_b32 s20, s46, s47
	s_cselect_b32 s21, 26, 62
	s_cselect_b32 s23, s48, s60
	s_cselect_b32 s29, s65, s94
	s_cselect_b32 s4, s40, s30
	s_cselect_b32 s5, s41, s31
	s_cselect_b32 s38, s35, s39
	s_cselect_b64 s[10:11], -1, 0
	s_cmp_ge_u32 s2, s59
	s_cselect_b64 s[44:45], -1, 0
	s_andn2_b64 s[44:45], s[44:45], s[10:11]
	s_cmp_lg_u64 s[44:45], 0
	s_cselect_b32 s3, s59, s3
	s_cselect_b32 s4, s32, s4
	s_cselect_b32 s5, s33, s5
	s_cselect_b32 s38, s1, s38
	s_sub_u32 s2, s2, s3
	s_mul_hi_u32 s3, s2, s20
	s_mul_i32 s21, s3, s21
	s_sub_u32 s2, s2, s21
	s_mul_i32 s3, s3, s23
	s_lshl_b32 s2, s2, 10
	s_add_u32 s2, s2, s3
	s_add_u32 s38, s38, s2
	s_add_u32 s82, s28, s38
	s_addc_u32 s83, s27, 0
	s_add_u32 s2, s2, s29
	s_add_u32 s4, s4, s2
	s_addc_u32 s5, s5, 0
	global_load_dwordx4 v[116:119], v25, s[4:5]
	s_add_u32 s0, s0, s9
	s_min_u32 s2, s0, s57
	s_cmp_ge_u32 s2, s58
	s_cselect_b32 s3, s58, 0
	s_cselect_b32 s20, s46, s47
	s_cselect_b32 s21, 26, 62
	s_cselect_b32 s23, s48, s60
	s_cselect_b32 s29, s65, s94
	s_cselect_b32 s4, s40, s30
	s_cselect_b32 s5, s41, s31
	s_cselect_b32 s38, s35, s39
	s_cselect_b64 s[10:11], -1, 0
	s_cmp_ge_u32 s2, s59
	s_cselect_b64 s[44:45], -1, 0
	s_andn2_b64 s[44:45], s[44:45], s[10:11]
	s_cmp_lg_u64 s[44:45], 0
	s_cselect_b32 s3, s59, s3
	s_cselect_b32 s4, s32, s4
	s_cselect_b32 s5, s33, s5
	s_cselect_b32 s38, s1, s38
	s_sub_u32 s2, s2, s3
	s_mul_hi_u32 s3, s2, s20
	s_mul_i32 s21, s3, s21
	s_sub_u32 s2, s2, s21
	s_mul_i32 s3, s3, s23
	s_lshl_b32 s2, s2, 10
	s_add_u32 s2, s2, s3
	s_add_u32 s38, s38, s2
	s_add_u32 s84, s28, s38
	s_addc_u32 s85, s27, 0
	s_add_u32 s2, s2, s29
	s_add_u32 s4, s4, s2
	s_addc_u32 s5, s5, 0
	global_load_dwordx4 v[120:123], v25, s[4:5]
	s_add_u32 s0, s0, s9
	s_min_u32 s2, s0, s57
	s_cmp_ge_u32 s2, s58
	s_cselect_b32 s3, s58, 0
	s_cselect_b32 s20, s46, s47
	s_cselect_b32 s21, 26, 62
	s_cselect_b32 s23, s48, s60
	s_cselect_b32 s29, s65, s94
	s_cselect_b32 s4, s40, s30
	s_cselect_b32 s5, s41, s31
	s_cselect_b32 s38, s35, s39
	s_cselect_b64 s[10:11], -1, 0
	s_cmp_ge_u32 s2, s59
	s_cselect_b64 s[44:45], -1, 0
	s_andn2_b64 s[44:45], s[44:45], s[10:11]
	s_cmp_lg_u64 s[44:45], 0
	s_cselect_b32 s3, s59, s3
	s_cselect_b32 s4, s32, s4
	s_cselect_b32 s5, s33, s5
	s_cselect_b32 s38, s1, s38
	s_sub_u32 s2, s2, s3
	s_mul_hi_u32 s3, s2, s20
	s_mul_i32 s21, s3, s21
	s_sub_u32 s2, s2, s21
	s_mul_i32 s3, s3, s23
	s_lshl_b32 s2, s2, 10
	s_add_u32 s2, s2, s3
	s_add_u32 s38, s38, s2
	s_add_u32 s86, s28, s38
	s_addc_u32 s87, s27, 0
	s_add_u32 s2, s2, s29
	s_add_u32 s4, s4, s2
	s_addc_u32 s5, s5, 0
	global_load_dwordx4 v[124:127], v25, s[4:5]
	s_add_u32 s0, s0, s9
	s_min_u32 s2, s0, s57
	s_cmp_ge_u32 s2, s58
	s_cselect_b32 s3, s58, 0
	s_cselect_b32 s20, s46, s47
	s_cselect_b32 s21, 26, 62
	s_cselect_b32 s23, s48, s60
	s_cselect_b32 s29, s65, s94
	s_cselect_b32 s4, s40, s30
	s_cselect_b32 s5, s41, s31
	s_cselect_b32 s38, s35, s39
	s_cselect_b64 s[10:11], -1, 0
	s_cmp_ge_u32 s2, s59
	s_cselect_b64 s[44:45], -1, 0
	s_andn2_b64 s[44:45], s[44:45], s[10:11]
	s_cmp_lg_u64 s[44:45], 0
	s_cselect_b32 s3, s59, s3
	s_cselect_b32 s4, s32, s4
	s_cselect_b32 s5, s33, s5
	s_cselect_b32 s38, s1, s38
	s_sub_u32 s2, s2, s3
	s_mul_hi_u32 s3, s2, s20
	s_mul_i32 s21, s3, s21
	s_sub_u32 s2, s2, s21
	s_mul_i32 s3, s3, s23
	s_lshl_b32 s2, s2, 10
	s_add_u32 s2, s2, s3
	s_add_u32 s38, s38, s2
	s_add_u32 s88, s28, s38
	s_addc_u32 s89, s27, 0
	s_add_u32 s2, s2, s29
	s_add_u32 s4, s4, s2
	s_addc_u32 s5, s5, 0
	global_load_dwordx4 v[128:131], v25, s[4:5]
	s_add_u32 s0, s0, s9
	s_min_u32 s2, s0, s57
	s_cmp_ge_u32 s2, s58
	s_cselect_b32 s3, s58, 0
	s_cselect_b32 s20, s46, s47
	s_cselect_b32 s21, 26, 62
	s_cselect_b32 s23, s48, s60
	s_cselect_b32 s29, s65, s94
	s_cselect_b32 s4, s40, s30
	s_cselect_b32 s5, s41, s31
	s_cselect_b32 s38, s35, s39
	s_cselect_b64 s[10:11], -1, 0
	s_cmp_ge_u32 s2, s59
	s_cselect_b64 s[44:45], -1, 0
	s_andn2_b64 s[44:45], s[44:45], s[10:11]
	s_cmp_lg_u64 s[44:45], 0
	s_cselect_b32 s3, s59, s3
	s_cselect_b32 s4, s32, s4
	s_cselect_b32 s5, s33, s5
	s_cselect_b32 s38, s1, s38
	s_sub_u32 s2, s2, s3
	s_mul_hi_u32 s3, s2, s20
	s_mul_i32 s21, s3, s21
	s_sub_u32 s2, s2, s21
	s_mul_i32 s3, s3, s23
	s_lshl_b32 s2, s2, 10
	s_add_u32 s2, s2, s3
	s_add_u32 s38, s38, s2
	s_add_u32 s90, s28, s38
	s_addc_u32 s91, s27, 0
	s_add_u32 s2, s2, s29
	s_add_u32 s4, s4, s2
	s_addc_u32 s5, s5, 0
	global_load_dwordx4 v[132:135], v25, s[4:5]
	s_add_u32 s0, s0, s9
	s_min_u32 s2, s0, s57
	s_cmp_ge_u32 s2, s58
	s_cselect_b32 s3, s58, 0
	s_cselect_b32 s20, s46, s47
	s_cselect_b32 s21, 26, 62
	s_cselect_b32 s23, s48, s60
	s_cselect_b32 s29, s65, s94
	s_cselect_b32 s4, s40, s30
	s_cselect_b32 s5, s41, s31
	s_cselect_b32 s38, s35, s39
	s_cselect_b64 s[10:11], -1, 0
	s_cmp_ge_u32 s2, s59
	s_cselect_b64 s[44:45], -1, 0
	s_andn2_b64 s[44:45], s[44:45], s[10:11]
	s_cmp_lg_u64 s[44:45], 0
	s_cselect_b32 s3, s59, s3
	s_cselect_b32 s4, s32, s4
	s_cselect_b32 s5, s33, s5
	s_cselect_b32 s38, s1, s38
	s_sub_u32 s2, s2, s3
	s_mul_hi_u32 s3, s2, s20
	s_mul_i32 s21, s3, s21
	s_sub_u32 s2, s2, s21
	s_mul_i32 s3, s3, s23
	s_lshl_b32 s2, s2, 10
	s_add_u32 s2, s2, s3
	s_add_u32 s38, s38, s2
	s_add_u32 s92, s28, s38
	s_addc_u32 s93, s27, 0
	s_add_u32 s2, s2, s29
	s_add_u32 s4, s4, s2
	s_addc_u32 s5, s5, 0
	global_load_dwordx4 v[136:139], v25, s[4:5]
	s_add_u32 s0, s0, s9
	s_waitcnt vmcnt(12)
; #define INP(i) ((const float*)ld_ptr(pb, (i)))
; __global__ void __launch_bounds__(512, 2) hybrid_fwd(Params P) {
;     ...
;         { const float* ckp = INP(4); const float* cvp = INP(5); const float* scp = INP(8);
; #pragma unroll 4
;         for (int i = gt; i < DEPTH * NSB * 124 * 32; i += NGT) { const int c4 = i & 31, r = (i >> 5) % 124, lb = i / (32 * 124);
;             const size_t src = ((size_t)lb * 128 + r + 4) * 128 + c4 * 4, dst = ((size_t)lb * 128 + r) * 128 + c4 * 4;
;             *(f32x4*)(out + O_KS + dst) = *(const f32x4*)(ckp + src); *(f32x4*)(out + O_VS + dst) = *(const f32x4*)(cvp + src); }
; #pragma unroll 4
;         for (int i = gt; i < DEPTH * NSB * 26 * 64; i += NGT) { const int c4 = i & 63, r = (i >> 6) % 26, lb = i / (64 * 26);
;             *(f32x4*)(out + O_CS + ((size_t)lb * 30 + r) * 256 + c4 * 4) = *(const f32x4*)(scp + ((size_t)lb * 30 + r + 4) * 256 + c4 * 4); } }
;         float* scr = (float*)(lds + wave * 16384);
;         constexpr int I_IN = 16 * 48, I_OUT = 16 * 32, I_G = 16 * 88, I_DN = 44 * 32, I_GLU = 4 * 8, I_MOD = 16 * 192;
;         constexpr int I_LAYER = I_IN + I_OUT + 2 * I_G + I_DN + I_GLU + I_MOD;
;         for (int it = gw; it < DEPTH * I_LAYER; it += NGW) {
;             const int l = it / I_LAYER; int r = it % I_LAYER;
;             if (r < I_IN) { const int kb = r / 48, nbk = r % 48; transpose_item(INP(13) + (size_t)l * D * NIN, D, NIN, WIN + (size_t)l * NIN * D, nbk * 32, kb * 64, win_dst_row(nbk * 32), scr, lane); continue; } r -= I_IN;
	global_store_dwordx4 v25, v[88:91], s[66:67]
	s_waitcnt vmcnt(12)
	global_store_dwordx4 v25, v[92:95], s[68:69]
	s_waitcnt vmcnt(12)
	global_store_dwordx4 v25, v[96:99], s[70:71]
	s_waitcnt vmcnt(12)
	global_store_dwordx4 v25, v[100:103], s[72:73]
	s_waitcnt vmcnt(12)
	global_store_dwordx4 v25, v[104:107], s[74:75]
	s_waitcnt vmcnt(12)
	global_store_dwordx4 v25, v[108:111], s[76:77]
	s_waitcnt vmcnt(12)
	global_store_dwordx4 v25, v[112:115], s[80:81]
	s_waitcnt vmcnt(12)
	global_store_dwordx4 v25, v[116:119], s[82:83]
	s_waitcnt vmcnt(12)
	global_store_dwordx4 v25, v[120:123], s[84:85]
	s_waitcnt vmcnt(12)
	global_store_dwordx4 v25, v[124:127], s[86:87]
	s_waitcnt vmcnt(12)
	global_store_dwordx4 v25, v[128:131], s[88:89]
	s_waitcnt vmcnt(12)
	global_store_dwordx4 v25, v[132:135], s[90:91]
	s_waitcnt vmcnt(12)
	global_store_dwordx4 v25, v[136:139], s[92:93]
	s_cmp_le_u32 s0, s57
	s_cbranch_scc1 .Lcp_loop
	s_lshl_b32 s0, s26, 3
	s_add_i32 s10, s0, s25
	s_cmp_gt_i32 s10, 0x867f
	s_cbranch_scc1 .LBB0_116
	s_lshl_b32 s0, s25, 14
	s_lshl_b32 s11, s24, 3
	s_add_i32 s0, s0, 0
	s_add_u32 s12, s6, 0xe100000
	s_addc_u32 s13, s7, 0
	s_add_u32 s14, s6, 0x1600000
	s_addc_u32 s15, s7, 0
	s_add_u32 s16, s6, 0x6800000
	s_addc_u32 s17, s7, 0
	v_ashrrev_i32_e32 v4, 5, v24
	s_movk_i32 s2, 0x84
	s_add_u32 s18, s6, 0x3c00000
	v_mul_lo_u32 v0, v4, s2
	v_lshlrev_b32_e32 v2, 2, v8
	s_addc_u32 s19, s7, 0
	v_add3_u32 v5, s0, v0, v2
	v_lshlrev_b32_e32 v0, 3, v24
	s_add_u32 s20, s6, 0x3400000
	v_ashrrev_i32_e32 v6, 3, v24
	v_and_b32_e32 v2, 56, v0
	s_addc_u32 s21, s7, 0
	v_mul_u32_u24_e32 v0, 0x84, v2
	v_lshlrev_b32_e32 v3, 2, v6
	s_add_u32 s22, s6, 0x2800000
	s_mov_b32 s1, 0
	v_mov_b32_e32 v1, 0
	v_add3_u32 v7, s0, v0, v3
	v_add_u32_e32 v10, 8, v6
	v_add_u32_e32 v11, 16, v6
	v_add_u32_e32 v12, 24, v6
	s_addc_u32 s23, s7, 0
	s_lshl_b32 s25, s10, 1
	s_lshl_b32 s26, s24, 4
	s_lshl_b32 s27, s10, 5
	s_lshl_b32 s28, s24, 8
	s_lshl_b32 s29, s10, 3
	s_lshl_b32 s30, s24, 6
	s_movk_i32 s31, 0x6000
	s_movk_i32 s33, 0x1000
	s_movk_i32 s34, 0x2000
	s_movk_i32 s35, 0x3000
	s_movk_i32 s36, 0x4000
	s_movk_i32 s37, 0x5000
	s_movk_i32 s38, 0x7000
	s_mov_b32 s39, 0x8000
	s_mov_b32 s40, 0x9000
	s_mov_b32 s41, 0xa000
	s_mov_b32 s42, 0xb000
	s_mov_b32 s43, 0xc000
	s_mov_b32 s44, 0xd000
	s_mov_b32 s45, 0xe000
	s_mov_b32 s46, 0xf000
	s_mov_b32 s47, 0x10000
	s_mov_b32 s48, 0x12000
	s_mov_b32 s49, 0x14000
	s_mov_b32 s50, 0x16000
	s_mov_b32 s51, 0x18000
	s_mov_b32 s52, 0x1a000
	s_mov_b32 s53, 0x1c000
	s_mov_b32 s54, 0x1e000
	s_mov_b32 s55, 0x20000
	s_mov_b32 s56, 0x22000
	s_mov_b32 s57, 0x24000
	s_mov_b32 s58, 0x26000
	s_mov_b32 s59, 0x28000
	s_mov_b32 s60, 0x2a000
	s_mov_b32 s61, 0x2c000
	s_mov_b32 s62, 0x2e000
	s_mov_b32 s63, 0x30000
	s_mov_b32 s64, 0x32000
	s_mov_b32 s65, 0x34000
	s_mov_b32 s66, 0x36000
	s_mov_b32 s67, 0x38000
	s_mov_b32 s68, 0x3a000
	s_mov_b32 s69, 0x3c000
	s_mov_b32 s70, 0x3e000
	s_movk_i32 s71, 0x1600
	s_movk_i32 s72, 0x2c00
	s_movk_i32 s73, 0x1800
	v_lshlrev_b32_e32 v0, 2, v8
	v_add_u32_e32 v8, 0x400, v5
	v_add_u32_e32 v13, 0x800, v5
	v_add_u32_e32 v14, 0xc00, v5
	v_add_u32_e32 v16, 0x1000, v5
	v_add_u32_e32 v17, 0x1400, v5
	v_add_u32_e32 v18, 0x1800, v5
	v_add_u32_e32 v19, 0x1c00, v5
	v_lshlrev_b32_e32 v2, 1, v2
	s_branch .LBB0_76

; #define PHASE_END if (ph + 1 < hi) grid_barrier((unsigned*)ws, (unsigned)G, tid, (volatile LAS unsigned*)(ldsl + XBST_OFF)); } ++ph;
; __global__ void __launch_bounds__(512, 2) hybrid_fwd(Params P) {
;     ...
;                 __syncthreads();
;             }
;         }
;         PHASE_END
.LBB0_977:
	s_add_i32 s22, s73, 2
	s_cmp_ge_i32 s22, s79
	s_waitcnt vmcnt(0)
	s_barrier
	s_branch .LBB0_1031
	s_waitcnt vmcnt(0) lgkmcnt(0)
	v_cmp_eq_u32_e32 vcc, 0, v121
	s_barrier
	s_and_saveexec_b64 s[0:1], vcc
	s_cbranch_execz .LBB0_1030
	v_readlane_b32 s3, v253, 8
	s_getreg_b32 s2, hwreg(HW_REG_XCC_ID, 0, 4)
	s_and_b32 s16, s2, 15
	v_mov_b32_e32 v0, s3
	ds_read_b32 v2, v0
	v_readlane_b32 s3, v253, 9
	s_waitcnt lgkmcnt(0)
	v_cmp_ne_u32_e32 vcc, 0, v2
	v_mov_b32_e32 v0, s3
	ds_read_b32 v0, v0
	s_cbranch_vccnz .LBB0_994
	v_readlane_b32 s8, v253, 13
	v_readlane_b32 s9, v253, 14
	s_add_u32 s2, s8, 0x1000
	s_addc_u32 s3, s9, 0
	s_add_u32 s4, s8, 0x1100
	s_addc_u32 s5, s9, 0
	s_add_u32 s6, s8, 0x1200
	s_addc_u32 s7, s9, 0
	s_add_u32 s8, s8, 0x1300
	s_addc_u32 s9, s9, 0
	s_mov_b32 s17, 1
	s_branch .LBB0_982

;     __device__ __forceinline__ void operator()(const Acc& acc, const Unit& u, int wr, int wc, int fr, int fq) const {
; #pragma unroll
;         for (int ai = 0; ai < 2; ++ai)
; #pragma unroll
;             for (int m = 0; m < 4; ++m) { const int row = u.pm * 256 + ai * 128 + wr * 64 + m * 16 + fr;
;                 const float* base = xp ? (row < MP ? xp + (size_t)row * D : xs + (size_t)(row - MP) * D) : X + (size_t)row * D;
;                 const float* gp = gate + (size_t)mod_row(row) * 6144;
; #pragma unroll
;                 for (int bj = 0; bj < 2; ++bj)
; #pragma unroll
;                     for (int n = 0; n < 2; ++n) { const int col = u.pn * 256 + bj * 128 + wc * 32 + n * 16 + fq * 4;
;                         const f32x4 ga = *(const f32x4*)(gp + col) * acc[ai][bj][m][n];
;                         if (u.split) { *(f32x4*)(part + ((size_t)(u.k0 >> 8) * MS + (row - MP)) * D + col) = ga;
;                         } else *(f32x4*)(X + (size_t)row * D + col) = *(const f32x4*)(base + col) + ga; } }
;     }
; template <bool FINAL>
; __device__ __forceinline__ void norm_rows(const float* xp, const float* xs, const float* X, const float* g, const float* sh, const float* sc, bf16_t* XN, float* out, int gw, int NGW, int lane, const float* part, int nsplit) {
;     ...
;         for (int j = 0; j < 4; ++j) s += (v[j][0] * v[j][0] + v[j][1] * v[j][1]) + (v[j][2] * v[j][2] + v[j][3] * v[j][3]);
;         const float rstd = 1.0f / sqrtf(wave_sum(s) * (1.0f / D) + EPS);
.LBB0_1439:
	s_lshl_b32 s2, s4, 8
	s_add_i32 s2, s2, s55
	s_lshl_b32 s3, s36, 8
	s_add_i32 s3, s3, s56
	v_add_u32_e32 v207, s2, v155
	v_lshl_add_u32 v159, v156, 2, s3
	v_mov_b32_e32 v197, 0
	s_mov_b32 s70, 0x10000
	s_mov_b32 s71, 0
	s_mov_b32 s98, 0x50000
	s_mov_b32 s99, 0
	s_cmp_lg_u32 s63, 0
	s_cbranch_scc1 .Lepi_out_split
	s_mov_b32 s66, 0x10000
	s_mov_b32 s67, 0
	s_mov_b32 s68, 0x50000
	s_mov_b32 s69, 0
	v_lshlrev_b32_e32 v140, 11, v207
	v_lshl_add_u32 v140, v159, 1, v140
	v_mov_b32_e32 v141, 0
	s_add_u32 s70, s16, 0x4200000
	s_addc_u32 s71, s17, 0
	v_lshl_add_u64 v[128:129], v[140:141], 0, s[70:71]
	v_lshlrev_b32_e32 v196, 12, v207
	v_lshl_add_u32 v196, v159, 2, v196
	v_add_u32_e32 v142, s55, v155
	v_lshrrev_b32_e32 v207, 12, v207
	v_lshlrev_b32_e32 v159, 2, v159
	v_mad_u32_u24 v130, v207, s80, v159
	v_mov_b32_e32 v131, 0
	v_lshl_add_u64 v[130:131], v[130:131], 0, s[18:19]
	global_load_dwordx4 v[240:243], v[130:131], off
	global_load_dwordx4 v[244:247], v[130:131], off offset:64
	global_load_dwordx4 v[248:251], v[130:131], off offset:512
	global_load_dwordx4 v[184:187], v[130:131], off offset:576
	s_cmp_lg_u64 s[22:23], 0
	s_cselect_b32 s2, s8, s16
	s_cselect_b32 s3, s9, s17
	v_lshl_add_u64 v[144:145], v[196:197], 0, s[2:3]
	v_lshl_add_u64 v[146:147], v[196:197], 0, s[16:17]
	v_mov_b32_e32 v188, 0
	v_mov_b32_e32 v189, 0
	v_mov_b32_e32 v190, 0
	v_mov_b32_e32 v191, 0
	v_mov_b32_e32 v192, 0
	v_mov_b32_e32 v193, 0
	v_mov_b32_e32 v194, 0
	v_mov_b32_e32 v195, 0
	global_load_dwordx4 v[208:211], v[144:145], off
	global_load_dwordx4 v[212:215], v[144:145], off offset:64
	global_load_dwordx4 v[216:219], v[144:145], off offset:512
	global_load_dwordx4 v[220:223], v[144:145], off offset:576
	v_lshl_add_u64 v[144:145], v[144:145], 0, s[66:67]
	global_load_dwordx4 v[224:227], v[144:145], off
	global_load_dwordx4 v[228:231], v[144:145], off offset:64
	global_load_dwordx4 v[232:235], v[144:145], off offset:512
	global_load_dwordx4 v[236:239], v[144:145], off offset:576
	v_lshl_add_u64 v[144:145], v[144:145], 0, s[66:67]
	s_waitcnt vmcnt(4)
	v_pk_mul_f32 v[126:127], v[126:127], v[242:243]
	v_pk_mul_f32 v[124:125], v[124:125], v[240:241]
	v_pk_add_f32 v[126:127], v[126:127], v[210:211]
	v_pk_add_f32 v[124:125], v[124:125], v[208:209]
	v_pk_mul_f32 v[122:123], v[122:123], v[246:247]
	v_pk_mul_f32 v[120:121], v[120:121], v[244:245]
	v_pk_add_f32 v[122:123], v[122:123], v[214:215]
	v_pk_add_f32 v[120:121], v[120:121], v[212:213]
	v_pk_mul_f32 v[118:119], v[118:119], v[250:251]
	v_pk_mul_f32 v[116:117], v[116:117], v[248:249]
	v_pk_add_f32 v[118:119], v[118:119], v[218:219]
	v_pk_add_f32 v[116:117], v[116:117], v[216:217]
	v_pk_mul_f32 v[114:115], v[114:115], v[186:187]
	v_pk_mul_f32 v[112:113], v[112:113], v[184:185]
	v_pk_add_f32 v[114:115], v[114:115], v[222:223]
	v_pk_add_f32 v[112:113], v[112:113], v[220:221]
	v_pk_mul_f32 v[140:141], v[124:125], v[124:125]
	v_pk_fma_f32 v[140:141], v[126:127], v[126:127], v[140:141]
	v_add_f32_e32 v188, v188, v140
	v_add_f32_e32 v188, v188, v141
	v_pk_mul_f32 v[140:141], v[120:121], v[120:121]
	v_pk_fma_f32 v[140:141], v[122:123], v[122:123], v[140:141]
	v_add_f32_e32 v188, v188, v140
	v_add_f32_e32 v188, v188, v141
	v_pk_mul_f32 v[140:141], v[116:117], v[116:117]
	v_pk_fma_f32 v[140:141], v[118:119], v[118:119], v[140:141]
	v_add_f32_e32 v188, v188, v140
	v_add_f32_e32 v188, v188, v141
	v_pk_mul_f32 v[140:141], v[112:113], v[112:113]
	v_pk_fma_f32 v[140:141], v[114:115], v[114:115], v[140:141]
	v_add_f32_e32 v188, v188, v140
	v_add_f32_e32 v188, v188, v141
	global_load_dwordx4 v[208:211], v[144:145], off
	global_load_dwordx4 v[212:215], v[144:145], off offset:64
	global_load_dwordx4 v[216:219], v[144:145], off offset:512
	global_load_dwordx4 v[220:223], v[144:145], off offset:576
	v_lshl_add_u64 v[144:145], v[144:145], 0, s[66:67]
	s_waitcnt vmcnt(4)
	v_pk_mul_f32 v[110:111], v[110:111], v[242:243]
	v_pk_mul_f32 v[108:109], v[108:109], v[240:241]
	v_pk_add_f32 v[110:111], v[110:111], v[226:227]
	v_pk_add_f32 v[108:109], v[108:109], v[224:225]
	v_pk_mul_f32 v[106:107], v[106:107], v[246:247]
	v_pk_mul_f32 v[104:105], v[104:105], v[244:245]
	v_pk_add_f32 v[106:107], v[106:107], v[230:231]
	v_pk_add_f32 v[104:105], v[104:105], v[228:229]
	v_pk_mul_f32 v[102:103], v[102:103], v[250:251]
	v_pk_mul_f32 v[100:101], v[100:101], v[248:249]
	v_pk_add_f32 v[102:103], v[102:103], v[234:235]
	v_pk_add_f32 v[100:101], v[100:101], v[232:233]
	v_pk_mul_f32 v[98:99], v[98:99], v[186:187]
	v_pk_mul_f32 v[96:97], v[96:97], v[184:185]
	v_pk_add_f32 v[98:99], v[98:99], v[238:239]
	v_pk_add_f32 v[96:97], v[96:97], v[236:237]
	v_pk_mul_f32 v[140:141], v[108:109], v[108:109]
	v_pk_fma_f32 v[140:141], v[110:111], v[110:111], v[140:141]
	v_add_f32_e32 v189, v189, v140
	v_add_f32_e32 v189, v189, v141
	v_pk_mul_f32 v[140:141], v[104:105], v[104:105]
	v_pk_fma_f32 v[140:141], v[106:107], v[106:107], v[140:141]
	v_add_f32_e32 v189, v189, v140
	v_add_f32_e32 v189, v189, v141
	v_pk_mul_f32 v[140:141], v[100:101], v[100:101]
	v_pk_fma_f32 v[140:141], v[102:103], v[102:103], v[140:141]
	v_add_f32_e32 v189, v189, v140
	v_add_f32_e32 v189, v189, v141
	v_pk_mul_f32 v[140:141], v[96:97], v[96:97]
	v_pk_fma_f32 v[140:141], v[98:99], v[98:99], v[140:141]
	v_add_f32_e32 v189, v189, v140
	v_add_f32_e32 v189, v189, v141
	global_load_dwordx4 v[224:227], v[144:145], off
	global_load_dwordx4 v[228:231], v[144:145], off offset:64
	global_load_dwordx4 v[232:235], v[144:145], off offset:512
	global_load_dwordx4 v[236:239], v[144:145], off offset:576
	v_lshl_add_u64 v[144:145], v[144:145], 0, s[68:69]
	s_waitcnt vmcnt(4)
;     __device__ __forceinline__ void operator()(const Acc& acc, const Unit& u, int wr, int wc, int fr, int fq) const {
;     ...
;             for (int m = 0; m < 4; ++m) { const int row = u.pm * 256 + ai * 128 + wr * 64 + m * 16 + fr;
;                 const float* base = xp ? (row < MP ? xp + (size_t)row * D : xs + (size_t)(row - MP) * D) : X + (size_t)row * D;
;                 const float* gp = gate + (size_t)mod_row(row) * 6144;
; #pragma unroll
;                 for (int bj = 0; bj < 2; ++bj)
; #pragma unroll
;                     for (int n = 0; n < 2; ++n) { const int col = u.pn * 256 + bj * 128 + wc * 32 + n * 16 + fq * 4;
;                         const f32x4 ga = *(const f32x4*)(gp + col) * acc[ai][bj][m][n];
;                         if (u.split) { *(f32x4*)(part + ((size_t)(u.k0 >> 8) * MS + (row - MP)) * D + col) = ga;
;                         } else *(f32x4*)(X + (size_t)row * D + col) = *(const f32x4*)(base + col) + ga; } }
; template <bool FINAL>
; __device__ __forceinline__ void norm_rows(const float* xp, const float* xs, const float* X, const float* g, const float* sh, const float* sc, bf16_t* XN, float* out, int gw, int NGW, int lane, const float* part, int nsplit) {
;     ...
;         for (int j = 0; j < 4; ++j) s += (v[j][0] * v[j][0] + v[j][1] * v[j][1]) + (v[j][2] * v[j][2] + v[j][3] * v[j][3]);
	v_pk_mul_f32 v[94:95], v[94:95], v[242:243]
	v_pk_mul_f32 v[92:93], v[92:93], v[240:241]
	v_pk_add_f32 v[94:95], v[94:95], v[210:211]
	v_pk_add_f32 v[92:93], v[92:93], v[208:209]
	v_pk_mul_f32 v[90:91], v[90:91], v[246:247]
	v_pk_mul_f32 v[88:89], v[88:89], v[244:245]
	v_pk_add_f32 v[90:91], v[90:91], v[214:215]
	v_pk_add_f32 v[88:89], v[88:89], v[212:213]
	v_pk_mul_f32 v[86:87], v[86:87], v[250:251]
	v_pk_mul_f32 v[84:85], v[84:85], v[248:249]
	v_pk_add_f32 v[86:87], v[86:87], v[218:219]
	v_pk_add_f32 v[84:85], v[84:85], v[216:217]
	v_pk_mul_f32 v[82:83], v[82:83], v[186:187]
	v_pk_mul_f32 v[80:81], v[80:81], v[184:185]
	v_pk_add_f32 v[82:83], v[82:83], v[222:223]
	v_pk_add_f32 v[80:81], v[80:81], v[220:221]
	v_pk_mul_f32 v[140:141], v[92:93], v[92:93]
	v_pk_fma_f32 v[140:141], v[94:95], v[94:95], v[140:141]
	v_add_f32_e32 v190, v190, v140
	v_add_f32_e32 v190, v190, v141
	v_pk_mul_f32 v[140:141], v[88:89], v[88:89]
	v_pk_fma_f32 v[140:141], v[90:91], v[90:91], v[140:141]
	v_add_f32_e32 v190, v190, v140
	v_add_f32_e32 v190, v190, v141
	v_pk_mul_f32 v[140:141], v[84:85], v[84:85]
	v_pk_fma_f32 v[140:141], v[86:87], v[86:87], v[140:141]
	v_add_f32_e32 v190, v190, v140
	v_add_f32_e32 v190, v190, v141
	v_pk_mul_f32 v[140:141], v[80:81], v[80:81]
	v_pk_fma_f32 v[140:141], v[82:83], v[82:83], v[140:141]
	v_add_f32_e32 v190, v190, v140
	v_add_f32_e32 v190, v190, v141
	global_load_dwordx4 v[208:211], v[144:145], off
	global_load_dwordx4 v[212:215], v[144:145], off offset:64
	global_load_dwordx4 v[216:219], v[144:145], off offset:512
	global_load_dwordx4 v[220:223], v[144:145], off offset:576
	v_lshl_add_u64 v[144:145], v[144:145], 0, s[66:67]
	s_waitcnt vmcnt(4)
	v_pk_mul_f32 v[78:79], v[78:79], v[242:243]
	v_pk_mul_f32 v[76:77], v[76:77], v[240:241]
	v_pk_add_f32 v[78:79], v[78:79], v[226:227]
	v_pk_add_f32 v[76:77], v[76:77], v[224:225]
	v_pk_mul_f32 v[74:75], v[74:75], v[246:247]
	v_pk_mul_f32 v[72:73], v[72:73], v[244:245]
	v_pk_add_f32 v[74:75], v[74:75], v[230:231]
	v_pk_add_f32 v[72:73], v[72:73], v[228:229]
	v_pk_mul_f32 v[70:71], v[70:71], v[250:251]
	v_pk_mul_f32 v[68:69], v[68:69], v[248:249]
	v_pk_add_f32 v[70:71], v[70:71], v[234:235]
	v_pk_add_f32 v[68:69], v[68:69], v[232:233]
	v_pk_mul_f32 v[66:67], v[66:67], v[186:187]
	v_pk_mul_f32 v[64:65], v[64:65], v[184:185]
	v_pk_add_f32 v[66:67], v[66:67], v[238:239]
	v_pk_add_f32 v[64:65], v[64:65], v[236:237]
	v_pk_mul_f32 v[140:141], v[76:77], v[76:77]
	v_pk_fma_f32 v[140:141], v[78:79], v[78:79], v[140:141]
	v_add_f32_e32 v191, v191, v140
	v_add_f32_e32 v191, v191, v141
	v_pk_mul_f32 v[140:141], v[72:73], v[72:73]
	v_pk_fma_f32 v[140:141], v[74:75], v[74:75], v[140:141]
	v_add_f32_e32 v191, v191, v140
	v_add_f32_e32 v191, v191, v141
	v_pk_mul_f32 v[140:141], v[68:69], v[68:69]
	v_pk_fma_f32 v[140:141], v[70:71], v[70:71], v[140:141]
	v_add_f32_e32 v191, v191, v140
	v_add_f32_e32 v191, v191, v141
	v_pk_mul_f32 v[140:141], v[64:65], v[64:65]
	v_pk_fma_f32 v[140:141], v[66:67], v[66:67], v[140:141]
	v_add_f32_e32 v191, v191, v140
	v_add_f32_e32 v191, v191, v141
	global_load_dwordx4 v[224:227], v[144:145], off
	global_load_dwordx4 v[228:231], v[144:145], off offset:64
	global_load_dwordx4 v[232:235], v[144:145], off offset:512
	global_load_dwordx4 v[236:239], v[144:145], off offset:576
	v_lshl_add_u64 v[144:145], v[144:145], 0, s[66:67]
	s_waitcnt vmcnt(4)
	v_pk_mul_f32 v[62:63], v[62:63], v[242:243]
	v_pk_mul_f32 v[60:61], v[60:61], v[240:241]
	v_pk_add_f32 v[62:63], v[62:63], v[210:211]
	v_pk_add_f32 v[60:61], v[60:61], v[208:209]
	v_pk_mul_f32 v[58:59], v[58:59], v[246:247]
	v_pk_mul_f32 v[56:57], v[56:57], v[244:245]
	v_pk_add_f32 v[58:59], v[58:59], v[214:215]
	v_pk_add_f32 v[56:57], v[56:57], v[212:213]
	v_pk_mul_f32 v[54:55], v[54:55], v[250:251]
	v_pk_mul_f32 v[52:53], v[52:53], v[248:249]
	v_pk_add_f32 v[54:55], v[54:55], v[218:219]
	v_pk_add_f32 v[52:53], v[52:53], v[216:217]
	v_pk_mul_f32 v[50:51], v[50:51], v[186:187]
	v_pk_mul_f32 v[48:49], v[48:49], v[184:185]
	v_pk_add_f32 v[50:51], v[50:51], v[222:223]
	v_pk_add_f32 v[48:49], v[48:49], v[220:221]
	v_pk_mul_f32 v[140:141], v[60:61], v[60:61]
	v_pk_fma_f32 v[140:141], v[62:63], v[62:63], v[140:141]
	v_add_f32_e32 v192, v192, v140
	v_add_f32_e32 v192, v192, v141
	v_pk_mul_f32 v[140:141], v[56:57], v[56:57]
	v_pk_fma_f32 v[140:141], v[58:59], v[58:59], v[140:141]
	v_add_f32_e32 v192, v192, v140
	v_add_f32_e32 v192, v192, v141
	v_pk_mul_f32 v[140:141], v[52:53], v[52:53]
	v_pk_fma_f32 v[140:141], v[54:55], v[54:55], v[140:141]
	v_add_f32_e32 v192, v192, v140
	v_add_f32_e32 v192, v192, v141
	v_pk_mul_f32 v[140:141], v[48:49], v[48:49]
	v_pk_fma_f32 v[140:141], v[50:51], v[50:51], v[140:141]
	v_add_f32_e32 v192, v192, v140
	v_add_f32_e32 v192, v192, v141
	global_load_dwordx4 v[208:211], v[144:145], off
	global_load_dwordx4 v[212:215], v[144:145], off offset:64
	global_load_dwordx4 v[216:219], v[144:145], off offset:512
	global_load_dwordx4 v[220:223], v[144:145], off offset:576
	v_lshl_add_u64 v[144:145], v[144:145], 0, s[66:67]
	s_waitcnt vmcnt(4)
; #define SWZ(v, pat) __builtin_bit_cast(float, __builtin_amdgcn_ds_swizzle(__builtin_bit_cast(int, (v)), (pat)))
; __device__ __forceinline__ float xor32_sum(float v) { float a = v, b = v; asm volatile("s_nop 1\n\tv_permlane32_swap_b32 %0, %1\n\ts_nop 1" : "+v"(a), "+v"(b)); return a + b; }
; __device__ __forceinline__ float wave_sum(float v) {
;     v += SWZ(v, 0x041f); v += SWZ(v, 0x081f); v += SWZ(v, 0x101f); v += SWZ(v, 0x201f); v += SWZ(v, 0x401f); return xor32_sum(v);
; }
; template <bool FINAL>
; __device__ __forceinline__ void norm_rows(const float* xp, const float* xs, const float* X, const float* g, const float* sh, const float* sc, bf16_t* XN, float* out, int gw, int NGW, int lane, const float* part, int nsplit) {
;     ...
;         for (int j = 0; j < 4; ++j) s += (v[j][0] * v[j][0] + v[j][1] * v[j][1]) + (v[j][2] * v[j][2] + v[j][3] * v[j][3]);
;         const float rstd = 1.0f / sqrtf(wave_sum(s) * (1.0f / D) + EPS);
	v_pk_mul_f32 v[46:47], v[46:47], v[242:243]
	v_pk_mul_f32 v[44:45], v[44:45], v[240:241]
	v_pk_add_f32 v[46:47], v[46:47], v[226:227]
	v_pk_add_f32 v[44:45], v[44:45], v[224:225]
	v_pk_mul_f32 v[42:43], v[42:43], v[246:247]
	v_pk_mul_f32 v[40:41], v[40:41], v[244:245]
	v_pk_add_f32 v[42:43], v[42:43], v[230:231]
	v_pk_add_f32 v[40:41], v[40:41], v[228:229]
	v_pk_mul_f32 v[38:39], v[38:39], v[250:251]
	v_pk_mul_f32 v[36:37], v[36:37], v[248:249]
	v_pk_add_f32 v[38:39], v[38:39], v[234:235]
	v_pk_add_f32 v[36:37], v[36:37], v[232:233]
	v_pk_mul_f32 v[34:35], v[34:35], v[186:187]
	v_pk_mul_f32 v[32:33], v[32:33], v[184:185]
	v_pk_add_f32 v[34:35], v[34:35], v[238:239]
	v_pk_add_f32 v[32:33], v[32:33], v[236:237]
	v_pk_mul_f32 v[140:141], v[44:45], v[44:45]
	v_pk_fma_f32 v[140:141], v[46:47], v[46:47], v[140:141]
	v_add_f32_e32 v193, v193, v140
	v_add_f32_e32 v193, v193, v141
	v_pk_mul_f32 v[140:141], v[40:41], v[40:41]
	v_pk_fma_f32 v[140:141], v[42:43], v[42:43], v[140:141]
	v_add_f32_e32 v193, v193, v140
	v_add_f32_e32 v193, v193, v141
	v_pk_mul_f32 v[140:141], v[36:37], v[36:37]
	v_pk_fma_f32 v[140:141], v[38:39], v[38:39], v[140:141]
	v_add_f32_e32 v193, v193, v140
	v_add_f32_e32 v193, v193, v141
	v_pk_mul_f32 v[140:141], v[32:33], v[32:33]
	v_pk_fma_f32 v[140:141], v[34:35], v[34:35], v[140:141]
	v_add_f32_e32 v193, v193, v140
	v_add_f32_e32 v193, v193, v141
	global_load_dwordx4 v[224:227], v[144:145], off
	global_load_dwordx4 v[228:231], v[144:145], off offset:64
	global_load_dwordx4 v[232:235], v[144:145], off offset:512
	global_load_dwordx4 v[236:239], v[144:145], off offset:576
	s_waitcnt vmcnt(4)
	v_pk_mul_f32 v[30:31], v[30:31], v[242:243]
	v_pk_mul_f32 v[28:29], v[28:29], v[240:241]
	v_pk_add_f32 v[30:31], v[30:31], v[210:211]
	v_pk_add_f32 v[28:29], v[28:29], v[208:209]
	v_pk_mul_f32 v[26:27], v[26:27], v[246:247]
	v_pk_mul_f32 v[24:25], v[24:25], v[244:245]
	v_pk_add_f32 v[26:27], v[26:27], v[214:215]
	v_pk_add_f32 v[24:25], v[24:25], v[212:213]
	v_pk_mul_f32 v[22:23], v[22:23], v[250:251]
	v_pk_mul_f32 v[20:21], v[20:21], v[248:249]
	v_pk_add_f32 v[22:23], v[22:23], v[218:219]
	v_pk_add_f32 v[20:21], v[20:21], v[216:217]
	v_pk_mul_f32 v[18:19], v[18:19], v[186:187]
	v_pk_mul_f32 v[16:17], v[16:17], v[184:185]
	v_pk_add_f32 v[18:19], v[18:19], v[222:223]
	v_pk_add_f32 v[16:17], v[16:17], v[220:221]
	v_pk_mul_f32 v[140:141], v[28:29], v[28:29]
	v_pk_fma_f32 v[140:141], v[30:31], v[30:31], v[140:141]
	v_add_f32_e32 v194, v194, v140
	v_add_f32_e32 v194, v194, v141
	v_pk_mul_f32 v[140:141], v[24:25], v[24:25]
	v_pk_fma_f32 v[140:141], v[26:27], v[26:27], v[140:141]
	v_add_f32_e32 v194, v194, v140
	v_add_f32_e32 v194, v194, v141
	v_pk_mul_f32 v[140:141], v[20:21], v[20:21]
	v_pk_fma_f32 v[140:141], v[22:23], v[22:23], v[140:141]
	v_add_f32_e32 v194, v194, v140
	v_add_f32_e32 v194, v194, v141
	v_pk_mul_f32 v[140:141], v[16:17], v[16:17]
	v_pk_fma_f32 v[140:141], v[18:19], v[18:19], v[140:141]
	v_add_f32_e32 v194, v194, v140
	v_add_f32_e32 v194, v194, v141
	s_waitcnt vmcnt(0)
	v_pk_mul_f32 v[14:15], v[14:15], v[242:243]
	v_pk_mul_f32 v[12:13], v[12:13], v[240:241]
	v_pk_add_f32 v[14:15], v[14:15], v[226:227]
	v_pk_add_f32 v[12:13], v[12:13], v[224:225]
	v_pk_mul_f32 v[10:11], v[10:11], v[246:247]
	v_pk_mul_f32 v[8:9], v[8:9], v[244:245]
	v_pk_add_f32 v[10:11], v[10:11], v[230:231]
	v_pk_add_f32 v[8:9], v[8:9], v[228:229]
	v_pk_mul_f32 v[6:7], v[6:7], v[250:251]
	v_pk_mul_f32 v[4:5], v[4:5], v[248:249]
	v_pk_add_f32 v[6:7], v[6:7], v[234:235]
	v_pk_add_f32 v[4:5], v[4:5], v[232:233]
	v_pk_mul_f32 v[2:3], v[2:3], v[186:187]
	v_pk_mul_f32 v[0:1], v[0:1], v[184:185]
	v_pk_add_f32 v[2:3], v[2:3], v[238:239]
	v_pk_add_f32 v[0:1], v[0:1], v[236:237]
	v_pk_mul_f32 v[140:141], v[12:13], v[12:13]
	v_pk_fma_f32 v[140:141], v[14:15], v[14:15], v[140:141]
	v_add_f32_e32 v195, v195, v140
	v_add_f32_e32 v195, v195, v141
	v_pk_mul_f32 v[140:141], v[8:9], v[8:9]
	v_pk_fma_f32 v[140:141], v[10:11], v[10:11], v[140:141]
	v_add_f32_e32 v195, v195, v140
	v_add_f32_e32 v195, v195, v141
	v_pk_mul_f32 v[140:141], v[4:5], v[4:5]
	v_pk_fma_f32 v[140:141], v[6:7], v[6:7], v[140:141]
	v_add_f32_e32 v195, v195, v140
	v_add_f32_e32 v195, v195, v141
	v_pk_mul_f32 v[140:141], v[0:1], v[0:1]
	v_pk_fma_f32 v[140:141], v[2:3], v[2:3], v[140:141]
	v_add_f32_e32 v195, v195, v140
	v_add_f32_e32 v195, v195, v141
	ds_swizzle_b32 v208, v188 offset:swizzle(SWAP,16)
	ds_swizzle_b32 v209, v189 offset:swizzle(SWAP,16)
	ds_swizzle_b32 v210, v190 offset:swizzle(SWAP,16)
	ds_swizzle_b32 v211, v191 offset:swizzle(SWAP,16)
	ds_swizzle_b32 v212, v192 offset:swizzle(SWAP,16)
	ds_swizzle_b32 v213, v193 offset:swizzle(SWAP,16)
	ds_swizzle_b32 v214, v194 offset:swizzle(SWAP,16)
	ds_swizzle_b32 v215, v195 offset:swizzle(SWAP,16)
	s_waitcnt lgkmcnt(0)
	v_add_f32_e32 v188, v188, v208
	v_add_f32_e32 v189, v189, v209
	v_add_f32_e32 v190, v190, v210
	v_add_f32_e32 v191, v191, v211
	v_add_f32_e32 v192, v192, v212
	v_add_f32_e32 v193, v193, v213
	v_add_f32_e32 v194, v194, v214
	v_add_f32_e32 v195, v195, v215
	v_mov_b32_e32 v208, v188
	v_mov_b32_e32 v209, v189
	v_mov_b32_e32 v210, v190
	v_mov_b32_e32 v211, v191
	v_mov_b32_e32 v212, v192
	v_mov_b32_e32 v213, v193
	v_mov_b32_e32 v214, v194
	v_mov_b32_e32 v215, v195
	s_nop 1
	v_permlane32_swap_b32 v188, v208
	v_permlane32_swap_b32 v189, v209
	v_permlane32_swap_b32 v190, v210
	v_permlane32_swap_b32 v191, v211
	v_permlane32_swap_b32 v192, v212
	v_permlane32_swap_b32 v193, v213
	v_permlane32_swap_b32 v194, v214
	v_permlane32_swap_b32 v195, v215
	s_nop 1
	v_add_f32_e32 v188, v188, v208
	v_add_f32_e32 v189, v189, v209
	v_add_f32_e32 v190, v190, v210
	v_add_f32_e32 v191, v191, v211
	v_add_f32_e32 v192, v192, v212
	v_add_f32_e32 v193, v193, v213
	v_add_f32_e32 v194, v194, v214
	v_add_f32_e32 v195, v195, v215
	v_readlane_b32 s25, v253, 2
	s_nop 3
	s_and_b32 s27, s25, 3
	s_lshl_b32 s27, s27, 10
	s_add_i32 s27, s27, 0x20800
	v_lshl_add_u32 v143, v142, 2, s27
	ds_write_b32 v143, v188
	ds_write_b32 v143, v189 offset:64
	ds_write_b32 v143, v190 offset:128
	ds_write_b32 v143, v191 offset:192
	ds_write_b32 v143, v192 offset:512
	ds_write_b32 v143, v193 offset:576
	ds_write_b32 v143, v194 offset:640
	ds_write_b32 v143, v195 offset:704
	v_mbcnt_lo_u32_b32 v207, -1, 0
	v_mbcnt_hi_u32_b32 v207, -1, v207
	s_lshl_b32 s27, s25, 6
	v_add_u32_e32 v207, s27, v207
	v_lshlrev_b32_e32 v207, 2, v207
	s_sub_u32 s70, s16, 0x7800000
	s_subb_u32 s71, s17, 0
	s_lshl_b32 s74, s4, 10
	s_add_u32 s70, s70, s74
	s_addc_u32 s71, s71, 0
	s_sub_u32 s98, s16, 0x7dfffc0
	s_subb_u32 s99, s17, 0
	s_lshl_b32 s74, s4, 2
	s_add_u32 s98, s98, s74
	s_addc_u32 s99, s99, 0
	s_lshl_b32 s32, s96, 3
	s_add_i32 s32, s32, 4
	s_waitcnt lgkmcnt(0)
	s_barrier
; template <bool FINAL>
; __device__ __forceinline__ void norm_rows(const float* xp, const float* xs, const float* X, const float* g, const float* sh, const float* sc, bf16_t* XN, float* out, int gw, int NGW, int lane, const float* part, int nsplit) {
;     ...
;         const float rstd = 1.0f / sqrtf(wave_sum(s) * (1.0f / D) + EPS);
;         const int mr = mod_row(row);
;         if (!FINAL && xp && row >= MP) {
; #pragma unroll
;             for (int j = 0; j < 4; ++j) *(f32x4*)((float*)X + (size_t)row * D + 4 * lane + 256 * j) = v[j]; }
; #pragma unroll
;         for (int j = 0; j < 4; ++j) { const int col = 4 * lane + 256 * j; const f32x4 gg = *(const f32x4*)(g + col);
;             if (FINAL) { *(f32x4*)(out + (size_t)row * D + col) = v[j] * rstd * gg; }
;             else { const f32x4 s1 = *(const f32x4*)(sc + (size_t)mr * 6144 + col), s0 = *(const f32x4*)(sh + (size_t)mr * 6144 + col);
;                 const f32x4 h = v[j] * rstd * gg * (s1 + 1.0f) + s0;
	s_cmp_lt_u32 s25, 4
	s_cbranch_scc0 .Lfz_out_nopub
	v_add_u32_e32 v140, 0x20800, v207
	ds_read_b32 v212, v140
	ds_read_b32 v213, v140 offset:1024
	ds_read_b32 v214, v140 offset:2048
	ds_read_b32 v215, v140 offset:3072
	s_lshl_b32 s74, s36, 16
	v_add_u32_e32 v141, s74, v207
	s_waitcnt lgkmcnt(0)
	v_add_f32_e32 v212, v212, v213
	v_add_f32_e32 v212, v212, v214
	v_add_f32_e32 v212, v212, v215
	global_store_dword v141, v212, s[70:71] sc0 sc1
.Lfz_out_nopub:
	s_waitcnt vmcnt(0)
	s_barrier
	v_mov_b32_e32 v140, 0x20450
	ds_read_b64 v[140:141], v140
	s_waitcnt lgkmcnt(0)
	v_readfirstlane_b32 s2, v140
	v_readfirstlane_b32 s3, v141
	s_add_i32 s74, s96, 0
	s_lshl_b32 s74, s74, 12
	s_add_u32 s2, s2, s74
	s_addc_u32 s3, s3, 0
	s_nop 4
	global_load_dwordx4 v[208:211], v159, s[2:3]
	global_load_dwordx4 v[212:215], v159, s[2:3] offset:64
	global_load_dwordx4 v[216:219], v159, s[2:3] offset:512
	global_load_dwordx4 v[220:223], v159, s[2:3] offset:576
	s_mov_b32 s74, 0x1000
	v_add_co_u32_e32 v130, vcc, s74, v130
	s_nop 1
	v_addc_co_u32_e32 v131, vcc, 0, v131, vcc
	global_load_dwordx4 v[240:243], v[130:131], off
	global_load_dwordx4 v[244:247], v[130:131], off offset:64
	global_load_dwordx4 v[248:251], v[130:131], off offset:512
	global_load_dwordx4 v[184:187], v[130:131], off offset:576
	v_add_co_u32_e32 v130, vcc, 0x1000, v130
	s_nop 1
	v_addc_co_u32_e32 v131, vcc, 0, v131, vcc
	global_load_dwordx4 v[224:227], v[130:131], off
	global_load_dwordx4 v[228:231], v[130:131], off offset:64
	global_load_dwordx4 v[232:235], v[130:131], off offset:512
	global_load_dwordx4 v[236:239], v[130:131], off offset:576
	s_cmp_eq_u32 s25, 0
	s_cbranch_scc0 .Lfz_out_nopoll
	s_mov_b64 exec, 1
	v_mov_b32_e32 v140, 0
	v_mov_b32_e32 v141, 1
	global_atomic_add v140, v141, s[98:99]
	s_mov_b32 s65, 0
.Lfz_out_poll:
	global_load_dword v130, v140, s[98:99] sc1
	s_waitcnt vmcnt(0)
	v_readfirstlane_b32 s72, v130
	s_nop 3
	s_cmp_ge_u32 s72, s32
	s_cbranch_scc1 .Lfz_out_polled
	s_add_i32 s65, s65, 1
	s_cmp_lt_u32 s65, 0x8000
	s_cbranch_scc0 .Lfz_out_polled
	s_sleep 1
	s_branch .Lfz_out_poll
.Lfz_out_polled:
	buffer_inv sc1
	s_waitcnt vmcnt(0)
	s_mov_b64 exec, -1
.Lfz_out_nopoll:
	s_barrier
	s_cmp_lt_u32 s25, 4
	s_cbranch_scc0 .Lfz_out_norstd
	global_load_dword v140, v207, s[70:71] sc0 sc1
	v_add_u32_e32 v130, 0x10000, v207
	global_load_dword v141, v130, s[70:71] sc0 sc1
	v_add_u32_e32 v130, 0x20000, v207
	global_load_dword v144, v130, s[70:71] sc0 sc1
	v_add_u32_e32 v130, 0x30000, v207
	global_load_dword v145, v130, s[70:71] sc0 sc1
	s_waitcnt vmcnt(0)
	v_add_f32_e32 v140, v140, v141
	v_add_f32_e32 v140, v140, v144
	v_add_f32_e32 v140, v140, v145
	v_mov_b32_e32 v159, 0x358637bd
	v_fmamk_f32 v140, v140, 0x3a800000, v159
	v_mul_f32_e32 v130, 0x4f800000, v140
	v_cmp_gt_f32_e32 vcc, 0xf800000, v140
	s_nop 1
	v_cndmask_b32_e32 v140, v140, v130, vcc
	v_sqrt_f32_e32 v130, v140
	s_nop 0
	v_add_u32_e32 v131, -1, v130
	v_add_u32_e32 v196, 1, v130
	v_fma_f32 v197, -v131, v130, v140
	v_fma_f32 v159, -v196, v130, v140
	v_cmp_ge_f32_e64 s[98:99], 0, v197
	s_nop 1
	v_cndmask_b32_e64 v130, v130, v131, s[98:99]
	v_cmp_lt_f32_e64 s[98:99], 0, v159
	s_nop 1
	v_cndmask_b32_e64 v130, v130, v196, s[98:99]
	v_mul_f32_e32 v131, 0x37800000, v130
	v_cndmask_b32_e32 v130, v130, v131, vcc
	v_mov_b32_e32 v131, 0x260
	v_cmp_class_f32_e32 vcc, v140, v131
	s_nop 1
	v_cndmask_b32_e32 v140, v130, v140, vcc
	v_div_scale_f32 v130, s[98:99], v140, v140, 1.0
	v_rcp_f32_e32 v131, v130
	v_div_scale_f32 v196, vcc, 1.0, v140, 1.0
	s_nop 0
	v_fma_f32 v197, -v130, v131, 1.0
	v_fmac_f32_e32 v131, v197, v131
	v_mul_f32_e32 v197, v196, v131
	v_fma_f32 v159, -v130, v197, v196
	v_fmac_f32_e32 v197, v159, v131
	v_fma_f32 v130, -v130, v197, v196
	v_div_fmas_f32 v130, v130, v131, v197
	v_div_fixup_f32 v130, v130, v140, 1.0
	v_add_u32_e32 v131, 0x21800, v207
	ds_write_b32 v131, v130
.Lfz_out_norstd:
	s_waitcnt lgkmcnt(0)
	s_barrier
	v_lshlrev_b32_e32 v130, 2, v142
	v_add_u32_e32 v130, 0x21800, v130
	ds_read_b32 v188, v130
	ds_read_b32 v189, v130 offset:64
	ds_read_b32 v190, v130 offset:128
	ds_read_b32 v191, v130 offset:192
	ds_read_b32 v192, v130 offset:512
	ds_read_b32 v193, v130 offset:576
	ds_read_b32 v194, v130 offset:640
	ds_read_b32 v195, v130 offset:704
	s_waitcnt vmcnt(0) lgkmcnt(0)
; __device__ __forceinline__ unsigned cvt_pk_bf16(float lo, float hi) { const f32x2_t v = {lo, hi}; const bf16x2_t b = __builtin_convertvector(v, bf16x2_t); return __builtin_bit_cast(unsigned, b); }
;     __device__ __forceinline__ void operator()(const Acc& acc, const Unit& u, int wr, int wc, int fr, int fq) const {
;     ...
;                         } else *(f32x4*)(X + (size_t)row * D + col) = *(const f32x4*)(base + col) + ga; } }
; template <bool FINAL>
; __device__ __forceinline__ void norm_rows(const float* xp, const float* xs, const float* X, const float* g, const float* sh, const float* sc, bf16_t* XN, float* out, int gw, int NGW, int lane, const float* part, int nsplit) {
;     ...
;         for (int j = 0; j < 4; ++j) { const int col = 4 * lane + 256 * j; const f32x4 gg = *(const f32x4*)(g + col);
;             if (FINAL) { *(f32x4*)(out + (size_t)row * D + col) = v[j] * rstd * gg; }
;             else { const f32x4 s1 = *(const f32x4*)(sc + (size_t)mr * 6144 + col), s0 = *(const f32x4*)(sh + (size_t)mr * 6144 + col);
;                 const f32x4 h = v[j] * rstd * gg * (s1 + 1.0f) + s0;
;                 *(u32x2*)(XN + (size_t)row * D + col) = (u32x2){cvt_pk_bf16(h[0], h[1]), cvt_pk_bf16(h[2], h[3])}; } }
	v_pk_add_f32 v[226:227], v[226:227], 1.0 op_sel_hi:[1,0]
	v_pk_add_f32 v[224:225], v[224:225], 1.0 op_sel_hi:[1,0]
	v_pk_add_f32 v[230:231], v[230:231], 1.0 op_sel_hi:[1,0]
	v_pk_add_f32 v[228:229], v[228:229], 1.0 op_sel_hi:[1,0]
	v_pk_add_f32 v[234:235], v[234:235], 1.0 op_sel_hi:[1,0]
	v_pk_add_f32 v[232:233], v[232:233], 1.0 op_sel_hi:[1,0]
	v_pk_add_f32 v[238:239], v[238:239], 1.0 op_sel_hi:[1,0]
	v_pk_add_f32 v[236:237], v[236:237], 1.0 op_sel_hi:[1,0]
	global_store_dwordx4 v[146:147], v[124:127], off
	global_store_dwordx4 v[146:147], v[120:123], off offset:64
	global_store_dwordx4 v[146:147], v[116:119], off offset:512
	global_store_dwordx4 v[146:147], v[112:115], off offset:576
	s_nop 1
	v_mul_f32_e32 v124, v124, v188
	v_mul_f32_e32 v125, v125, v188
	v_mul_f32_e32 v126, v126, v188
	v_mul_f32_e32 v127, v127, v188
	v_pk_mul_f32 v[124:125], v[208:209], v[124:125]
	v_pk_mul_f32 v[126:127], v[210:211], v[126:127]
	v_pk_fma_f32 v[126:127], v[226:227], v[126:127], v[242:243]
	v_pk_fma_f32 v[124:125], v[224:225], v[124:125], v[240:241]
	s_nop 0
	v_cvt_pk_bf16_f32 v124, v124, v125
	v_cvt_pk_bf16_f32 v125, v126, v127
	global_store_dwordx2 v[128:129], v[124:125], off
	v_mul_f32_e32 v120, v120, v188
	v_mul_f32_e32 v121, v121, v188
	v_mul_f32_e32 v122, v122, v188
	v_mul_f32_e32 v123, v123, v188
	v_pk_mul_f32 v[120:121], v[212:213], v[120:121]
	v_pk_mul_f32 v[122:123], v[214:215], v[122:123]
	v_pk_fma_f32 v[122:123], v[230:231], v[122:123], v[246:247]
	v_pk_fma_f32 v[120:121], v[228:229], v[120:121], v[244:245]
	s_nop 0
	v_cvt_pk_bf16_f32 v120, v120, v121
	v_cvt_pk_bf16_f32 v121, v122, v123
	global_store_dwordx2 v[128:129], v[120:121], off offset:32
	v_mul_f32_e32 v116, v116, v188
	v_mul_f32_e32 v117, v117, v188
	v_mul_f32_e32 v118, v118, v188
	v_mul_f32_e32 v119, v119, v188
	v_pk_mul_f32 v[116:117], v[216:217], v[116:117]
	v_pk_mul_f32 v[118:119], v[218:219], v[118:119]
	v_pk_fma_f32 v[118:119], v[234:235], v[118:119], v[250:251]
	v_pk_fma_f32 v[116:117], v[232:233], v[116:117], v[248:249]
	s_nop 0
	v_cvt_pk_bf16_f32 v116, v116, v117
	v_cvt_pk_bf16_f32 v117, v118, v119
	global_store_dwordx2 v[128:129], v[116:117], off offset:256
	v_mul_f32_e32 v112, v112, v188
	v_mul_f32_e32 v113, v113, v188
	v_mul_f32_e32 v114, v114, v188
	v_mul_f32_e32 v115, v115, v188
	v_pk_mul_f32 v[112:113], v[220:221], v[112:113]
	v_pk_mul_f32 v[114:115], v[222:223], v[114:115]
	v_pk_fma_f32 v[114:115], v[238:239], v[114:115], v[186:187]
	v_pk_fma_f32 v[112:113], v[236:237], v[112:113], v[184:185]
	s_nop 0
	v_cvt_pk_bf16_f32 v112, v112, v113
	v_cvt_pk_bf16_f32 v113, v114, v115
	global_store_dwordx2 v[128:129], v[112:113], off offset:288
	v_lshl_add_u64 v[146:147], v[146:147], 0, s[66:67]
	v_add_co_u32_e32 v128, vcc, 0x8000, v128
	s_nop 1
	v_addc_co_u32_e32 v129, vcc, 0, v129, vcc
	global_store_dwordx4 v[146:147], v[108:111], off
	global_store_dwordx4 v[146:147], v[104:107], off offset:64
	global_store_dwordx4 v[146:147], v[100:103], off offset:512
	global_store_dwordx4 v[146:147], v[96:99], off offset:576
	s_nop 1
	v_mul_f32_e32 v108, v108, v189
	v_mul_f32_e32 v109, v109, v189
	v_mul_f32_e32 v110, v110, v189
	v_mul_f32_e32 v111, v111, v189
	v_pk_mul_f32 v[108:109], v[208:209], v[108:109]
	v_pk_mul_f32 v[110:111], v[210:211], v[110:111]
	v_pk_fma_f32 v[110:111], v[226:227], v[110:111], v[242:243]
	v_pk_fma_f32 v[108:109], v[224:225], v[108:109], v[240:241]
	s_nop 0
	v_cvt_pk_bf16_f32 v108, v108, v109
	v_cvt_pk_bf16_f32 v109, v110, v111
	global_store_dwordx2 v[128:129], v[108:109], off
	v_mul_f32_e32 v104, v104, v189
	v_mul_f32_e32 v105, v105, v189
	v_mul_f32_e32 v106, v106, v189
	v_mul_f32_e32 v107, v107, v189
	v_pk_mul_f32 v[104:105], v[212:213], v[104:105]
	v_pk_mul_f32 v[106:107], v[214:215], v[106:107]
	v_pk_fma_f32 v[106:107], v[230:231], v[106:107], v[246:247]
	v_pk_fma_f32 v[104:105], v[228:229], v[104:105], v[244:245]
	s_nop 0
	v_cvt_pk_bf16_f32 v104, v104, v105
	v_cvt_pk_bf16_f32 v105, v106, v107
	global_store_dwordx2 v[128:129], v[104:105], off offset:32
	v_mul_f32_e32 v100, v100, v189
	v_mul_f32_e32 v101, v101, v189
	v_mul_f32_e32 v102, v102, v189
	v_mul_f32_e32 v103, v103, v189
	v_pk_mul_f32 v[100:101], v[216:217], v[100:101]
	v_pk_mul_f32 v[102:103], v[218:219], v[102:103]
	v_pk_fma_f32 v[102:103], v[234:235], v[102:103], v[250:251]
	v_pk_fma_f32 v[100:101], v[232:233], v[100:101], v[248:249]
	s_nop 0
	v_cvt_pk_bf16_f32 v100, v100, v101
	v_cvt_pk_bf16_f32 v101, v102, v103
	global_store_dwordx2 v[128:129], v[100:101], off offset:256
	v_mul_f32_e32 v96, v96, v189
	v_mul_f32_e32 v97, v97, v189
	v_mul_f32_e32 v98, v98, v189
	v_mul_f32_e32 v99, v99, v189
	v_pk_mul_f32 v[96:97], v[220:221], v[96:97]
	v_pk_mul_f32 v[98:99], v[222:223], v[98:99]
	v_pk_fma_f32 v[98:99], v[238:239], v[98:99], v[186:187]
	v_pk_fma_f32 v[96:97], v[236:237], v[96:97], v[184:185]
	s_nop 0
	v_cvt_pk_bf16_f32 v96, v96, v97
	v_cvt_pk_bf16_f32 v97, v98, v99
	global_store_dwordx2 v[128:129], v[96:97], off offset:288
	v_lshl_add_u64 v[146:147], v[146:147], 0, s[66:67]
	v_add_co_u32_e32 v128, vcc, 0x8000, v128
	s_nop 1
	v_addc_co_u32_e32 v129, vcc, 0, v129, vcc
	global_store_dwordx4 v[146:147], v[92:95], off
	global_store_dwordx4 v[146:147], v[88:91], off offset:64
	global_store_dwordx4 v[146:147], v[84:87], off offset:512
	global_store_dwordx4 v[146:147], v[80:83], off offset:576
	s_nop 1
	v_mul_f32_e32 v92, v92, v190
	v_mul_f32_e32 v93, v93, v190
	v_mul_f32_e32 v94, v94, v190
	v_mul_f32_e32 v95, v95, v190
	v_pk_mul_f32 v[92:93], v[208:209], v[92:93]
	v_pk_mul_f32 v[94:95], v[210:211], v[94:95]
	v_pk_fma_f32 v[94:95], v[226:227], v[94:95], v[242:243]
	v_pk_fma_f32 v[92:93], v[224:225], v[92:93], v[240:241]
; __device__ __forceinline__ unsigned cvt_pk_bf16(float lo, float hi) { const f32x2_t v = {lo, hi}; const bf16x2_t b = __builtin_convertvector(v, bf16x2_t); return __builtin_bit_cast(unsigned, b); }
;     __device__ __forceinline__ void operator()(const Acc& acc, const Unit& u, int wr, int wc, int fr, int fq) const {
;     ...
;                         } else *(f32x4*)(X + (size_t)row * D + col) = *(const f32x4*)(base + col) + ga; } }
; template <bool FINAL>
; __device__ __forceinline__ void norm_rows(const float* xp, const float* xs, const float* X, const float* g, const float* sh, const float* sc, bf16_t* XN, float* out, int gw, int NGW, int lane, const float* part, int nsplit) {
;     ...
;         for (int j = 0; j < 4; ++j) { const int col = 4 * lane + 256 * j; const f32x4 gg = *(const f32x4*)(g + col);
;             if (FINAL) { *(f32x4*)(out + (size_t)row * D + col) = v[j] * rstd * gg; }
;             else { const f32x4 s1 = *(const f32x4*)(sc + (size_t)mr * 6144 + col), s0 = *(const f32x4*)(sh + (size_t)mr * 6144 + col);
;                 const f32x4 h = v[j] * rstd * gg * (s1 + 1.0f) + s0;
;                 *(u32x2*)(XN + (size_t)row * D + col) = (u32x2){cvt_pk_bf16(h[0], h[1]), cvt_pk_bf16(h[2], h[3])}; } }
	s_nop 0
	v_cvt_pk_bf16_f32 v92, v92, v93
	v_cvt_pk_bf16_f32 v93, v94, v95
	global_store_dwordx2 v[128:129], v[92:93], off
	v_mul_f32_e32 v88, v88, v190
	v_mul_f32_e32 v89, v89, v190
	v_mul_f32_e32 v90, v90, v190
	v_mul_f32_e32 v91, v91, v190
	v_pk_mul_f32 v[88:89], v[212:213], v[88:89]
	v_pk_mul_f32 v[90:91], v[214:215], v[90:91]
	v_pk_fma_f32 v[90:91], v[230:231], v[90:91], v[246:247]
	v_pk_fma_f32 v[88:89], v[228:229], v[88:89], v[244:245]
	s_nop 0
	v_cvt_pk_bf16_f32 v88, v88, v89
	v_cvt_pk_bf16_f32 v89, v90, v91
	global_store_dwordx2 v[128:129], v[88:89], off offset:32
	v_mul_f32_e32 v84, v84, v190
	v_mul_f32_e32 v85, v85, v190
	v_mul_f32_e32 v86, v86, v190
	v_mul_f32_e32 v87, v87, v190
	v_pk_mul_f32 v[84:85], v[216:217], v[84:85]
	v_pk_mul_f32 v[86:87], v[218:219], v[86:87]
	v_pk_fma_f32 v[86:87], v[234:235], v[86:87], v[250:251]
	v_pk_fma_f32 v[84:85], v[232:233], v[84:85], v[248:249]
	s_nop 0
	v_cvt_pk_bf16_f32 v84, v84, v85
	v_cvt_pk_bf16_f32 v85, v86, v87
	global_store_dwordx2 v[128:129], v[84:85], off offset:256
	v_mul_f32_e32 v80, v80, v190
	v_mul_f32_e32 v81, v81, v190
	v_mul_f32_e32 v82, v82, v190
	v_mul_f32_e32 v83, v83, v190
	v_pk_mul_f32 v[80:81], v[220:221], v[80:81]
	v_pk_mul_f32 v[82:83], v[222:223], v[82:83]
	v_pk_fma_f32 v[82:83], v[238:239], v[82:83], v[186:187]
	v_pk_fma_f32 v[80:81], v[236:237], v[80:81], v[184:185]
	s_nop 0
	v_cvt_pk_bf16_f32 v80, v80, v81
	v_cvt_pk_bf16_f32 v81, v82, v83
	global_store_dwordx2 v[128:129], v[80:81], off offset:288
	v_lshl_add_u64 v[146:147], v[146:147], 0, s[66:67]
	v_add_co_u32_e32 v128, vcc, 0x8000, v128
	s_nop 1
	v_addc_co_u32_e32 v129, vcc, 0, v129, vcc
	global_store_dwordx4 v[146:147], v[76:79], off
	global_store_dwordx4 v[146:147], v[72:75], off offset:64
	global_store_dwordx4 v[146:147], v[68:71], off offset:512
	global_store_dwordx4 v[146:147], v[64:67], off offset:576
	s_nop 1
	v_mul_f32_e32 v76, v76, v191
	v_mul_f32_e32 v77, v77, v191
	v_mul_f32_e32 v78, v78, v191
	v_mul_f32_e32 v79, v79, v191
	v_pk_mul_f32 v[76:77], v[208:209], v[76:77]
	v_pk_mul_f32 v[78:79], v[210:211], v[78:79]
	v_pk_fma_f32 v[78:79], v[226:227], v[78:79], v[242:243]
	v_pk_fma_f32 v[76:77], v[224:225], v[76:77], v[240:241]
	s_nop 0
	v_cvt_pk_bf16_f32 v76, v76, v77
	v_cvt_pk_bf16_f32 v77, v78, v79
	global_store_dwordx2 v[128:129], v[76:77], off
	v_mul_f32_e32 v72, v72, v191
	v_mul_f32_e32 v73, v73, v191
	v_mul_f32_e32 v74, v74, v191
	v_mul_f32_e32 v75, v75, v191
	v_pk_mul_f32 v[72:73], v[212:213], v[72:73]
	v_pk_mul_f32 v[74:75], v[214:215], v[74:75]
	v_pk_fma_f32 v[74:75], v[230:231], v[74:75], v[246:247]
	v_pk_fma_f32 v[72:73], v[228:229], v[72:73], v[244:245]
	s_nop 0
	v_cvt_pk_bf16_f32 v72, v72, v73
	v_cvt_pk_bf16_f32 v73, v74, v75
	global_store_dwordx2 v[128:129], v[72:73], off offset:32
	v_mul_f32_e32 v68, v68, v191
	v_mul_f32_e32 v69, v69, v191
	v_mul_f32_e32 v70, v70, v191
	v_mul_f32_e32 v71, v71, v191
	v_pk_mul_f32 v[68:69], v[216:217], v[68:69]
	v_pk_mul_f32 v[70:71], v[218:219], v[70:71]
	v_pk_fma_f32 v[70:71], v[234:235], v[70:71], v[250:251]
	v_pk_fma_f32 v[68:69], v[232:233], v[68:69], v[248:249]
	s_nop 0
	v_cvt_pk_bf16_f32 v68, v68, v69
	v_cvt_pk_bf16_f32 v69, v70, v71
	global_store_dwordx2 v[128:129], v[68:69], off offset:256
	v_mul_f32_e32 v64, v64, v191
	v_mul_f32_e32 v65, v65, v191
	v_mul_f32_e32 v66, v66, v191
	v_mul_f32_e32 v67, v67, v191
	v_pk_mul_f32 v[64:65], v[220:221], v[64:65]
	v_pk_mul_f32 v[66:67], v[222:223], v[66:67]
	v_pk_fma_f32 v[66:67], v[238:239], v[66:67], v[186:187]
	v_pk_fma_f32 v[64:65], v[236:237], v[64:65], v[184:185]
	s_nop 0
	v_cvt_pk_bf16_f32 v64, v64, v65
	v_cvt_pk_bf16_f32 v65, v66, v67
	global_store_dwordx2 v[128:129], v[64:65], off offset:288
	v_lshl_add_u64 v[146:147], v[146:147], 0, s[68:69]
	v_add_co_u32_e32 v128, vcc, 0x28000, v128
	s_nop 1
	v_addc_co_u32_e32 v129, vcc, 0, v129, vcc
	global_store_dwordx4 v[146:147], v[60:63], off
	global_store_dwordx4 v[146:147], v[56:59], off offset:64
	global_store_dwordx4 v[146:147], v[52:55], off offset:512
	global_store_dwordx4 v[146:147], v[48:51], off offset:576
	s_nop 1
	v_mul_f32_e32 v60, v60, v192
	v_mul_f32_e32 v61, v61, v192
	v_mul_f32_e32 v62, v62, v192
	v_mul_f32_e32 v63, v63, v192
	v_pk_mul_f32 v[60:61], v[208:209], v[60:61]
	v_pk_mul_f32 v[62:63], v[210:211], v[62:63]
	v_pk_fma_f32 v[62:63], v[226:227], v[62:63], v[242:243]
	v_pk_fma_f32 v[60:61], v[224:225], v[60:61], v[240:241]
	s_nop 0
	v_cvt_pk_bf16_f32 v60, v60, v61
	v_cvt_pk_bf16_f32 v61, v62, v63
	global_store_dwordx2 v[128:129], v[60:61], off
	v_mul_f32_e32 v56, v56, v192
	v_mul_f32_e32 v57, v57, v192
	v_mul_f32_e32 v58, v58, v192
	v_mul_f32_e32 v59, v59, v192
	v_pk_mul_f32 v[56:57], v[212:213], v[56:57]
	v_pk_mul_f32 v[58:59], v[214:215], v[58:59]
	v_pk_fma_f32 v[58:59], v[230:231], v[58:59], v[246:247]
	v_pk_fma_f32 v[56:57], v[228:229], v[56:57], v[244:245]
	s_nop 0
	v_cvt_pk_bf16_f32 v56, v56, v57
	v_cvt_pk_bf16_f32 v57, v58, v59
	global_store_dwordx2 v[128:129], v[56:57], off offset:32
	v_mul_f32_e32 v52, v52, v192
	v_mul_f32_e32 v53, v53, v192
	v_mul_f32_e32 v54, v54, v192
	v_mul_f32_e32 v55, v55, v192
	v_pk_mul_f32 v[52:53], v[216:217], v[52:53]
	v_pk_mul_f32 v[54:55], v[218:219], v[54:55]
	v_pk_fma_f32 v[54:55], v[234:235], v[54:55], v[250:251]
	v_pk_fma_f32 v[52:53], v[232:233], v[52:53], v[248:249]
	s_nop 0
	v_cvt_pk_bf16_f32 v52, v52, v53
	v_cvt_pk_bf16_f32 v53, v54, v55
	global_store_dwordx2 v[128:129], v[52:53], off offset:256
	v_mul_f32_e32 v48, v48, v192
	v_mul_f32_e32 v49, v49, v192
	v_mul_f32_e32 v50, v50, v192
	v_mul_f32_e32 v51, v51, v192
	v_pk_mul_f32 v[48:49], v[220:221], v[48:49]
	v_pk_mul_f32 v[50:51], v[222:223], v[50:51]
; __device__ __forceinline__ unsigned cvt_pk_bf16(float lo, float hi) { const f32x2_t v = {lo, hi}; const bf16x2_t b = __builtin_convertvector(v, bf16x2_t); return __builtin_bit_cast(unsigned, b); }
;     __device__ __forceinline__ void operator()(const Acc& acc, const Unit& u, int wr, int wc, int fr, int fq) const {
;     ...
;                         } else *(f32x4*)(X + (size_t)row * D + col) = *(const f32x4*)(base + col) + ga; } }
; template <bool FINAL>
; __device__ __forceinline__ void norm_rows(const float* xp, const float* xs, const float* X, const float* g, const float* sh, const float* sc, bf16_t* XN, float* out, int gw, int NGW, int lane, const float* part, int nsplit) {
;     ...
;         for (int j = 0; j < 4; ++j) { const int col = 4 * lane + 256 * j; const f32x4 gg = *(const f32x4*)(g + col);
;             if (FINAL) { *(f32x4*)(out + (size_t)row * D + col) = v[j] * rstd * gg; }
;             else { const f32x4 s1 = *(const f32x4*)(sc + (size_t)mr * 6144 + col), s0 = *(const f32x4*)(sh + (size_t)mr * 6144 + col);
;                 const f32x4 h = v[j] * rstd * gg * (s1 + 1.0f) + s0;
;                 *(u32x2*)(XN + (size_t)row * D + col) = (u32x2){cvt_pk_bf16(h[0], h[1]), cvt_pk_bf16(h[2], h[3])}; } }
	v_pk_fma_f32 v[50:51], v[238:239], v[50:51], v[186:187]
	v_pk_fma_f32 v[48:49], v[236:237], v[48:49], v[184:185]
	s_nop 0
	v_cvt_pk_bf16_f32 v48, v48, v49
	v_cvt_pk_bf16_f32 v49, v50, v51
	global_store_dwordx2 v[128:129], v[48:49], off offset:288
	v_lshl_add_u64 v[146:147], v[146:147], 0, s[66:67]
	v_add_co_u32_e32 v128, vcc, 0x8000, v128
	s_nop 1
	v_addc_co_u32_e32 v129, vcc, 0, v129, vcc
	global_store_dwordx4 v[146:147], v[44:47], off
	global_store_dwordx4 v[146:147], v[40:43], off offset:64
	global_store_dwordx4 v[146:147], v[36:39], off offset:512
	global_store_dwordx4 v[146:147], v[32:35], off offset:576
	s_nop 1
	v_mul_f32_e32 v44, v44, v193
	v_mul_f32_e32 v45, v45, v193
	v_mul_f32_e32 v46, v46, v193
	v_mul_f32_e32 v47, v47, v193
	v_pk_mul_f32 v[44:45], v[208:209], v[44:45]
	v_pk_mul_f32 v[46:47], v[210:211], v[46:47]
	v_pk_fma_f32 v[46:47], v[226:227], v[46:47], v[242:243]
	v_pk_fma_f32 v[44:45], v[224:225], v[44:45], v[240:241]
	s_nop 0
	v_cvt_pk_bf16_f32 v44, v44, v45
	v_cvt_pk_bf16_f32 v45, v46, v47
	global_store_dwordx2 v[128:129], v[44:45], off
	v_mul_f32_e32 v40, v40, v193
	v_mul_f32_e32 v41, v41, v193
	v_mul_f32_e32 v42, v42, v193
	v_mul_f32_e32 v43, v43, v193
	v_pk_mul_f32 v[40:41], v[212:213], v[40:41]
	v_pk_mul_f32 v[42:43], v[214:215], v[42:43]
	v_pk_fma_f32 v[42:43], v[230:231], v[42:43], v[246:247]
	v_pk_fma_f32 v[40:41], v[228:229], v[40:41], v[244:245]
	s_nop 0
	v_cvt_pk_bf16_f32 v40, v40, v41
	v_cvt_pk_bf16_f32 v41, v42, v43
	global_store_dwordx2 v[128:129], v[40:41], off offset:32
	v_mul_f32_e32 v36, v36, v193
	v_mul_f32_e32 v37, v37, v193
	v_mul_f32_e32 v38, v38, v193
	v_mul_f32_e32 v39, v39, v193
	v_pk_mul_f32 v[36:37], v[216:217], v[36:37]
	v_pk_mul_f32 v[38:39], v[218:219], v[38:39]
	v_pk_fma_f32 v[38:39], v[234:235], v[38:39], v[250:251]
	v_pk_fma_f32 v[36:37], v[232:233], v[36:37], v[248:249]
	s_nop 0
	v_cvt_pk_bf16_f32 v36, v36, v37
	v_cvt_pk_bf16_f32 v37, v38, v39
	global_store_dwordx2 v[128:129], v[36:37], off offset:256
	v_mul_f32_e32 v32, v32, v193
	v_mul_f32_e32 v33, v33, v193
	v_mul_f32_e32 v34, v34, v193
	v_mul_f32_e32 v35, v35, v193
	v_pk_mul_f32 v[32:33], v[220:221], v[32:33]
	v_pk_mul_f32 v[34:35], v[222:223], v[34:35]
	v_pk_fma_f32 v[34:35], v[238:239], v[34:35], v[186:187]
	v_pk_fma_f32 v[32:33], v[236:237], v[32:33], v[184:185]
	s_nop 0
	v_cvt_pk_bf16_f32 v32, v32, v33
	v_cvt_pk_bf16_f32 v33, v34, v35
	global_store_dwordx2 v[128:129], v[32:33], off offset:288
	v_lshl_add_u64 v[146:147], v[146:147], 0, s[66:67]
	v_add_co_u32_e32 v128, vcc, 0x8000, v128
	s_nop 1
	v_addc_co_u32_e32 v129, vcc, 0, v129, vcc
	global_store_dwordx4 v[146:147], v[28:31], off
	global_store_dwordx4 v[146:147], v[24:27], off offset:64
	global_store_dwordx4 v[146:147], v[20:23], off offset:512
	global_store_dwordx4 v[146:147], v[16:19], off offset:576
	s_nop 1
	v_mul_f32_e32 v28, v28, v194
	v_mul_f32_e32 v29, v29, v194
	v_mul_f32_e32 v30, v30, v194
	v_mul_f32_e32 v31, v31, v194
	v_pk_mul_f32 v[28:29], v[208:209], v[28:29]
	v_pk_mul_f32 v[30:31], v[210:211], v[30:31]
	v_pk_fma_f32 v[30:31], v[226:227], v[30:31], v[242:243]
	v_pk_fma_f32 v[28:29], v[224:225], v[28:29], v[240:241]
	s_nop 0
	v_cvt_pk_bf16_f32 v28, v28, v29
	v_cvt_pk_bf16_f32 v29, v30, v31
	global_store_dwordx2 v[128:129], v[28:29], off
	v_mul_f32_e32 v24, v24, v194
	v_mul_f32_e32 v25, v25, v194
	v_mul_f32_e32 v26, v26, v194
	v_mul_f32_e32 v27, v27, v194
	v_pk_mul_f32 v[24:25], v[212:213], v[24:25]
	v_pk_mul_f32 v[26:27], v[214:215], v[26:27]
	v_pk_fma_f32 v[26:27], v[230:231], v[26:27], v[246:247]
	v_pk_fma_f32 v[24:25], v[228:229], v[24:25], v[244:245]
	s_nop 0
	v_cvt_pk_bf16_f32 v24, v24, v25
	v_cvt_pk_bf16_f32 v25, v26, v27
	global_store_dwordx2 v[128:129], v[24:25], off offset:32
	v_mul_f32_e32 v20, v20, v194
	v_mul_f32_e32 v21, v21, v194
	v_mul_f32_e32 v22, v22, v194
	v_mul_f32_e32 v23, v23, v194
	v_pk_mul_f32 v[20:21], v[216:217], v[20:21]
	v_pk_mul_f32 v[22:23], v[218:219], v[22:23]
	v_pk_fma_f32 v[22:23], v[234:235], v[22:23], v[250:251]
	v_pk_fma_f32 v[20:21], v[232:233], v[20:21], v[248:249]
	s_nop 0
	v_cvt_pk_bf16_f32 v20, v20, v21
	v_cvt_pk_bf16_f32 v21, v22, v23
	global_store_dwordx2 v[128:129], v[20:21], off offset:256
	v_mul_f32_e32 v16, v16, v194
	v_mul_f32_e32 v17, v17, v194
	v_mul_f32_e32 v18, v18, v194
	v_mul_f32_e32 v19, v19, v194
	v_pk_mul_f32 v[16:17], v[220:221], v[16:17]
	v_pk_mul_f32 v[18:19], v[222:223], v[18:19]
	v_pk_fma_f32 v[18:19], v[238:239], v[18:19], v[186:187]
	v_pk_fma_f32 v[16:17], v[236:237], v[16:17], v[184:185]
	s_nop 0
	v_cvt_pk_bf16_f32 v16, v16, v17
	v_cvt_pk_bf16_f32 v17, v18, v19
	global_store_dwordx2 v[128:129], v[16:17], off offset:288
	v_lshl_add_u64 v[146:147], v[146:147], 0, s[66:67]
	v_add_co_u32_e32 v128, vcc, 0x8000, v128
	s_nop 1
	v_addc_co_u32_e32 v129, vcc, 0, v129, vcc
	global_store_dwordx4 v[146:147], v[12:15], off
	global_store_dwordx4 v[146:147], v[8:11], off offset:64
	global_store_dwordx4 v[146:147], v[4:7], off offset:512
	global_store_dwordx4 v[146:147], v[0:3], off offset:576
	s_nop 1
	v_mul_f32_e32 v12, v12, v195
	v_mul_f32_e32 v13, v13, v195
	v_mul_f32_e32 v14, v14, v195
	v_mul_f32_e32 v15, v15, v195
	v_pk_mul_f32 v[12:13], v[208:209], v[12:13]
	v_pk_mul_f32 v[14:15], v[210:211], v[14:15]
	v_pk_fma_f32 v[14:15], v[226:227], v[14:15], v[242:243]
	v_pk_fma_f32 v[12:13], v[224:225], v[12:13], v[240:241]
	s_nop 0
	v_cvt_pk_bf16_f32 v12, v12, v13
	v_cvt_pk_bf16_f32 v13, v14, v15
	global_store_dwordx2 v[128:129], v[12:13], off
	v_mul_f32_e32 v8, v8, v195
	v_mul_f32_e32 v9, v9, v195
	v_mul_f32_e32 v10, v10, v195
	v_mul_f32_e32 v11, v11, v195
	v_pk_mul_f32 v[8:9], v[212:213], v[8:9]
	v_pk_mul_f32 v[10:11], v[214:215], v[10:11]
	v_pk_fma_f32 v[10:11], v[230:231], v[10:11], v[246:247]
	v_pk_fma_f32 v[8:9], v[228:229], v[8:9], v[244:245]
	s_nop 0
	v_cvt_pk_bf16_f32 v8, v8, v9
	v_cvt_pk_bf16_f32 v9, v10, v11
	global_store_dwordx2 v[128:129], v[8:9], off offset:32
	v_mul_f32_e32 v4, v4, v195
	v_mul_f32_e32 v5, v5, v195
	v_mul_f32_e32 v6, v6, v195
	v_mul_f32_e32 v7, v7, v195
	v_pk_mul_f32 v[4:5], v[216:217], v[4:5]
	v_pk_mul_f32 v[6:7], v[218:219], v[6:7]
	v_pk_fma_f32 v[6:7], v[234:235], v[6:7], v[250:251]
	v_pk_fma_f32 v[4:5], v[232:233], v[4:5], v[248:249]
	s_nop 0
	v_cvt_pk_bf16_f32 v4, v4, v5
	v_cvt_pk_bf16_f32 v5, v6, v7
	global_store_dwordx2 v[128:129], v[4:5], off offset:256
	v_mul_f32_e32 v0, v0, v195
	v_mul_f32_e32 v1, v1, v195
	v_mul_f32_e32 v2, v2, v195
	v_mul_f32_e32 v3, v3, v195
	v_pk_mul_f32 v[0:1], v[220:221], v[0:1]
	v_pk_mul_f32 v[2:3], v[222:223], v[2:3]
	v_pk_fma_f32 v[2:3], v[238:239], v[2:3], v[186:187]
	v_pk_fma_f32 v[0:1], v[236:237], v[0:1], v[184:185]
	s_nop 0
	v_cvt_pk_bf16_f32 v0, v0, v1
	v_cvt_pk_bf16_f32 v1, v2, v3
	global_store_dwordx2 v[128:129], v[0:1], off offset:288
	s_branch .Lepi_out_done

; #define INP(i) ((const float*)ld_ptr(pb, (i)))
; template <bool FINAL>
; __device__ __forceinline__ void norm_rows(const float* xp, const float* xs, const float* X, const float* g, const float* sh, const float* sc, bf16_t* XN, float* out, int gw, int NGW, int lane, const float* part, int nsplit) {
;     f32x4 vnext[4];
;     if (gw < M) { const float* xr0 = xp ? (gw < MP ? xp + (size_t)gw * D : xs + (size_t)(gw - MP) * D) : X + (size_t)gw * D;
; #pragma unroll
;         for (int j = 0; j < 4; ++j) vnext[j] = *(const f32x4*)(xr0 + 4 * lane + 256 * j); }
;     for (int row = gw; row < M; row += NGW) {
;         f32x4 v[4]; float s = 0.f;
; #pragma unroll
;         for (int j = 0; j < 4; ++j) v[j] = vnext[j];
;         { const int rn = row + NGW; if (rn < M) { const float* xrn = xp ? (rn < MP ? xp + (size_t)rn * D : xs + (size_t)(rn - MP) * D) : X + (size_t)rn * D;
; #pragma unroll
;             for (int j = 0; j < 4; ++j) vnext[j] = *(const f32x4*)(xrn + 4 * lane + 256 * j); } }
; __global__ void __launch_bounds__(512, 2) hybrid_fwd(Params P) {
;     ...
;         norm_rows<false>(nullptr, nullptr, X, INP(10) + l * D, (MOD + (size_t)l * NMODROWS * 6144) + 3072, (MOD + (size_t)l * NMODROWS * 6144) + 4096, XN, nullptr, gw, NGW, lane, (const float*)(ws + WS_PART), D / 256);
.LBB0_1707:
	s_andn2_b64 vcc, exec, s[0:1]
	s_cbranch_vccnz .LBB0_1769
	v_readlane_b32 s1, v253, 7
	v_readlane_b32 s0, v253, 0
	v_readlane_b32 s18, v253, 1
	v_readlane_b32 s12, v253, 2
	v_mov_b32_e32 v0, s1
	v_mbcnt_lo_u32_b32 v44, -1, 0
	v_mbcnt_hi_u32_b32 v44, -1, v44
	ds_read2_b64 v[0:3], v0 offset0:10 offset1:35
	s_lshl_b32 s0, s0, 3
	s_add_i32 s0, s0, s12
	s_add_i32 s0, s0, 0x4000
	s_cmpk_gt_i32 s0, 0x41ff
	s_mov_b32 s13, 0x200000
	s_waitcnt lgkmcnt(0)
	v_readfirstlane_b32 s3, v3
	v_readfirstlane_b32 s2, v2
	v_readfirstlane_b32 s1, v1
	v_readfirstlane_b32 s5, v0
	s_mov_b32 s16, 0x600000
	s_cbranch_scc1 .LBB0_1715
	s_mul_i32 s74, s96, 0xc6000
	s_lshl_b32 s4, s18, 3
	s_lshl_b64 s[6:7], s[74:75], 2
	s_add_u32 s6, s2, s6
	s_addc_u32 s7, s3, s7
	s_add_u32 s8, s2, 0x7e00000
	s_addc_u32 s9, s3, 0
	s_lshl_b32 s74, s96, 10
	s_lshl_b64 s[10:11], s[74:75], 2
	s_add_u32 s10, s5, s10
	s_addc_u32 s11, s1, s11
	s_ashr_i32 s1, s0, 31
	s_lshl_b64 s[14:15], s[0:1], 12
	v_lshlrev_b32_e32 v12, 2, v44
	s_add_u32 s14, s8, s14
	v_ashrrev_i32_e32 v13, 31, v12
	s_addc_u32 s15, s9, s15
	v_lshlrev_b64 v[14:15], 2, v[12:13]
	v_lshl_add_u64 v[0:1], s[14:15], 0, v[14:15]
	global_load_dwordx4 v[28:31], v[0:1], off
	global_load_dwordx4 v[8:11], v[0:1], off offset:1024
	global_load_dwordx4 v[4:7], v[0:1], off offset:2048
	s_nop 0
	global_load_dwordx4 v[0:3], v[0:1], off offset:3072
	v_lshl_add_u64 v[16:17], s[2:3], 0, v[14:15]
	v_lshl_add_u64 v[34:35], s[8:9], 0, v[14:15]
	v_lshl_add_u64 v[36:37], s[10:11], 0, v[14:15]
	v_lshl_add_u64 v[14:15], s[6:7], 0, v[14:15]
	s_mov_b64 s[6:7], 0x804000
	v_lshl_add_u64 v[38:39], v[14:15], 0, s[6:7]
	s_mov_b64 s[6:7], 0x803000
	v_lshl_add_u64 v[40:41], v[14:15], 0, s[6:7]
	s_lshl_b64 s[6:7], s[0:1], 11
	s_add_u32 s6, s2, s6
	s_addc_u32 s7, s3, s7
	s_mov_b64 s[14:15], 0x13c00000
	v_lshl_add_u64 v[12:13], v[12:13], 1, s[6:7]
	s_mov_b64 s[6:7], 0xc000000
	s_ashr_i32 s5, s4, 31
	v_lshl_add_u64 v[32:33], v[16:17], 0, s[14:15]
	v_lshl_add_u64 v[42:43], v[12:13], 0, s[6:7]
	s_lshl_b64 s[6:7], s[4:5], 11
	s_branch .LBB0_1711
; __device__ __forceinline__ unsigned cvt_pk_bf16(float lo, float hi) { const f32x2_t v = {lo, hi}; const bf16x2_t b = __builtin_convertvector(v, bf16x2_t); return __builtin_bit_cast(unsigned, b); }
; template <bool FINAL>
; __device__ __forceinline__ void norm_rows(const float* xp, const float* xs, const float* X, const float* g, const float* sh, const float* sc, bf16_t* XN, float* out, int gw, int NGW, int lane, const float* part, int nsplit) {
;     ...
;     for (int row = gw; row < M; row += NGW) {
;         f32x4 v[4]; float s = 0.f;
; #pragma unroll
;         for (int j = 0; j < 4; ++j) v[j] = vnext[j];
;         { const int rn = row + NGW; if (rn < M) { const float* xrn = xp ? (rn < MP ? xp + (size_t)rn * D : xs + (size_t)(rn - MP) * D) : X + (size_t)rn * D;
; #pragma unroll
;             for (int j = 0; j < 4; ++j) vnext[j] = *(const f32x4*)(xrn + 4 * lane + 256 * j); } }
;         if (nsplit > 0 && row >= MP) {
;             for (int sp = 0; sp < nsplit; ++sp) { const float* pr = part + ((size_t)sp * MS + (row - MP)) * D + 4 * lane;
; #pragma unroll
;                 for (int j = 0; j < 4; ++j) v[j] += *(const f32x4*)(pr + 256 * j); }
; #pragma unroll
;             for (int j = 0; j < 4; ++j) *(f32x4*)((float*)X + (size_t)row * D + 4 * lane + 256 * j) = v[j]; }
; #pragma unroll
;         for (int j = 0; j < 4; ++j) s += (v[j][0] * v[j][0] + v[j][1] * v[j][1]) + (v[j][2] * v[j][2] + v[j][3] * v[j][3]);
;         const float rstd = 1.0f / sqrtf(wave_sum(s) * (1.0f / D) + EPS);
;         const int mr = mod_row(row);
;         if (!FINAL && xp && row >= MP) {
; #pragma unroll
;             for (int j = 0; j < 4; ++j) *(f32x4*)((float*)X + (size_t)row * D + 4 * lane + 256 * j) = v[j]; }
; #pragma unroll
;         for (int j = 0; j < 4; ++j) { const int col = 4 * lane + 256 * j; const f32x4 gg = *(const f32x4*)(g + col);
;             if (FINAL) { *(f32x4*)(out + (size_t)row * D + col) = v[j] * rstd * gg; }
;             else { const f32x4 s1 = *(const f32x4*)(sc + (size_t)mr * 6144 + col), s0 = *(const f32x4*)(sh + (size_t)mr * 6144 + col);
;                 const f32x4 h = v[j] * rstd * gg * (s1 + 1.0f) + s0;
;                 *(u32x2*)(XN + (size_t)row * D + col) = (u32x2){cvt_pk_bf16(h[0], h[1]), cvt_pk_bf16(h[2], h[3])}; } }
.LBB0_1710:
	v_mul_f32_e32 v45, v29, v29
	v_mul_f32_e32 v46, v31, v31
	v_fmac_f32_e32 v45, v28, v28
	v_fmac_f32_e32 v46, v30, v30
	v_add_f32_e32 v45, v45, v46
	v_mul_f32_e32 v46, v9, v9
	v_mul_f32_e32 v47, v11, v11
	v_fmac_f32_e32 v46, v8, v8
	v_fmac_f32_e32 v47, v10, v10
	v_add_f32_e32 v46, v46, v47
	v_add_f32_e32 v45, v45, v46
	v_mul_f32_e32 v46, v5, v5
	v_mul_f32_e32 v47, v7, v7
	v_fmac_f32_e32 v46, v4, v4
	v_fmac_f32_e32 v47, v6, v6
	v_add_f32_e32 v46, v46, v47
	v_add_f32_e32 v45, v46, v45
	v_mul_f32_e32 v46, v1, v1
	v_mul_f32_e32 v47, v3, v3
	v_fmac_f32_e32 v46, v0, v0
	v_fmac_f32_e32 v47, v2, v2
	v_add_f32_e32 v46, v46, v47
	v_add_f32_e32 v45, v46, v45
	ds_swizzle_b32 v46, v45 offset:swizzle(SWAP,1)
	s_waitcnt lgkmcnt(0)
	v_add_f32_e32 v45, v45, v46
	ds_swizzle_b32 v46, v45 offset:swizzle(SWAP,2)
	s_waitcnt lgkmcnt(0)
	v_add_f32_e32 v45, v45, v46
	ds_swizzle_b32 v46, v45 offset:swizzle(SWAP,4)
	s_waitcnt lgkmcnt(0)
	v_add_f32_e32 v45, v45, v46
	ds_swizzle_b32 v46, v45 offset:swizzle(SWAP,8)
	s_waitcnt lgkmcnt(0)
	v_add_f32_e32 v45, v45, v46
	ds_swizzle_b32 v46, v45 offset:swizzle(SWAP,16)
	s_waitcnt lgkmcnt(0)
	v_add_f32_e32 v45, v45, v46
	v_mov_b32_e32 v62, v45
	s_nop 1
	v_permlane32_swap_b32 v45, v62
	s_nop 1
	v_add_f32_e32 v45, v45, v62
	v_fmamk_f32 v45, v45, 0x3a800000, v202
	v_mul_f32_e32 v62, 0x4f800000, v45
	v_cmp_gt_f32_e32 vcc, s95, v45
	s_nop 1
	v_cndmask_b32_e32 v45, v45, v62, vcc
	v_sqrt_f32_e32 v62, v45
	s_nop 0
	v_add_u32_e32 v63, -1, v62
	v_add_u32_e32 v64, 1, v62
	v_fma_f32 v65, -v63, v62, v45
	v_fma_f32 v66, -v64, v62, v45
	v_cmp_ge_f32_e64 s[0:1], 0, v65
	s_nop 1
	v_cndmask_b32_e64 v62, v62, v63, s[0:1]
	v_cmp_lt_f32_e64 s[0:1], 0, v66
	s_nop 1
	v_cndmask_b32_e64 v62, v62, v64, s[0:1]
	v_mul_f32_e32 v63, 0x37800000, v62
	v_cndmask_b32_e32 v62, v62, v63, vcc
	v_cmp_class_f32_e32 vcc, v45, v203
	s_nop 1
	v_cndmask_b32_e32 v45, v62, v45, vcc
	v_div_scale_f32 v62, s[0:1], v45, v45, 1.0
	v_rcp_f32_e32 v63, v62
	v_div_scale_f32 v64, vcc, 1.0, v45, 1.0
	s_mov_b32 s0, s8
	v_fma_f32 v65, -v62, v63, 1.0
	v_fmac_f32_e32 v63, v65, v63
	v_mul_f32_e32 v65, v64, v63
	v_fma_f32 v66, -v62, v65, v64
	v_fmac_f32_e32 v65, v66, v63
	v_fma_f32 v62, -v62, v65, v64
	v_div_fmas_f32 v62, v62, v63, v65
	v_div_fixup_f32 v62, v62, v45, 1.0
	v_pk_mul_f32 v[30:31], v[30:31], v[62:63] op_sel_hi:[1,0]
	v_pk_mul_f32 v[28:29], v[28:29], v[62:63] op_sel_hi:[1,0]
	v_pk_mul_f32 v[10:11], v[10:11], v[62:63] op_sel_hi:[1,0]
	v_pk_mul_f32 v[8:9], v[8:9], v[62:63] op_sel_hi:[1,0]
	v_pk_mul_f32 v[6:7], v[6:7], v[62:63] op_sel_hi:[1,0]
	v_pk_mul_f32 v[4:5], v[4:5], v[62:63] op_sel_hi:[1,0]
	v_pk_mul_f32 v[2:3], v[2:3], v[62:63] op_sel_hi:[1,0]
	v_pk_mul_f32 v[0:1], v[0:1], v[62:63] op_sel_hi:[1,0]
	s_andn2_b64 vcc, exec, s[10:11]
	s_waitcnt vmcnt(4)
	v_pk_mul_f32 v[28:29], v[112:113], v[28:29]
	v_pk_mul_f32 v[30:31], v[114:115], v[30:31]
	v_pk_add_f32 v[130:131], v[130:131], 1.0 op_sel_hi:[1,0]
	v_pk_add_f32 v[128:129], v[128:129], 1.0 op_sel_hi:[1,0]
	v_pk_fma_f32 v[30:31], v[130:131], v[30:31], v[146:147]
	v_pk_fma_f32 v[28:29], v[128:129], v[28:29], v[144:145]
	s_nop 0
	v_cvt_pk_bf16_f32 v28, v28, v29
	v_cvt_pk_bf16_f32 v29, v30, v31
	global_store_dwordx2 v[42:43], v[28:29], off
	v_pk_mul_f32 v[8:9], v[116:117], v[8:9]
	v_pk_mul_f32 v[10:11], v[118:119], v[10:11]
	v_pk_add_f32 v[134:135], v[134:135], 1.0 op_sel_hi:[1,0]
	v_pk_add_f32 v[132:133], v[132:133], 1.0 op_sel_hi:[1,0]
	v_pk_fma_f32 v[10:11], v[134:135], v[10:11], v[150:151]
	v_pk_fma_f32 v[8:9], v[132:133], v[8:9], v[148:149]
	s_nop 0
	v_cvt_pk_bf16_f32 v8, v8, v9
	v_cvt_pk_bf16_f32 v9, v10, v11
	global_store_dwordx2 v[42:43], v[8:9], off offset:512
	v_pk_mul_f32 v[4:5], v[120:121], v[4:5]
	v_pk_mul_f32 v[6:7], v[122:123], v[6:7]
	v_pk_add_f32 v[138:139], v[138:139], 1.0 op_sel_hi:[1,0]
	v_pk_add_f32 v[136:137], v[136:137], 1.0 op_sel_hi:[1,0]
	v_pk_fma_f32 v[6:7], v[138:139], v[6:7], v[154:155]
	v_pk_fma_f32 v[4:5], v[136:137], v[4:5], v[152:153]
	s_nop 0
	v_cvt_pk_bf16_f32 v4, v4, v5
	v_cvt_pk_bf16_f32 v5, v6, v7
	global_store_dwordx2 v[42:43], v[4:5], off offset:1024
	v_pk_mul_f32 v[0:1], v[124:125], v[0:1]
	v_pk_mul_f32 v[2:3], v[126:127], v[2:3]
	v_pk_add_f32 v[142:143], v[142:143], 1.0 op_sel_hi:[1,0]
	v_pk_add_f32 v[140:141], v[140:141], 1.0 op_sel_hi:[1,0]
	v_pk_fma_f32 v[2:3], v[142:143], v[2:3], v[158:159]
	v_pk_fma_f32 v[0:1], v[140:141], v[0:1], v[156:157]
	s_nop 0
	v_cvt_pk_bf16_f32 v0, v0, v1
	v_cvt_pk_bf16_f32 v1, v2, v3
	global_store_dwordx2 v[42:43], v[0:1], off offset:1536
	s_waitcnt vmcnt(4)
	v_mov_b32_e32 v28, v16
	v_mov_b32_e32 v29, v17
	v_mov_b32_e32 v30, v18
	v_mov_b32_e32 v31, v19
	v_mov_b32_e32 v8, v20
	v_mov_b32_e32 v9, v21
	v_mov_b32_e32 v10, v22
	v_mov_b32_e32 v11, v23
	v_mov_b32_e32 v4, v24
	v_mov_b32_e32 v5, v25
	v_mov_b32_e32 v6, v26
	v_mov_b32_e32 v7, v27
	v_mov_b32_e32 v0, v12
	v_mov_b32_e32 v1, v13
	v_mov_b32_e32 v2, v14
	v_mov_b32_e32 v3, v15
	v_lshl_add_u64 v[42:43], v[42:43], 0, s[6:7]
	s_cbranch_vccz .LBB0_1715
.LBB0_1711:
	s_add_i32 s8, s0, s4
	s_cmpk_gt_i32 s8, 0x41ff
	s_cselect_b64 s[10:11], -1, 0
	s_and_b64 vcc, exec, s[10:11]
	s_waitcnt vmcnt(0)
	v_mov_b32_e32 v16, v28
	v_mov_b32_e32 v17, v29
	v_mov_b32_e32 v18, v30
	v_mov_b32_e32 v19, v31
	v_mov_b32_e32 v20, v8
	v_mov_b32_e32 v21, v9
	v_mov_b32_e32 v22, v10
	v_mov_b32_e32 v23, v11
	v_mov_b32_e32 v24, v4
	v_mov_b32_e32 v25, v5
	v_mov_b32_e32 v26, v6
	v_mov_b32_e32 v27, v7
	v_mov_b32_e32 v12, v0
	v_mov_b32_e32 v13, v1
	v_mov_b32_e32 v14, v2
	v_mov_b32_e32 v15, v3
	s_add_i32 s74, s0, 0xffffc000
	s_lshr_b32 s5, s74, 2
	s_ashr_i32 s1, s0, 12
	s_add_i32 s5, s5, 4
	s_cmpk_lt_i32 s0, 0x4000
	s_cselect_b32 s5, s1, s5
	v_mad_i64_i32 v[58:59], s[20:21], s5, v206, v[38:39]
	v_mad_i64_i32 v[60:61], s[20:21], s5, v206, v[40:41]
	global_load_dwordx4 v[112:115], v[36:37], off
	global_load_dwordx4 v[128:131], v[58:59], off
	global_load_dwordx4 v[144:147], v[60:61], off
	global_load_dwordx4 v[116:119], v[36:37], off offset:1024
	global_load_dwordx4 v[132:135], v[58:59], off offset:1024
	global_load_dwordx4 v[148:151], v[60:61], off offset:1024
	global_load_dwordx4 v[120:123], v[36:37], off offset:2048
	global_load_dwordx4 v[136:139], v[58:59], off offset:2048
	global_load_dwordx4 v[152:155], v[60:61], off offset:2048
	global_load_dwordx4 v[124:127], v[36:37], off offset:3072
	global_load_dwordx4 v[140:143], v[58:59], off offset:3072
	global_load_dwordx4 v[156:159], v[60:61], off offset:3072
	s_cmpk_gt_i32 s8, 0x41ff
	s_cselect_b32 s22, s0, s8
	s_ashr_i32 s23, s22, 31
	s_lshl_b64 s[22:23], s[22:23], 12
	v_lshl_add_u64 v[12:13], v[34:35], 0, s[22:23]
	global_load_dwordx4 v[16:19], v[12:13], off
	global_load_dwordx4 v[20:23], v[12:13], off offset:1024
	global_load_dwordx4 v[24:27], v[12:13], off offset:2048
	s_nop 0
	global_load_dwordx4 v[12:15], v[12:13], off offset:3072

; #define INP(i) ((const float*)ld_ptr(pb, (i)))
; #define PHASE_END if (ph + 1 < hi) grid_barrier((unsigned*)ws, (unsigned)G, tid, (volatile LAS unsigned*)(ldsl + XBST_OFF)); } ++ph;
;     __device__ __forceinline__ void operator()(const Acc& acc, const Unit& u, int wr, int wc, int fr, int fq) const {
; #pragma unroll
;         for (int ai = 0; ai < 2; ++ai)
; #pragma unroll
;             for (int m = 0; m < 4; ++m) { const int row = u.pm * 256 + ai * 128 + wr * 64 + m * 16 + fr;
;                 const float* base = xp ? (row < MP ? xp + (size_t)row * D : xs + (size_t)(row - MP) * D) : X + (size_t)row * D;
;                 const float* gp = gate + (size_t)mod_row(row) * 6144;
; #pragma unroll
;                 for (int bj = 0; bj < 2; ++bj)
; #pragma unroll
;                     for (int n = 0; n < 2; ++n) { const int col = u.pn * 256 + bj * 128 + wc * 32 + n * 16 + fq * 4;
;                         const f32x4 ga = *(const f32x4*)(gp + col) * acc[ai][bj][m][n];
;                         if (u.split) { *(f32x4*)(part + ((size_t)(u.k0 >> 8) * MS + (row - MP)) * D + col) = ga;
;                         } else *(f32x4*)(X + (size_t)row * D + col) = *(const f32x4*)(base + col) + ga; } }
; __global__ void __launch_bounds__(512, 2) hybrid_fwd(Params P) {
;     ...
;             EpiRes E{nullptr, nullptr, X, (MOD + (size_t)l * NMODROWS * 6144) + 5120, (float*)(ws + WS_PART)};
;             pg8::gemm_phase<EpiRes, true>(ldsl, g, S, E, wave);
;         }
;         PHASE_END
;         PHASE_BEGIN
;         if (l + 1 < DEPTH) norm_rows<false>(nullptr, nullptr, X, INP(9) + (l + 1) * D, (MOD + (size_t)l * NMODROWS * 6144) + (size_t)NMODROWS * 6144, (MOD + (size_t)l * NMODROWS * 6144) + (size_t)NMODROWS * 6144 + 1024, XN, nullptr, gw, NGW, lane, (const float*)(ws + WS_PART), DFF / 256);
;         else norm_rows<true>(nullptr, nullptr, X, INP(33), nullptr, nullptr, nullptr, out, gw, NGW, lane, (const float*)(ws + WS_PART), DFF / 256);
.LBB0_1882:
	s_lshl_b32 s2, s55, 8
	s_add_i32 s2, s2, s43
	s_lshl_b32 s3, s53, 8
	s_add_i32 s3, s3, s44
	v_add_u32_e32 v207, s2, v151
	v_lshl_add_u32 v159, v152, 2, s3
	v_mov_b32_e32 v197, 0
	s_mov_b32 s70, 0x10000
	s_mov_b32 s71, 0
	s_mov_b32 s98, 0x50000
	s_mov_b32 s99, 0
	s_cmp_lg_u32 s54, 0
	s_cbranch_scc1 .Lepi_dn_split
	s_cmp_eq_u32 s96, 3
	s_cbranch_scc1 .Lepi_dn_final
	s_mov_b32 s66, 0x10000
	s_mov_b32 s67, 0
	s_mov_b32 s68, 0x50000
	s_mov_b32 s69, 0
	v_lshlrev_b32_e32 v140, 11, v207
	v_lshl_add_u32 v140, v159, 1, v140
	v_mov_b32_e32 v141, 0
	s_add_u32 s70, s10, 0x4200000
	s_addc_u32 s71, s11, 0
	v_lshl_add_u64 v[128:129], v[140:141], 0, s[70:71]
	v_lshlrev_b32_e32 v196, 12, v207
	v_lshl_add_u32 v196, v159, 2, v196
	v_add_u32_e32 v142, s43, v151
	v_lshrrev_b32_e32 v207, 12, v207
	v_lshlrev_b32_e32 v159, 2, v159
	v_mad_u32_u24 v130, v207, s80, v159
	v_mov_b32_e32 v131, 0
	v_lshl_add_u64 v[130:131], v[130:131], 0, s[12:13]
	global_load_dwordx4 v[240:243], v[130:131], off
	global_load_dwordx4 v[244:247], v[130:131], off offset:64
	global_load_dwordx4 v[248:251], v[130:131], off offset:512
	global_load_dwordx4 v[184:187], v[130:131], off offset:576
	v_lshl_add_u64 v[144:145], v[196:197], 0, s[10:11]
	v_lshl_add_u64 v[146:147], v[196:197], 0, s[10:11]
	v_mov_b32_e32 v188, 0
	v_mov_b32_e32 v189, 0
	v_mov_b32_e32 v190, 0
	v_mov_b32_e32 v191, 0
	v_mov_b32_e32 v192, 0
	v_mov_b32_e32 v193, 0
	v_mov_b32_e32 v194, 0
	v_mov_b32_e32 v195, 0
	global_load_dwordx4 v[208:211], v[144:145], off
	global_load_dwordx4 v[212:215], v[144:145], off offset:64
	global_load_dwordx4 v[216:219], v[144:145], off offset:512
	global_load_dwordx4 v[220:223], v[144:145], off offset:576
	v_lshl_add_u64 v[144:145], v[144:145], 0, s[66:67]
	global_load_dwordx4 v[224:227], v[144:145], off
	global_load_dwordx4 v[228:231], v[144:145], off offset:64
	global_load_dwordx4 v[232:235], v[144:145], off offset:512
	global_load_dwordx4 v[236:239], v[144:145], off offset:576
	v_lshl_add_u64 v[144:145], v[144:145], 0, s[66:67]
	s_waitcnt vmcnt(4)
	v_pk_mul_f32 v[126:127], v[126:127], v[242:243]
	v_pk_mul_f32 v[124:125], v[124:125], v[240:241]
	v_pk_add_f32 v[126:127], v[126:127], v[210:211]
	v_pk_add_f32 v[124:125], v[124:125], v[208:209]
	v_pk_mul_f32 v[122:123], v[122:123], v[246:247]
	v_pk_mul_f32 v[120:121], v[120:121], v[244:245]
	v_pk_add_f32 v[122:123], v[122:123], v[214:215]
	v_pk_add_f32 v[120:121], v[120:121], v[212:213]
	v_pk_mul_f32 v[118:119], v[118:119], v[250:251]
	v_pk_mul_f32 v[116:117], v[116:117], v[248:249]
	v_pk_add_f32 v[118:119], v[118:119], v[218:219]
	v_pk_add_f32 v[116:117], v[116:117], v[216:217]
	v_pk_mul_f32 v[114:115], v[114:115], v[186:187]
	v_pk_mul_f32 v[112:113], v[112:113], v[184:185]
	v_pk_add_f32 v[114:115], v[114:115], v[222:223]
	v_pk_add_f32 v[112:113], v[112:113], v[220:221]
	v_pk_mul_f32 v[140:141], v[124:125], v[124:125]
	v_pk_fma_f32 v[140:141], v[126:127], v[126:127], v[140:141]
	v_add_f32_e32 v188, v188, v140
	v_add_f32_e32 v188, v188, v141
	v_pk_mul_f32 v[140:141], v[120:121], v[120:121]
	v_pk_fma_f32 v[140:141], v[122:123], v[122:123], v[140:141]
	v_add_f32_e32 v188, v188, v140
	v_add_f32_e32 v188, v188, v141
	v_pk_mul_f32 v[140:141], v[116:117], v[116:117]
	v_pk_fma_f32 v[140:141], v[118:119], v[118:119], v[140:141]
	v_add_f32_e32 v188, v188, v140
	v_add_f32_e32 v188, v188, v141
	v_pk_mul_f32 v[140:141], v[112:113], v[112:113]
	v_pk_fma_f32 v[140:141], v[114:115], v[114:115], v[140:141]
	v_add_f32_e32 v188, v188, v140
	v_add_f32_e32 v188, v188, v141
	global_load_dwordx4 v[208:211], v[144:145], off
	global_load_dwordx4 v[212:215], v[144:145], off offset:64
	global_load_dwordx4 v[216:219], v[144:145], off offset:512
	global_load_dwordx4 v[220:223], v[144:145], off offset:576
	v_lshl_add_u64 v[144:145], v[144:145], 0, s[66:67]
	s_waitcnt vmcnt(4)
	v_pk_mul_f32 v[110:111], v[110:111], v[242:243]
	v_pk_mul_f32 v[108:109], v[108:109], v[240:241]
	v_pk_add_f32 v[110:111], v[110:111], v[226:227]
	v_pk_add_f32 v[108:109], v[108:109], v[224:225]
	v_pk_mul_f32 v[106:107], v[106:107], v[246:247]
	v_pk_mul_f32 v[104:105], v[104:105], v[244:245]
	v_pk_add_f32 v[106:107], v[106:107], v[230:231]
	v_pk_add_f32 v[104:105], v[104:105], v[228:229]
	v_pk_mul_f32 v[102:103], v[102:103], v[250:251]
	v_pk_mul_f32 v[100:101], v[100:101], v[248:249]
	v_pk_add_f32 v[102:103], v[102:103], v[234:235]
	v_pk_add_f32 v[100:101], v[100:101], v[232:233]
	v_pk_mul_f32 v[98:99], v[98:99], v[186:187]
	v_pk_mul_f32 v[96:97], v[96:97], v[184:185]
	v_pk_add_f32 v[98:99], v[98:99], v[238:239]
	v_pk_add_f32 v[96:97], v[96:97], v[236:237]
	v_pk_mul_f32 v[140:141], v[108:109], v[108:109]
	v_pk_fma_f32 v[140:141], v[110:111], v[110:111], v[140:141]
	v_add_f32_e32 v189, v189, v140
	v_add_f32_e32 v189, v189, v141
	v_pk_mul_f32 v[140:141], v[104:105], v[104:105]
	v_pk_fma_f32 v[140:141], v[106:107], v[106:107], v[140:141]
	v_add_f32_e32 v189, v189, v140
	v_add_f32_e32 v189, v189, v141
	v_pk_mul_f32 v[140:141], v[100:101], v[100:101]
	v_pk_fma_f32 v[140:141], v[102:103], v[102:103], v[140:141]
	v_add_f32_e32 v189, v189, v140
	v_add_f32_e32 v189, v189, v141
	v_pk_mul_f32 v[140:141], v[96:97], v[96:97]
	v_pk_fma_f32 v[140:141], v[98:99], v[98:99], v[140:141]
	v_add_f32_e32 v189, v189, v140
	v_add_f32_e32 v189, v189, v141
	global_load_dwordx4 v[224:227], v[144:145], off
	global_load_dwordx4 v[228:231], v[144:145], off offset:64
	global_load_dwordx4 v[232:235], v[144:145], off offset:512
	global_load_dwordx4 v[236:239], v[144:145], off offset:576
	v_lshl_add_u64 v[144:145], v[144:145], 0, s[68:69]
	s_waitcnt vmcnt(4)
;     __device__ __forceinline__ void operator()(const Acc& acc, const Unit& u, int wr, int wc, int fr, int fq) const {
;     ...
;             for (int m = 0; m < 4; ++m) { const int row = u.pm * 256 + ai * 128 + wr * 64 + m * 16 + fr;
;                 const float* base = xp ? (row < MP ? xp + (size_t)row * D : xs + (size_t)(row - MP) * D) : X + (size_t)row * D;
;                 const float* gp = gate + (size_t)mod_row(row) * 6144;
; #pragma unroll
;                 for (int bj = 0; bj < 2; ++bj)
; #pragma unroll
;                     for (int n = 0; n < 2; ++n) { const int col = u.pn * 256 + bj * 128 + wc * 32 + n * 16 + fq * 4;
;                         const f32x4 ga = *(const f32x4*)(gp + col) * acc[ai][bj][m][n];
;                         if (u.split) { *(f32x4*)(part + ((size_t)(u.k0 >> 8) * MS + (row - MP)) * D + col) = ga;
;                         } else *(f32x4*)(X + (size_t)row * D + col) = *(const f32x4*)(base + col) + ga; } }
; template <bool FINAL>
; __device__ __forceinline__ void norm_rows(const float* xp, const float* xs, const float* X, const float* g, const float* sh, const float* sc, bf16_t* XN, float* out, int gw, int NGW, int lane, const float* part, int nsplit) {
;     ...
;         for (int j = 0; j < 4; ++j) s += (v[j][0] * v[j][0] + v[j][1] * v[j][1]) + (v[j][2] * v[j][2] + v[j][3] * v[j][3]);
	v_pk_mul_f32 v[94:95], v[94:95], v[242:243]
	v_pk_mul_f32 v[92:93], v[92:93], v[240:241]
	v_pk_add_f32 v[94:95], v[94:95], v[210:211]
	v_pk_add_f32 v[92:93], v[92:93], v[208:209]
	v_pk_mul_f32 v[90:91], v[90:91], v[246:247]
	v_pk_mul_f32 v[88:89], v[88:89], v[244:245]
	v_pk_add_f32 v[90:91], v[90:91], v[214:215]
	v_pk_add_f32 v[88:89], v[88:89], v[212:213]
	v_pk_mul_f32 v[86:87], v[86:87], v[250:251]
	v_pk_mul_f32 v[84:85], v[84:85], v[248:249]
	v_pk_add_f32 v[86:87], v[86:87], v[218:219]
	v_pk_add_f32 v[84:85], v[84:85], v[216:217]
	v_pk_mul_f32 v[82:83], v[82:83], v[186:187]
	v_pk_mul_f32 v[80:81], v[80:81], v[184:185]
	v_pk_add_f32 v[82:83], v[82:83], v[222:223]
	v_pk_add_f32 v[80:81], v[80:81], v[220:221]
	v_pk_mul_f32 v[140:141], v[92:93], v[92:93]
	v_pk_fma_f32 v[140:141], v[94:95], v[94:95], v[140:141]
	v_add_f32_e32 v190, v190, v140
	v_add_f32_e32 v190, v190, v141
	v_pk_mul_f32 v[140:141], v[88:89], v[88:89]
	v_pk_fma_f32 v[140:141], v[90:91], v[90:91], v[140:141]
	v_add_f32_e32 v190, v190, v140
	v_add_f32_e32 v190, v190, v141
	v_pk_mul_f32 v[140:141], v[84:85], v[84:85]
	v_pk_fma_f32 v[140:141], v[86:87], v[86:87], v[140:141]
	v_add_f32_e32 v190, v190, v140
	v_add_f32_e32 v190, v190, v141
	v_pk_mul_f32 v[140:141], v[80:81], v[80:81]
	v_pk_fma_f32 v[140:141], v[82:83], v[82:83], v[140:141]
	v_add_f32_e32 v190, v190, v140
	v_add_f32_e32 v190, v190, v141
	global_load_dwordx4 v[208:211], v[144:145], off
	global_load_dwordx4 v[212:215], v[144:145], off offset:64
	global_load_dwordx4 v[216:219], v[144:145], off offset:512
	global_load_dwordx4 v[220:223], v[144:145], off offset:576
	v_lshl_add_u64 v[144:145], v[144:145], 0, s[66:67]
	s_waitcnt vmcnt(4)
	v_pk_mul_f32 v[78:79], v[78:79], v[242:243]
	v_pk_mul_f32 v[76:77], v[76:77], v[240:241]
	v_pk_add_f32 v[78:79], v[78:79], v[226:227]
	v_pk_add_f32 v[76:77], v[76:77], v[224:225]
	v_pk_mul_f32 v[74:75], v[74:75], v[246:247]
	v_pk_mul_f32 v[72:73], v[72:73], v[244:245]
	v_pk_add_f32 v[74:75], v[74:75], v[230:231]
	v_pk_add_f32 v[72:73], v[72:73], v[228:229]
	v_pk_mul_f32 v[70:71], v[70:71], v[250:251]
	v_pk_mul_f32 v[68:69], v[68:69], v[248:249]
	v_pk_add_f32 v[70:71], v[70:71], v[234:235]
	v_pk_add_f32 v[68:69], v[68:69], v[232:233]
	v_pk_mul_f32 v[66:67], v[66:67], v[186:187]
	v_pk_mul_f32 v[64:65], v[64:65], v[184:185]
	v_pk_add_f32 v[66:67], v[66:67], v[238:239]
	v_pk_add_f32 v[64:65], v[64:65], v[236:237]
	v_pk_mul_f32 v[140:141], v[76:77], v[76:77]
	v_pk_fma_f32 v[140:141], v[78:79], v[78:79], v[140:141]
	v_add_f32_e32 v191, v191, v140
	v_add_f32_e32 v191, v191, v141
	v_pk_mul_f32 v[140:141], v[72:73], v[72:73]
	v_pk_fma_f32 v[140:141], v[74:75], v[74:75], v[140:141]
	v_add_f32_e32 v191, v191, v140
	v_add_f32_e32 v191, v191, v141
	v_pk_mul_f32 v[140:141], v[68:69], v[68:69]
	v_pk_fma_f32 v[140:141], v[70:71], v[70:71], v[140:141]
	v_add_f32_e32 v191, v191, v140
	v_add_f32_e32 v191, v191, v141
	v_pk_mul_f32 v[140:141], v[64:65], v[64:65]
	v_pk_fma_f32 v[140:141], v[66:67], v[66:67], v[140:141]
	v_add_f32_e32 v191, v191, v140
	v_add_f32_e32 v191, v191, v141
	global_load_dwordx4 v[224:227], v[144:145], off
	global_load_dwordx4 v[228:231], v[144:145], off offset:64
	global_load_dwordx4 v[232:235], v[144:145], off offset:512
	global_load_dwordx4 v[236:239], v[144:145], off offset:576
	v_lshl_add_u64 v[144:145], v[144:145], 0, s[66:67]
	s_waitcnt vmcnt(4)
	v_pk_mul_f32 v[62:63], v[62:63], v[242:243]
	v_pk_mul_f32 v[60:61], v[60:61], v[240:241]
	v_pk_add_f32 v[62:63], v[62:63], v[210:211]
	v_pk_add_f32 v[60:61], v[60:61], v[208:209]
	v_pk_mul_f32 v[58:59], v[58:59], v[246:247]
	v_pk_mul_f32 v[56:57], v[56:57], v[244:245]
	v_pk_add_f32 v[58:59], v[58:59], v[214:215]
	v_pk_add_f32 v[56:57], v[56:57], v[212:213]
	v_pk_mul_f32 v[54:55], v[54:55], v[250:251]
	v_pk_mul_f32 v[52:53], v[52:53], v[248:249]
	v_pk_add_f32 v[54:55], v[54:55], v[218:219]
	v_pk_add_f32 v[52:53], v[52:53], v[216:217]
	v_pk_mul_f32 v[50:51], v[50:51], v[186:187]
	v_pk_mul_f32 v[48:49], v[48:49], v[184:185]
	v_pk_add_f32 v[50:51], v[50:51], v[222:223]
	v_pk_add_f32 v[48:49], v[48:49], v[220:221]
	v_pk_mul_f32 v[140:141], v[60:61], v[60:61]
	v_pk_fma_f32 v[140:141], v[62:63], v[62:63], v[140:141]
	v_add_f32_e32 v192, v192, v140
	v_add_f32_e32 v192, v192, v141
	v_pk_mul_f32 v[140:141], v[56:57], v[56:57]
	v_pk_fma_f32 v[140:141], v[58:59], v[58:59], v[140:141]
	v_add_f32_e32 v192, v192, v140
	v_add_f32_e32 v192, v192, v141
	v_pk_mul_f32 v[140:141], v[52:53], v[52:53]
	v_pk_fma_f32 v[140:141], v[54:55], v[54:55], v[140:141]
	v_add_f32_e32 v192, v192, v140
	v_add_f32_e32 v192, v192, v141
	v_pk_mul_f32 v[140:141], v[48:49], v[48:49]
	v_pk_fma_f32 v[140:141], v[50:51], v[50:51], v[140:141]
	v_add_f32_e32 v192, v192, v140
	v_add_f32_e32 v192, v192, v141
	global_load_dwordx4 v[208:211], v[144:145], off
	global_load_dwordx4 v[212:215], v[144:145], off offset:64
	global_load_dwordx4 v[216:219], v[144:145], off offset:512
	global_load_dwordx4 v[220:223], v[144:145], off offset:576
	v_lshl_add_u64 v[144:145], v[144:145], 0, s[66:67]
	s_waitcnt vmcnt(4)
; #define SWZ(v, pat) __builtin_bit_cast(float, __builtin_amdgcn_ds_swizzle(__builtin_bit_cast(int, (v)), (pat)))
; __device__ __forceinline__ float xor32_sum(float v) { float a = v, b = v; asm volatile("s_nop 1\n\tv_permlane32_swap_b32 %0, %1\n\ts_nop 1" : "+v"(a), "+v"(b)); return a + b; }
; __device__ __forceinline__ float wave_sum(float v) {
;     v += SWZ(v, 0x041f); v += SWZ(v, 0x081f); v += SWZ(v, 0x101f); v += SWZ(v, 0x201f); v += SWZ(v, 0x401f); return xor32_sum(v);
; }
; template <bool FINAL>
; __device__ __forceinline__ void norm_rows(const float* xp, const float* xs, const float* X, const float* g, const float* sh, const float* sc, bf16_t* XN, float* out, int gw, int NGW, int lane, const float* part, int nsplit) {
;     ...
;         for (int j = 0; j < 4; ++j) s += (v[j][0] * v[j][0] + v[j][1] * v[j][1]) + (v[j][2] * v[j][2] + v[j][3] * v[j][3]);
;         const float rstd = 1.0f / sqrtf(wave_sum(s) * (1.0f / D) + EPS);
	v_pk_mul_f32 v[46:47], v[46:47], v[242:243]
	v_pk_mul_f32 v[44:45], v[44:45], v[240:241]
	v_pk_add_f32 v[46:47], v[46:47], v[226:227]
	v_pk_add_f32 v[44:45], v[44:45], v[224:225]
	v_pk_mul_f32 v[42:43], v[42:43], v[246:247]
	v_pk_mul_f32 v[40:41], v[40:41], v[244:245]
	v_pk_add_f32 v[42:43], v[42:43], v[230:231]
	v_pk_add_f32 v[40:41], v[40:41], v[228:229]
	v_pk_mul_f32 v[38:39], v[38:39], v[250:251]
	v_pk_mul_f32 v[36:37], v[36:37], v[248:249]
	v_pk_add_f32 v[38:39], v[38:39], v[234:235]
	v_pk_add_f32 v[36:37], v[36:37], v[232:233]
	v_pk_mul_f32 v[34:35], v[34:35], v[186:187]
	v_pk_mul_f32 v[32:33], v[32:33], v[184:185]
	v_pk_add_f32 v[34:35], v[34:35], v[238:239]
	v_pk_add_f32 v[32:33], v[32:33], v[236:237]
	v_pk_mul_f32 v[140:141], v[44:45], v[44:45]
	v_pk_fma_f32 v[140:141], v[46:47], v[46:47], v[140:141]
	v_add_f32_e32 v193, v193, v140
	v_add_f32_e32 v193, v193, v141
	v_pk_mul_f32 v[140:141], v[40:41], v[40:41]
	v_pk_fma_f32 v[140:141], v[42:43], v[42:43], v[140:141]
	v_add_f32_e32 v193, v193, v140
	v_add_f32_e32 v193, v193, v141
	v_pk_mul_f32 v[140:141], v[36:37], v[36:37]
	v_pk_fma_f32 v[140:141], v[38:39], v[38:39], v[140:141]
	v_add_f32_e32 v193, v193, v140
	v_add_f32_e32 v193, v193, v141
	v_pk_mul_f32 v[140:141], v[32:33], v[32:33]
	v_pk_fma_f32 v[140:141], v[34:35], v[34:35], v[140:141]
	v_add_f32_e32 v193, v193, v140
	v_add_f32_e32 v193, v193, v141
	global_load_dwordx4 v[224:227], v[144:145], off
	global_load_dwordx4 v[228:231], v[144:145], off offset:64
	global_load_dwordx4 v[232:235], v[144:145], off offset:512
	global_load_dwordx4 v[236:239], v[144:145], off offset:576
	s_waitcnt vmcnt(4)
	v_pk_mul_f32 v[30:31], v[30:31], v[242:243]
	v_pk_mul_f32 v[28:29], v[28:29], v[240:241]
	v_pk_add_f32 v[30:31], v[30:31], v[210:211]
	v_pk_add_f32 v[28:29], v[28:29], v[208:209]
	v_pk_mul_f32 v[26:27], v[26:27], v[246:247]
	v_pk_mul_f32 v[24:25], v[24:25], v[244:245]
	v_pk_add_f32 v[26:27], v[26:27], v[214:215]
	v_pk_add_f32 v[24:25], v[24:25], v[212:213]
	v_pk_mul_f32 v[22:23], v[22:23], v[250:251]
	v_pk_mul_f32 v[20:21], v[20:21], v[248:249]
	v_pk_add_f32 v[22:23], v[22:23], v[218:219]
	v_pk_add_f32 v[20:21], v[20:21], v[216:217]
	v_pk_mul_f32 v[18:19], v[18:19], v[186:187]
	v_pk_mul_f32 v[16:17], v[16:17], v[184:185]
	v_pk_add_f32 v[18:19], v[18:19], v[222:223]
	v_pk_add_f32 v[16:17], v[16:17], v[220:221]
	v_pk_mul_f32 v[140:141], v[28:29], v[28:29]
	v_pk_fma_f32 v[140:141], v[30:31], v[30:31], v[140:141]
	v_add_f32_e32 v194, v194, v140
	v_add_f32_e32 v194, v194, v141
	v_pk_mul_f32 v[140:141], v[24:25], v[24:25]
	v_pk_fma_f32 v[140:141], v[26:27], v[26:27], v[140:141]
	v_add_f32_e32 v194, v194, v140
	v_add_f32_e32 v194, v194, v141
	v_pk_mul_f32 v[140:141], v[20:21], v[20:21]
	v_pk_fma_f32 v[140:141], v[22:23], v[22:23], v[140:141]
	v_add_f32_e32 v194, v194, v140
	v_add_f32_e32 v194, v194, v141
	v_pk_mul_f32 v[140:141], v[16:17], v[16:17]
	v_pk_fma_f32 v[140:141], v[18:19], v[18:19], v[140:141]
	v_add_f32_e32 v194, v194, v140
	v_add_f32_e32 v194, v194, v141
	s_waitcnt vmcnt(0)
	v_pk_mul_f32 v[14:15], v[14:15], v[242:243]
	v_pk_mul_f32 v[12:13], v[12:13], v[240:241]
	v_pk_add_f32 v[14:15], v[14:15], v[226:227]
	v_pk_add_f32 v[12:13], v[12:13], v[224:225]
	v_pk_mul_f32 v[10:11], v[10:11], v[246:247]
	v_pk_mul_f32 v[8:9], v[8:9], v[244:245]
	v_pk_add_f32 v[10:11], v[10:11], v[230:231]
	v_pk_add_f32 v[8:9], v[8:9], v[228:229]
	v_pk_mul_f32 v[6:7], v[6:7], v[250:251]
	v_pk_mul_f32 v[4:5], v[4:5], v[248:249]
	v_pk_add_f32 v[6:7], v[6:7], v[234:235]
	v_pk_add_f32 v[4:5], v[4:5], v[232:233]
	v_pk_mul_f32 v[2:3], v[2:3], v[186:187]
	v_pk_mul_f32 v[0:1], v[0:1], v[184:185]
	v_pk_add_f32 v[2:3], v[2:3], v[238:239]
	v_pk_add_f32 v[0:1], v[0:1], v[236:237]
	v_pk_mul_f32 v[140:141], v[12:13], v[12:13]
	v_pk_fma_f32 v[140:141], v[14:15], v[14:15], v[140:141]
	v_add_f32_e32 v195, v195, v140
	v_add_f32_e32 v195, v195, v141
	v_pk_mul_f32 v[140:141], v[8:9], v[8:9]
	v_pk_fma_f32 v[140:141], v[10:11], v[10:11], v[140:141]
	v_add_f32_e32 v195, v195, v140
	v_add_f32_e32 v195, v195, v141
	v_pk_mul_f32 v[140:141], v[4:5], v[4:5]
	v_pk_fma_f32 v[140:141], v[6:7], v[6:7], v[140:141]
	v_add_f32_e32 v195, v195, v140
	v_add_f32_e32 v195, v195, v141
	v_pk_mul_f32 v[140:141], v[0:1], v[0:1]
	v_pk_fma_f32 v[140:141], v[2:3], v[2:3], v[140:141]
	v_add_f32_e32 v195, v195, v140
	v_add_f32_e32 v195, v195, v141
	ds_swizzle_b32 v208, v188 offset:swizzle(SWAP,16)
	ds_swizzle_b32 v209, v189 offset:swizzle(SWAP,16)
	ds_swizzle_b32 v210, v190 offset:swizzle(SWAP,16)
	ds_swizzle_b32 v211, v191 offset:swizzle(SWAP,16)
	ds_swizzle_b32 v212, v192 offset:swizzle(SWAP,16)
	ds_swizzle_b32 v213, v193 offset:swizzle(SWAP,16)
	ds_swizzle_b32 v214, v194 offset:swizzle(SWAP,16)
	ds_swizzle_b32 v215, v195 offset:swizzle(SWAP,16)
	s_waitcnt lgkmcnt(0)
	v_add_f32_e32 v188, v188, v208
	v_add_f32_e32 v189, v189, v209
	v_add_f32_e32 v190, v190, v210
	v_add_f32_e32 v191, v191, v211
	v_add_f32_e32 v192, v192, v212
	v_add_f32_e32 v193, v193, v213
	v_add_f32_e32 v194, v194, v214
	v_add_f32_e32 v195, v195, v215
	v_mov_b32_e32 v208, v188
	v_mov_b32_e32 v209, v189
	v_mov_b32_e32 v210, v190
	v_mov_b32_e32 v211, v191
	v_mov_b32_e32 v212, v192
	v_mov_b32_e32 v213, v193
	v_mov_b32_e32 v214, v194
	v_mov_b32_e32 v215, v195
	s_nop 1
	v_permlane32_swap_b32 v188, v208
	v_permlane32_swap_b32 v189, v209
	v_permlane32_swap_b32 v190, v210
	v_permlane32_swap_b32 v191, v211
	v_permlane32_swap_b32 v192, v212
	v_permlane32_swap_b32 v193, v213
	v_permlane32_swap_b32 v194, v214
	v_permlane32_swap_b32 v195, v215
	s_nop 1
	v_add_f32_e32 v188, v188, v208
	v_add_f32_e32 v189, v189, v209
	v_add_f32_e32 v190, v190, v210
	v_add_f32_e32 v191, v191, v211
	v_add_f32_e32 v192, v192, v212
	v_add_f32_e32 v193, v193, v213
	v_add_f32_e32 v194, v194, v214
	v_add_f32_e32 v195, v195, v215
	v_readlane_b32 s25, v253, 2
	s_nop 3
	s_and_b32 s27, s25, 3
	s_lshl_b32 s27, s27, 10
	s_add_i32 s27, s27, 0x20800
	v_lshl_add_u32 v143, v142, 2, s27
	ds_write_b32 v143, v188
	ds_write_b32 v143, v189 offset:64
	ds_write_b32 v143, v190 offset:128
	ds_write_b32 v143, v191 offset:192
	ds_write_b32 v143, v192 offset:512
	ds_write_b32 v143, v193 offset:576
	ds_write_b32 v143, v194 offset:640
	ds_write_b32 v143, v195 offset:704
	v_mbcnt_lo_u32_b32 v207, -1, 0
	v_mbcnt_hi_u32_b32 v207, -1, v207
	s_lshl_b32 s27, s25, 6
	v_add_u32_e32 v207, s27, v207
	v_lshlrev_b32_e32 v207, 2, v207
	s_sub_u32 s70, s10, 0x7800000
	s_subb_u32 s71, s11, 0
	s_lshl_b32 s74, s55, 10
	s_add_u32 s70, s70, s74
	s_addc_u32 s71, s71, 0
	s_sub_u32 s98, s10, 0x7dfffc0
	s_subb_u32 s99, s11, 0
	s_lshl_b32 s74, s55, 2
	s_add_u32 s98, s98, s74
	s_addc_u32 s99, s99, 0
	s_lshl_b32 s32, s96, 3
	s_add_i32 s32, s32, 8
	s_waitcnt lgkmcnt(0)
	s_barrier
; template <bool FINAL>
; __device__ __forceinline__ void norm_rows(const float* xp, const float* xs, const float* X, const float* g, const float* sh, const float* sc, bf16_t* XN, float* out, int gw, int NGW, int lane, const float* part, int nsplit) {
;     ...
;         const float rstd = 1.0f / sqrtf(wave_sum(s) * (1.0f / D) + EPS);
;         const int mr = mod_row(row);
;         if (!FINAL && xp && row >= MP) {
; #pragma unroll
;             for (int j = 0; j < 4; ++j) *(f32x4*)((float*)X + (size_t)row * D + 4 * lane + 256 * j) = v[j]; }
; #pragma unroll
;         for (int j = 0; j < 4; ++j) { const int col = 4 * lane + 256 * j; const f32x4 gg = *(const f32x4*)(g + col);
;             if (FINAL) { *(f32x4*)(out + (size_t)row * D + col) = v[j] * rstd * gg; }
;             else { const f32x4 s1 = *(const f32x4*)(sc + (size_t)mr * 6144 + col), s0 = *(const f32x4*)(sh + (size_t)mr * 6144 + col);
;                 const f32x4 h = v[j] * rstd * gg * (s1 + 1.0f) + s0;
	s_cmp_lt_u32 s25, 4
	s_cbranch_scc0 .Lfz_dn_nopub
	v_add_u32_e32 v140, 0x20800, v207
	ds_read_b32 v212, v140
	ds_read_b32 v213, v140 offset:1024
	ds_read_b32 v214, v140 offset:2048
	ds_read_b32 v215, v140 offset:3072
	s_lshl_b32 s74, s53, 16
	v_add_u32_e32 v141, s74, v207
	s_waitcnt lgkmcnt(0)
	v_add_f32_e32 v212, v212, v213
	v_add_f32_e32 v212, v212, v214
	v_add_f32_e32 v212, v212, v215
	global_store_dword v141, v212, s[70:71] sc0 sc1
.Lfz_dn_nopub:
	s_waitcnt vmcnt(0)
	s_barrier
	v_mov_b32_e32 v140, 0x20448
	ds_read_b64 v[140:141], v140
	s_waitcnt lgkmcnt(0)
	v_readfirstlane_b32 s2, v140
	v_readfirstlane_b32 s3, v141
	s_add_i32 s74, s96, 1
	s_lshl_b32 s74, s74, 12
	s_add_u32 s2, s2, s74
	s_addc_u32 s3, s3, 0
	s_nop 4
	global_load_dwordx4 v[208:211], v159, s[2:3]
	global_load_dwordx4 v[212:215], v159, s[2:3] offset:64
	global_load_dwordx4 v[216:219], v159, s[2:3] offset:512
	global_load_dwordx4 v[220:223], v159, s[2:3] offset:576
	s_mov_b32 s74, 0x313000
	v_add_co_u32_e32 v130, vcc, s74, v130
	s_nop 1
	v_addc_co_u32_e32 v131, vcc, 0, v131, vcc
	global_load_dwordx4 v[240:243], v[130:131], off
	global_load_dwordx4 v[244:247], v[130:131], off offset:64
	global_load_dwordx4 v[248:251], v[130:131], off offset:512
	global_load_dwordx4 v[184:187], v[130:131], off offset:576
	v_add_co_u32_e32 v130, vcc, 0x1000, v130
	s_nop 1
	v_addc_co_u32_e32 v131, vcc, 0, v131, vcc
	global_load_dwordx4 v[224:227], v[130:131], off
	global_load_dwordx4 v[228:231], v[130:131], off offset:64
	global_load_dwordx4 v[232:235], v[130:131], off offset:512
	global_load_dwordx4 v[236:239], v[130:131], off offset:576
	s_cmp_eq_u32 s25, 0
	s_cbranch_scc0 .Lfz_dn_nopoll
	s_mov_b64 exec, 1
	v_mov_b32_e32 v140, 0
	v_mov_b32_e32 v141, 1
	global_atomic_add v140, v141, s[98:99]
	s_mov_b32 s65, 0

; #define INP(i) ((const float*)ld_ptr(pb, (i)))
;     __device__ __forceinline__ void operator()(const Acc& acc, const Unit& u, int wr, int wc, int fr, int fq) const {
; #pragma unroll
;         for (int ai = 0; ai < 2; ++ai)
; #pragma unroll
;             for (int m = 0; m < 4; ++m) { const int row = u.pm * 256 + ai * 128 + wr * 64 + m * 16 + fr;
;                 const float* base = xp ? (row < MP ? xp + (size_t)row * D : xs + (size_t)(row - MP) * D) : X + (size_t)row * D;
;                 const float* gp = gate + (size_t)mod_row(row) * 6144;
; #pragma unroll
;                 for (int bj = 0; bj < 2; ++bj)
; #pragma unroll
;                     for (int n = 0; n < 2; ++n) { const int col = u.pn * 256 + bj * 128 + wc * 32 + n * 16 + fq * 4;
;                         const f32x4 ga = *(const f32x4*)(gp + col) * acc[ai][bj][m][n];
;                         if (u.split) { *(f32x4*)(part + ((size_t)(u.k0 >> 8) * MS + (row - MP)) * D + col) = ga;
;                         } else *(f32x4*)(X + (size_t)row * D + col) = *(const f32x4*)(base + col) + ga; } }
; __global__ void __launch_bounds__(512, 2) hybrid_fwd(Params P) {
;     ...
;         else norm_rows<true>(nullptr, nullptr, X, INP(33), nullptr, nullptr, nullptr, out, gw, NGW, lane, (const float*)(ws + WS_PART), DFF / 256);
.Lepi_dn_final:
	s_mov_b32 s66, 0x10000
	s_mov_b32 s67, 0
	s_mov_b32 s68, 0x50000
	s_mov_b32 s69, 0
	v_lshlrev_b32_e32 v140, 11, v207
	v_lshl_add_u32 v140, v159, 1, v140
	v_mov_b32_e32 v141, 0
	s_add_u32 s70, s10, 0x4200000
	s_addc_u32 s71, s11, 0
	v_lshl_add_u64 v[128:129], v[140:141], 0, s[70:71]
	v_lshlrev_b32_e32 v196, 12, v207
	v_lshl_add_u32 v196, v159, 2, v196
	v_add_u32_e32 v142, s43, v151
	v_lshrrev_b32_e32 v207, 12, v207
	v_lshlrev_b32_e32 v159, 2, v159
	v_mad_u32_u24 v130, v207, s80, v159
	v_mov_b32_e32 v131, 0
	v_lshl_add_u64 v[130:131], v[130:131], 0, s[12:13]
	global_load_dwordx4 v[240:243], v[130:131], off
	global_load_dwordx4 v[244:247], v[130:131], off offset:64
	global_load_dwordx4 v[248:251], v[130:131], off offset:512
	global_load_dwordx4 v[184:187], v[130:131], off offset:576
	v_mov_b32_e32 v140, 0x20510
	ds_read_b64 v[140:141], v140
	v_lshl_add_u64 v[144:145], v[196:197], 0, s[10:11]
	s_waitcnt lgkmcnt(0)
	v_readfirstlane_b32 s2, v140
	v_readfirstlane_b32 s3, v141
	s_nop 3
	v_lshl_add_u64 v[146:147], v[196:197], 0, s[2:3]
	v_mov_b32_e32 v188, 0
	v_mov_b32_e32 v189, 0
	v_mov_b32_e32 v190, 0
	v_mov_b32_e32 v191, 0
	v_mov_b32_e32 v192, 0
	v_mov_b32_e32 v193, 0
	v_mov_b32_e32 v194, 0
	v_mov_b32_e32 v195, 0
	global_load_dwordx4 v[208:211], v[144:145], off
	global_load_dwordx4 v[212:215], v[144:145], off offset:64
	global_load_dwordx4 v[216:219], v[144:145], off offset:512
	global_load_dwordx4 v[220:223], v[144:145], off offset:576
	v_lshl_add_u64 v[144:145], v[144:145], 0, s[66:67]
	global_load_dwordx4 v[224:227], v[144:145], off
	global_load_dwordx4 v[228:231], v[144:145], off offset:64
	global_load_dwordx4 v[232:235], v[144:145], off offset:512
	global_load_dwordx4 v[236:239], v[144:145], off offset:576
	v_lshl_add_u64 v[144:145], v[144:145], 0, s[66:67]
	s_waitcnt vmcnt(4)
	v_pk_mul_f32 v[126:127], v[126:127], v[242:243]
	v_pk_mul_f32 v[124:125], v[124:125], v[240:241]
	v_pk_add_f32 v[126:127], v[126:127], v[210:211]
	v_pk_add_f32 v[124:125], v[124:125], v[208:209]
	v_pk_mul_f32 v[122:123], v[122:123], v[246:247]
	v_pk_mul_f32 v[120:121], v[120:121], v[244:245]
	v_pk_add_f32 v[122:123], v[122:123], v[214:215]
	v_pk_add_f32 v[120:121], v[120:121], v[212:213]
	v_pk_mul_f32 v[118:119], v[118:119], v[250:251]
	v_pk_mul_f32 v[116:117], v[116:117], v[248:249]
	v_pk_add_f32 v[118:119], v[118:119], v[218:219]
	v_pk_add_f32 v[116:117], v[116:117], v[216:217]
	v_pk_mul_f32 v[114:115], v[114:115], v[186:187]
	v_pk_mul_f32 v[112:113], v[112:113], v[184:185]
	v_pk_add_f32 v[114:115], v[114:115], v[222:223]
	v_pk_add_f32 v[112:113], v[112:113], v[220:221]
	v_pk_mul_f32 v[140:141], v[124:125], v[124:125]
	v_pk_fma_f32 v[140:141], v[126:127], v[126:127], v[140:141]
	v_add_f32_e32 v188, v188, v140
	v_add_f32_e32 v188, v188, v141
	v_pk_mul_f32 v[140:141], v[120:121], v[120:121]
	v_pk_fma_f32 v[140:141], v[122:123], v[122:123], v[140:141]
	v_add_f32_e32 v188, v188, v140
	v_add_f32_e32 v188, v188, v141
	v_pk_mul_f32 v[140:141], v[116:117], v[116:117]
	v_pk_fma_f32 v[140:141], v[118:119], v[118:119], v[140:141]
	v_add_f32_e32 v188, v188, v140
	v_add_f32_e32 v188, v188, v141
	v_pk_mul_f32 v[140:141], v[112:113], v[112:113]
	v_pk_fma_f32 v[140:141], v[114:115], v[114:115], v[140:141]
	v_add_f32_e32 v188, v188, v140
	v_add_f32_e32 v188, v188, v141
	global_load_dwordx4 v[208:211], v[144:145], off
	global_load_dwordx4 v[212:215], v[144:145], off offset:64
	global_load_dwordx4 v[216:219], v[144:145], off offset:512
	global_load_dwordx4 v[220:223], v[144:145], off offset:576
	v_lshl_add_u64 v[144:145], v[144:145], 0, s[66:67]
	s_waitcnt vmcnt(4)
	v_pk_mul_f32 v[110:111], v[110:111], v[242:243]
	v_pk_mul_f32 v[108:109], v[108:109], v[240:241]
	v_pk_add_f32 v[110:111], v[110:111], v[226:227]
	v_pk_add_f32 v[108:109], v[108:109], v[224:225]
	v_pk_mul_f32 v[106:107], v[106:107], v[246:247]
	v_pk_mul_f32 v[104:105], v[104:105], v[244:245]
	v_pk_add_f32 v[106:107], v[106:107], v[230:231]
	v_pk_add_f32 v[104:105], v[104:105], v[228:229]
	v_pk_mul_f32 v[102:103], v[102:103], v[250:251]
	v_pk_mul_f32 v[100:101], v[100:101], v[248:249]
	v_pk_add_f32 v[102:103], v[102:103], v[234:235]
	v_pk_add_f32 v[100:101], v[100:101], v[232:233]
	v_pk_mul_f32 v[98:99], v[98:99], v[186:187]
	v_pk_mul_f32 v[96:97], v[96:97], v[184:185]
	v_pk_add_f32 v[98:99], v[98:99], v[238:239]
	v_pk_add_f32 v[96:97], v[96:97], v[236:237]
	v_pk_mul_f32 v[140:141], v[108:109], v[108:109]
	v_pk_fma_f32 v[140:141], v[110:111], v[110:111], v[140:141]
	v_add_f32_e32 v189, v189, v140
	v_add_f32_e32 v189, v189, v141
	v_pk_mul_f32 v[140:141], v[104:105], v[104:105]
	v_pk_fma_f32 v[140:141], v[106:107], v[106:107], v[140:141]
	v_add_f32_e32 v189, v189, v140
	v_add_f32_e32 v189, v189, v141
	v_pk_mul_f32 v[140:141], v[100:101], v[100:101]
	v_pk_fma_f32 v[140:141], v[102:103], v[102:103], v[140:141]
	v_add_f32_e32 v189, v189, v140
	v_add_f32_e32 v189, v189, v141
	v_pk_mul_f32 v[140:141], v[96:97], v[96:97]
	v_pk_fma_f32 v[140:141], v[98:99], v[98:99], v[140:141]
	v_add_f32_e32 v189, v189, v140
	v_add_f32_e32 v189, v189, v141
	global_load_dwordx4 v[224:227], v[144:145], off
	global_load_dwordx4 v[228:231], v[144:145], off offset:64
	global_load_dwordx4 v[232:235], v[144:145], off offset:512
	global_load_dwordx4 v[236:239], v[144:145], off offset:576
	v_lshl_add_u64 v[144:145], v[144:145], 0, s[68:69]
	s_waitcnt vmcnt(4)
;     __device__ __forceinline__ void operator()(const Acc& acc, const Unit& u, int wr, int wc, int fr, int fq) const {
;     ...
;             for (int m = 0; m < 4; ++m) { const int row = u.pm * 256 + ai * 128 + wr * 64 + m * 16 + fr;
;                 const float* base = xp ? (row < MP ? xp + (size_t)row * D : xs + (size_t)(row - MP) * D) : X + (size_t)row * D;
;                 const float* gp = gate + (size_t)mod_row(row) * 6144;
; #pragma unroll
;                 for (int bj = 0; bj < 2; ++bj)
; #pragma unroll
;                     for (int n = 0; n < 2; ++n) { const int col = u.pn * 256 + bj * 128 + wc * 32 + n * 16 + fq * 4;
;                         const f32x4 ga = *(const f32x4*)(gp + col) * acc[ai][bj][m][n];
;                         if (u.split) { *(f32x4*)(part + ((size_t)(u.k0 >> 8) * MS + (row - MP)) * D + col) = ga;
;                         } else *(f32x4*)(X + (size_t)row * D + col) = *(const f32x4*)(base + col) + ga; } }
; template <bool FINAL>
; __device__ __forceinline__ void norm_rows(const float* xp, const float* xs, const float* X, const float* g, const float* sh, const float* sc, bf16_t* XN, float* out, int gw, int NGW, int lane, const float* part, int nsplit) {
;     ...
;         for (int j = 0; j < 4; ++j) s += (v[j][0] * v[j][0] + v[j][1] * v[j][1]) + (v[j][2] * v[j][2] + v[j][3] * v[j][3]);
	v_pk_mul_f32 v[94:95], v[94:95], v[242:243]
	v_pk_mul_f32 v[92:93], v[92:93], v[240:241]
	v_pk_add_f32 v[94:95], v[94:95], v[210:211]
	v_pk_add_f32 v[92:93], v[92:93], v[208:209]
	v_pk_mul_f32 v[90:91], v[90:91], v[246:247]
	v_pk_mul_f32 v[88:89], v[88:89], v[244:245]
	v_pk_add_f32 v[90:91], v[90:91], v[214:215]
	v_pk_add_f32 v[88:89], v[88:89], v[212:213]
	v_pk_mul_f32 v[86:87], v[86:87], v[250:251]
	v_pk_mul_f32 v[84:85], v[84:85], v[248:249]
	v_pk_add_f32 v[86:87], v[86:87], v[218:219]
	v_pk_add_f32 v[84:85], v[84:85], v[216:217]
	v_pk_mul_f32 v[82:83], v[82:83], v[186:187]
	v_pk_mul_f32 v[80:81], v[80:81], v[184:185]
	v_pk_add_f32 v[82:83], v[82:83], v[222:223]
	v_pk_add_f32 v[80:81], v[80:81], v[220:221]
	v_pk_mul_f32 v[140:141], v[92:93], v[92:93]
	v_pk_fma_f32 v[140:141], v[94:95], v[94:95], v[140:141]
	v_add_f32_e32 v190, v190, v140
	v_add_f32_e32 v190, v190, v141
	v_pk_mul_f32 v[140:141], v[88:89], v[88:89]
	v_pk_fma_f32 v[140:141], v[90:91], v[90:91], v[140:141]
	v_add_f32_e32 v190, v190, v140
	v_add_f32_e32 v190, v190, v141
	v_pk_mul_f32 v[140:141], v[84:85], v[84:85]
	v_pk_fma_f32 v[140:141], v[86:87], v[86:87], v[140:141]
	v_add_f32_e32 v190, v190, v140
	v_add_f32_e32 v190, v190, v141
	v_pk_mul_f32 v[140:141], v[80:81], v[80:81]
	v_pk_fma_f32 v[140:141], v[82:83], v[82:83], v[140:141]
	v_add_f32_e32 v190, v190, v140
	v_add_f32_e32 v190, v190, v141
	global_load_dwordx4 v[208:211], v[144:145], off
	global_load_dwordx4 v[212:215], v[144:145], off offset:64
	global_load_dwordx4 v[216:219], v[144:145], off offset:512
	global_load_dwordx4 v[220:223], v[144:145], off offset:576
	v_lshl_add_u64 v[144:145], v[144:145], 0, s[66:67]
	s_waitcnt vmcnt(4)
	v_pk_mul_f32 v[78:79], v[78:79], v[242:243]
	v_pk_mul_f32 v[76:77], v[76:77], v[240:241]
	v_pk_add_f32 v[78:79], v[78:79], v[226:227]
	v_pk_add_f32 v[76:77], v[76:77], v[224:225]
	v_pk_mul_f32 v[74:75], v[74:75], v[246:247]
	v_pk_mul_f32 v[72:73], v[72:73], v[244:245]
	v_pk_add_f32 v[74:75], v[74:75], v[230:231]
	v_pk_add_f32 v[72:73], v[72:73], v[228:229]
	v_pk_mul_f32 v[70:71], v[70:71], v[250:251]
	v_pk_mul_f32 v[68:69], v[68:69], v[248:249]
	v_pk_add_f32 v[70:71], v[70:71], v[234:235]
	v_pk_add_f32 v[68:69], v[68:69], v[232:233]
	v_pk_mul_f32 v[66:67], v[66:67], v[186:187]
	v_pk_mul_f32 v[64:65], v[64:65], v[184:185]
	v_pk_add_f32 v[66:67], v[66:67], v[238:239]
	v_pk_add_f32 v[64:65], v[64:65], v[236:237]
	v_pk_mul_f32 v[140:141], v[76:77], v[76:77]
	v_pk_fma_f32 v[140:141], v[78:79], v[78:79], v[140:141]
	v_add_f32_e32 v191, v191, v140
	v_add_f32_e32 v191, v191, v141
	v_pk_mul_f32 v[140:141], v[72:73], v[72:73]
	v_pk_fma_f32 v[140:141], v[74:75], v[74:75], v[140:141]
	v_add_f32_e32 v191, v191, v140
	v_add_f32_e32 v191, v191, v141
	v_pk_mul_f32 v[140:141], v[68:69], v[68:69]
	v_pk_fma_f32 v[140:141], v[70:71], v[70:71], v[140:141]
	v_add_f32_e32 v191, v191, v140
	v_add_f32_e32 v191, v191, v141
	v_pk_mul_f32 v[140:141], v[64:65], v[64:65]
	v_pk_fma_f32 v[140:141], v[66:67], v[66:67], v[140:141]
	v_add_f32_e32 v191, v191, v140
	v_add_f32_e32 v191, v191, v141
	global_load_dwordx4 v[224:227], v[144:145], off
	global_load_dwordx4 v[228:231], v[144:145], off offset:64
	global_load_dwordx4 v[232:235], v[144:145], off offset:512
	global_load_dwordx4 v[236:239], v[144:145], off offset:576
	v_lshl_add_u64 v[144:145], v[144:145], 0, s[66:67]
	s_waitcnt vmcnt(4)
	v_pk_mul_f32 v[62:63], v[62:63], v[242:243]
	v_pk_mul_f32 v[60:61], v[60:61], v[240:241]
	v_pk_add_f32 v[62:63], v[62:63], v[210:211]
	v_pk_add_f32 v[60:61], v[60:61], v[208:209]
	v_pk_mul_f32 v[58:59], v[58:59], v[246:247]
	v_pk_mul_f32 v[56:57], v[56:57], v[244:245]
	v_pk_add_f32 v[58:59], v[58:59], v[214:215]
	v_pk_add_f32 v[56:57], v[56:57], v[212:213]
	v_pk_mul_f32 v[54:55], v[54:55], v[250:251]
	v_pk_mul_f32 v[52:53], v[52:53], v[248:249]
	v_pk_add_f32 v[54:55], v[54:55], v[218:219]
	v_pk_add_f32 v[52:53], v[52:53], v[216:217]
	v_pk_mul_f32 v[50:51], v[50:51], v[186:187]
	v_pk_mul_f32 v[48:49], v[48:49], v[184:185]
	v_pk_add_f32 v[50:51], v[50:51], v[222:223]
	v_pk_add_f32 v[48:49], v[48:49], v[220:221]
	v_pk_mul_f32 v[140:141], v[60:61], v[60:61]
	v_pk_fma_f32 v[140:141], v[62:63], v[62:63], v[140:141]
	v_add_f32_e32 v192, v192, v140
	v_add_f32_e32 v192, v192, v141
	v_pk_mul_f32 v[140:141], v[56:57], v[56:57]
	v_pk_fma_f32 v[140:141], v[58:59], v[58:59], v[140:141]
	v_add_f32_e32 v192, v192, v140
	v_add_f32_e32 v192, v192, v141
	v_pk_mul_f32 v[140:141], v[52:53], v[52:53]
	v_pk_fma_f32 v[140:141], v[54:55], v[54:55], v[140:141]
	v_add_f32_e32 v192, v192, v140
	v_add_f32_e32 v192, v192, v141
	v_pk_mul_f32 v[140:141], v[48:49], v[48:49]
	v_pk_fma_f32 v[140:141], v[50:51], v[50:51], v[140:141]
	v_add_f32_e32 v192, v192, v140
	v_add_f32_e32 v192, v192, v141
	global_load_dwordx4 v[208:211], v[144:145], off
	global_load_dwordx4 v[212:215], v[144:145], off offset:64
	global_load_dwordx4 v[216:219], v[144:145], off offset:512
	global_load_dwordx4 v[220:223], v[144:145], off offset:576
	v_lshl_add_u64 v[144:145], v[144:145], 0, s[66:67]
	s_waitcnt vmcnt(4)
; #define SWZ(v, pat) __builtin_bit_cast(float, __builtin_amdgcn_ds_swizzle(__builtin_bit_cast(int, (v)), (pat)))
; __device__ __forceinline__ float xor32_sum(float v) { float a = v, b = v; asm volatile("s_nop 1\n\tv_permlane32_swap_b32 %0, %1\n\ts_nop 1" : "+v"(a), "+v"(b)); return a + b; }
; __device__ __forceinline__ float wave_sum(float v) {
;     v += SWZ(v, 0x041f); v += SWZ(v, 0x081f); v += SWZ(v, 0x101f); v += SWZ(v, 0x201f); v += SWZ(v, 0x401f); return xor32_sum(v);
; }
; template <bool FINAL>
; __device__ __forceinline__ void norm_rows(const float* xp, const float* xs, const float* X, const float* g, const float* sh, const float* sc, bf16_t* XN, float* out, int gw, int NGW, int lane, const float* part, int nsplit) {
;     ...
;         for (int j = 0; j < 4; ++j) s += (v[j][0] * v[j][0] + v[j][1] * v[j][1]) + (v[j][2] * v[j][2] + v[j][3] * v[j][3]);
;         const float rstd = 1.0f / sqrtf(wave_sum(s) * (1.0f / D) + EPS);
	v_pk_mul_f32 v[46:47], v[46:47], v[242:243]
	v_pk_mul_f32 v[44:45], v[44:45], v[240:241]
	v_pk_add_f32 v[46:47], v[46:47], v[226:227]
	v_pk_add_f32 v[44:45], v[44:45], v[224:225]
	v_pk_mul_f32 v[42:43], v[42:43], v[246:247]
	v_pk_mul_f32 v[40:41], v[40:41], v[244:245]
	v_pk_add_f32 v[42:43], v[42:43], v[230:231]
	v_pk_add_f32 v[40:41], v[40:41], v[228:229]
	v_pk_mul_f32 v[38:39], v[38:39], v[250:251]
	v_pk_mul_f32 v[36:37], v[36:37], v[248:249]
	v_pk_add_f32 v[38:39], v[38:39], v[234:235]
	v_pk_add_f32 v[36:37], v[36:37], v[232:233]
	v_pk_mul_f32 v[34:35], v[34:35], v[186:187]
	v_pk_mul_f32 v[32:33], v[32:33], v[184:185]
	v_pk_add_f32 v[34:35], v[34:35], v[238:239]
	v_pk_add_f32 v[32:33], v[32:33], v[236:237]
	v_pk_mul_f32 v[140:141], v[44:45], v[44:45]
	v_pk_fma_f32 v[140:141], v[46:47], v[46:47], v[140:141]
	v_add_f32_e32 v193, v193, v140
	v_add_f32_e32 v193, v193, v141
	v_pk_mul_f32 v[140:141], v[40:41], v[40:41]
	v_pk_fma_f32 v[140:141], v[42:43], v[42:43], v[140:141]
	v_add_f32_e32 v193, v193, v140
	v_add_f32_e32 v193, v193, v141
	v_pk_mul_f32 v[140:141], v[36:37], v[36:37]
	v_pk_fma_f32 v[140:141], v[38:39], v[38:39], v[140:141]
	v_add_f32_e32 v193, v193, v140
	v_add_f32_e32 v193, v193, v141
	v_pk_mul_f32 v[140:141], v[32:33], v[32:33]
	v_pk_fma_f32 v[140:141], v[34:35], v[34:35], v[140:141]
	v_add_f32_e32 v193, v193, v140
	v_add_f32_e32 v193, v193, v141
	global_load_dwordx4 v[224:227], v[144:145], off
	global_load_dwordx4 v[228:231], v[144:145], off offset:64
	global_load_dwordx4 v[232:235], v[144:145], off offset:512
	global_load_dwordx4 v[236:239], v[144:145], off offset:576
	s_waitcnt vmcnt(4)
	v_pk_mul_f32 v[30:31], v[30:31], v[242:243]
	v_pk_mul_f32 v[28:29], v[28:29], v[240:241]
	v_pk_add_f32 v[30:31], v[30:31], v[210:211]
	v_pk_add_f32 v[28:29], v[28:29], v[208:209]
	v_pk_mul_f32 v[26:27], v[26:27], v[246:247]
	v_pk_mul_f32 v[24:25], v[24:25], v[244:245]
	v_pk_add_f32 v[26:27], v[26:27], v[214:215]
	v_pk_add_f32 v[24:25], v[24:25], v[212:213]
	v_pk_mul_f32 v[22:23], v[22:23], v[250:251]
	v_pk_mul_f32 v[20:21], v[20:21], v[248:249]
	v_pk_add_f32 v[22:23], v[22:23], v[218:219]
	v_pk_add_f32 v[20:21], v[20:21], v[216:217]
	v_pk_mul_f32 v[18:19], v[18:19], v[186:187]
	v_pk_mul_f32 v[16:17], v[16:17], v[184:185]
	v_pk_add_f32 v[18:19], v[18:19], v[222:223]
	v_pk_add_f32 v[16:17], v[16:17], v[220:221]
	v_pk_mul_f32 v[140:141], v[28:29], v[28:29]
	v_pk_fma_f32 v[140:141], v[30:31], v[30:31], v[140:141]
	v_add_f32_e32 v194, v194, v140
	v_add_f32_e32 v194, v194, v141
	v_pk_mul_f32 v[140:141], v[24:25], v[24:25]
	v_pk_fma_f32 v[140:141], v[26:27], v[26:27], v[140:141]
	v_add_f32_e32 v194, v194, v140
	v_add_f32_e32 v194, v194, v141
	v_pk_mul_f32 v[140:141], v[20:21], v[20:21]
	v_pk_fma_f32 v[140:141], v[22:23], v[22:23], v[140:141]
	v_add_f32_e32 v194, v194, v140
	v_add_f32_e32 v194, v194, v141
	v_pk_mul_f32 v[140:141], v[16:17], v[16:17]
	v_pk_fma_f32 v[140:141], v[18:19], v[18:19], v[140:141]
	v_add_f32_e32 v194, v194, v140
	v_add_f32_e32 v194, v194, v141
	s_waitcnt vmcnt(0)
	v_pk_mul_f32 v[14:15], v[14:15], v[242:243]
	v_pk_mul_f32 v[12:13], v[12:13], v[240:241]
	v_pk_add_f32 v[14:15], v[14:15], v[226:227]
	v_pk_add_f32 v[12:13], v[12:13], v[224:225]
	v_pk_mul_f32 v[10:11], v[10:11], v[246:247]
	v_pk_mul_f32 v[8:9], v[8:9], v[244:245]
	v_pk_add_f32 v[10:11], v[10:11], v[230:231]
	v_pk_add_f32 v[8:9], v[8:9], v[228:229]
	v_pk_mul_f32 v[6:7], v[6:7], v[250:251]
	v_pk_mul_f32 v[4:5], v[4:5], v[248:249]
	v_pk_add_f32 v[6:7], v[6:7], v[234:235]
	v_pk_add_f32 v[4:5], v[4:5], v[232:233]
	v_pk_mul_f32 v[2:3], v[2:3], v[186:187]
	v_pk_mul_f32 v[0:1], v[0:1], v[184:185]
	v_pk_add_f32 v[2:3], v[2:3], v[238:239]
	v_pk_add_f32 v[0:1], v[0:1], v[236:237]
	v_pk_mul_f32 v[140:141], v[12:13], v[12:13]
	v_pk_fma_f32 v[140:141], v[14:15], v[14:15], v[140:141]
	v_add_f32_e32 v195, v195, v140
	v_add_f32_e32 v195, v195, v141
	v_pk_mul_f32 v[140:141], v[8:9], v[8:9]
	v_pk_fma_f32 v[140:141], v[10:11], v[10:11], v[140:141]
	v_add_f32_e32 v195, v195, v140
	v_add_f32_e32 v195, v195, v141
	v_pk_mul_f32 v[140:141], v[4:5], v[4:5]
	v_pk_fma_f32 v[140:141], v[6:7], v[6:7], v[140:141]
	v_add_f32_e32 v195, v195, v140
	v_add_f32_e32 v195, v195, v141
	v_pk_mul_f32 v[140:141], v[0:1], v[0:1]
	v_pk_fma_f32 v[140:141], v[2:3], v[2:3], v[140:141]
	v_add_f32_e32 v195, v195, v140
	v_add_f32_e32 v195, v195, v141
	ds_swizzle_b32 v208, v188 offset:swizzle(SWAP,16)
	ds_swizzle_b32 v209, v189 offset:swizzle(SWAP,16)
	ds_swizzle_b32 v210, v190 offset:swizzle(SWAP,16)
	ds_swizzle_b32 v211, v191 offset:swizzle(SWAP,16)
	ds_swizzle_b32 v212, v192 offset:swizzle(SWAP,16)
	ds_swizzle_b32 v213, v193 offset:swizzle(SWAP,16)
	ds_swizzle_b32 v214, v194 offset:swizzle(SWAP,16)
	ds_swizzle_b32 v215, v195 offset:swizzle(SWAP,16)
	s_waitcnt lgkmcnt(0)
	v_add_f32_e32 v188, v188, v208
	v_add_f32_e32 v189, v189, v209
	v_add_f32_e32 v190, v190, v210
	v_add_f32_e32 v191, v191, v211
	v_add_f32_e32 v192, v192, v212
	v_add_f32_e32 v193, v193, v213
	v_add_f32_e32 v194, v194, v214
	v_add_f32_e32 v195, v195, v215
	v_mov_b32_e32 v208, v188
	v_mov_b32_e32 v209, v189
	v_mov_b32_e32 v210, v190
	v_mov_b32_e32 v211, v191
	v_mov_b32_e32 v212, v192
	v_mov_b32_e32 v213, v193
	v_mov_b32_e32 v214, v194
	v_mov_b32_e32 v215, v195
	s_nop 1
	v_permlane32_swap_b32 v188, v208
	v_permlane32_swap_b32 v189, v209
	v_permlane32_swap_b32 v190, v210
	v_permlane32_swap_b32 v191, v211
	v_permlane32_swap_b32 v192, v212
	v_permlane32_swap_b32 v193, v213
	v_permlane32_swap_b32 v194, v214
	v_permlane32_swap_b32 v195, v215
	s_nop 1
	v_add_f32_e32 v188, v188, v208
	v_add_f32_e32 v189, v189, v209
	v_add_f32_e32 v190, v190, v210
	v_add_f32_e32 v191, v191, v211
	v_add_f32_e32 v192, v192, v212
	v_add_f32_e32 v193, v193, v213
	v_add_f32_e32 v194, v194, v214
	v_add_f32_e32 v195, v195, v215
	v_readlane_b32 s25, v253, 2
	s_nop 3
	s_and_b32 s27, s25, 3
	s_lshl_b32 s27, s27, 10
	s_add_i32 s27, s27, 0x20800
	v_lshl_add_u32 v143, v142, 2, s27
	ds_write_b32 v143, v188
	ds_write_b32 v143, v189 offset:64
	ds_write_b32 v143, v190 offset:128
	ds_write_b32 v143, v191 offset:192
	ds_write_b32 v143, v192 offset:512
	ds_write_b32 v143, v193 offset:576
	ds_write_b32 v143, v194 offset:640
	ds_write_b32 v143, v195 offset:704
	v_mbcnt_lo_u32_b32 v207, -1, 0
	v_mbcnt_hi_u32_b32 v207, -1, v207
	s_lshl_b32 s27, s25, 6
	v_add_u32_e32 v207, s27, v207
	v_lshlrev_b32_e32 v207, 2, v207
	s_sub_u32 s70, s10, 0x7800000
	s_subb_u32 s71, s11, 0
	s_lshl_b32 s74, s55, 10
	s_add_u32 s70, s70, s74
	s_addc_u32 s71, s71, 0
	s_sub_u32 s98, s10, 0x7dfffc0
	s_subb_u32 s99, s11, 0
	s_lshl_b32 s74, s55, 2
	s_add_u32 s98, s98, s74
	s_addc_u32 s99, s99, 0
	s_lshl_b32 s32, s96, 3
	s_add_i32 s32, s32, 8
	s_waitcnt lgkmcnt(0)
	s_barrier
; template <bool FINAL>
; __device__ __forceinline__ void norm_rows(const float* xp, const float* xs, const float* X, const float* g, const float* sh, const float* sc, bf16_t* XN, float* out, int gw, int NGW, int lane, const float* part, int nsplit) {
;     ...
;         const float rstd = 1.0f / sqrtf(wave_sum(s) * (1.0f / D) + EPS);
;         const int mr = mod_row(row);
;         if (!FINAL && xp && row >= MP) {
; #pragma unroll
;             for (int j = 0; j < 4; ++j) *(f32x4*)((float*)X + (size_t)row * D + 4 * lane + 256 * j) = v[j]; }
; #pragma unroll
;         for (int j = 0; j < 4; ++j) { const int col = 4 * lane + 256 * j; const f32x4 gg = *(const f32x4*)(g + col);
;             if (FINAL) { *(f32x4*)(out + (size_t)row * D + col) = v[j] * rstd * gg; }
	s_cmp_lt_u32 s25, 4
	s_cbranch_scc0 .Lfz_dnf_nopub
	v_add_u32_e32 v140, 0x20800, v207
	ds_read_b32 v212, v140
	ds_read_b32 v213, v140 offset:1024
	ds_read_b32 v214, v140 offset:2048
	ds_read_b32 v215, v140 offset:3072
	s_lshl_b32 s74, s53, 16
	v_add_u32_e32 v141, s74, v207
	s_waitcnt lgkmcnt(0)
	v_add_f32_e32 v212, v212, v213
	v_add_f32_e32 v212, v212, v214
	v_add_f32_e32 v212, v212, v215
	global_store_dword v141, v212, s[70:71] sc0 sc1
.Lfz_dnf_nopub:
	s_waitcnt vmcnt(0)
	s_barrier
	v_mov_b32_e32 v140, 0x20508
	ds_read_b64 v[140:141], v140
	s_waitcnt lgkmcnt(0)
	v_readfirstlane_b32 s2, v140
	v_readfirstlane_b32 s3, v141
	s_nop 4
	global_load_dwordx4 v[208:211], v159, s[2:3]
	global_load_dwordx4 v[212:215], v159, s[2:3] offset:64
	global_load_dwordx4 v[216:219], v159, s[2:3] offset:512
	global_load_dwordx4 v[220:223], v159, s[2:3] offset:576
	s_cmp_eq_u32 s25, 0
	s_cbranch_scc0 .Lfz_dnf_nopoll
	s_mov_b64 exec, 1
	v_mov_b32_e32 v140, 0
	v_mov_b32_e32 v141, 1
	global_atomic_add v140, v141, s[98:99]
	s_mov_b32 s65, 0

; template <bool FINAL>
; __device__ __forceinline__ void norm_rows(const float* xp, const float* xs, const float* X, const float* g, const float* sh, const float* sc, bf16_t* XN, float* out, int gw, int NGW, int lane, const float* part, int nsplit) {
;     ...
;         for (int j = 0; j < 4; ++j) { const int col = 4 * lane + 256 * j; const f32x4 gg = *(const f32x4*)(g + col);
;             if (FINAL) { *(f32x4*)(out + (size_t)row * D + col) = v[j] * rstd * gg; }
.Lfz_dnf_norstd:
	s_waitcnt lgkmcnt(0)
	s_barrier
	v_lshlrev_b32_e32 v130, 2, v142
	v_add_u32_e32 v130, 0x21800, v130
	ds_read_b32 v188, v130
	ds_read_b32 v189, v130 offset:64
	ds_read_b32 v190, v130 offset:128
	ds_read_b32 v191, v130 offset:192
	ds_read_b32 v192, v130 offset:512
	ds_read_b32 v193, v130 offset:576
	ds_read_b32 v194, v130 offset:640
	ds_read_b32 v195, v130 offset:704
	s_waitcnt vmcnt(0) lgkmcnt(0)
	v_mul_f32_e32 v124, v124, v188
	v_mul_f32_e32 v125, v125, v188
	v_mul_f32_e32 v126, v126, v188
	v_mul_f32_e32 v127, v127, v188
	v_pk_mul_f32 v[124:125], v[208:209], v[124:125]
	v_pk_mul_f32 v[126:127], v[210:211], v[126:127]
	global_store_dwordx4 v[146:147], v[124:127], off
	v_mul_f32_e32 v120, v120, v188
	v_mul_f32_e32 v121, v121, v188
	v_mul_f32_e32 v122, v122, v188
	v_mul_f32_e32 v123, v123, v188
	v_pk_mul_f32 v[120:121], v[212:213], v[120:121]
	v_pk_mul_f32 v[122:123], v[214:215], v[122:123]
	global_store_dwordx4 v[146:147], v[120:123], off offset:64
	v_mul_f32_e32 v116, v116, v188
	v_mul_f32_e32 v117, v117, v188
	v_mul_f32_e32 v118, v118, v188
	v_mul_f32_e32 v119, v119, v188
	v_pk_mul_f32 v[116:117], v[216:217], v[116:117]
	v_pk_mul_f32 v[118:119], v[218:219], v[118:119]
	global_store_dwordx4 v[146:147], v[116:119], off offset:512
	v_mul_f32_e32 v112, v112, v188
	v_mul_f32_e32 v113, v113, v188
	v_mul_f32_e32 v114, v114, v188
	v_mul_f32_e32 v115, v115, v188
	v_pk_mul_f32 v[112:113], v[220:221], v[112:113]
	v_pk_mul_f32 v[114:115], v[222:223], v[114:115]
	global_store_dwordx4 v[146:147], v[112:115], off offset:576
	v_lshl_add_u64 v[146:147], v[146:147], 0, s[66:67]
	v_mul_f32_e32 v108, v108, v189
	v_mul_f32_e32 v109, v109, v189
	v_mul_f32_e32 v110, v110, v189
	v_mul_f32_e32 v111, v111, v189
	v_pk_mul_f32 v[108:109], v[208:209], v[108:109]
	v_pk_mul_f32 v[110:111], v[210:211], v[110:111]
	global_store_dwordx4 v[146:147], v[108:111], off
	v_mul_f32_e32 v104, v104, v189
	v_mul_f32_e32 v105, v105, v189
	v_mul_f32_e32 v106, v106, v189
	v_mul_f32_e32 v107, v107, v189
	v_pk_mul_f32 v[104:105], v[212:213], v[104:105]
	v_pk_mul_f32 v[106:107], v[214:215], v[106:107]
	global_store_dwordx4 v[146:147], v[104:107], off offset:64
	v_mul_f32_e32 v100, v100, v189
	v_mul_f32_e32 v101, v101, v189
	v_mul_f32_e32 v102, v102, v189
	v_mul_f32_e32 v103, v103, v189
	v_pk_mul_f32 v[100:101], v[216:217], v[100:101]
	v_pk_mul_f32 v[102:103], v[218:219], v[102:103]
	global_store_dwordx4 v[146:147], v[100:103], off offset:512
	v_mul_f32_e32 v96, v96, v189
	v_mul_f32_e32 v97, v97, v189
	v_mul_f32_e32 v98, v98, v189
	v_mul_f32_e32 v99, v99, v189
	v_pk_mul_f32 v[96:97], v[220:221], v[96:97]
	v_pk_mul_f32 v[98:99], v[222:223], v[98:99]
	global_store_dwordx4 v[146:147], v[96:99], off offset:576
	v_lshl_add_u64 v[146:147], v[146:147], 0, s[66:67]
	v_mul_f32_e32 v92, v92, v190
	v_mul_f32_e32 v93, v93, v190
	v_mul_f32_e32 v94, v94, v190
	v_mul_f32_e32 v95, v95, v190
	v_pk_mul_f32 v[92:93], v[208:209], v[92:93]
	v_pk_mul_f32 v[94:95], v[210:211], v[94:95]
	global_store_dwordx4 v[146:147], v[92:95], off
	v_mul_f32_e32 v88, v88, v190
	v_mul_f32_e32 v89, v89, v190
	v_mul_f32_e32 v90, v90, v190
	v_mul_f32_e32 v91, v91, v190
	v_pk_mul_f32 v[88:89], v[212:213], v[88:89]
	v_pk_mul_f32 v[90:91], v[214:215], v[90:91]
	global_store_dwordx4 v[146:147], v[88:91], off offset:64
	v_mul_f32_e32 v84, v84, v190
	v_mul_f32_e32 v85, v85, v190
	v_mul_f32_e32 v86, v86, v190
	v_mul_f32_e32 v87, v87, v190
	v_pk_mul_f32 v[84:85], v[216:217], v[84:85]
	v_pk_mul_f32 v[86:87], v[218:219], v[86:87]
	global_store_dwordx4 v[146:147], v[84:87], off offset:512
	v_mul_f32_e32 v80, v80, v190
	v_mul_f32_e32 v81, v81, v190
	v_mul_f32_e32 v82, v82, v190
	v_mul_f32_e32 v83, v83, v190
	v_pk_mul_f32 v[80:81], v[220:221], v[80:81]
	v_pk_mul_f32 v[82:83], v[222:223], v[82:83]
	global_store_dwordx4 v[146:147], v[80:83], off offset:576
	v_lshl_add_u64 v[146:147], v[146:147], 0, s[66:67]
	v_mul_f32_e32 v76, v76, v191
	v_mul_f32_e32 v77, v77, v191
	v_mul_f32_e32 v78, v78, v191
	v_mul_f32_e32 v79, v79, v191
	v_pk_mul_f32 v[76:77], v[208:209], v[76:77]
	v_pk_mul_f32 v[78:79], v[210:211], v[78:79]
	global_store_dwordx4 v[146:147], v[76:79], off
	v_mul_f32_e32 v72, v72, v191
	v_mul_f32_e32 v73, v73, v191
	v_mul_f32_e32 v74, v74, v191
	v_mul_f32_e32 v75, v75, v191
	v_pk_mul_f32 v[72:73], v[212:213], v[72:73]
	v_pk_mul_f32 v[74:75], v[214:215], v[74:75]
	global_store_dwordx4 v[146:147], v[72:75], off offset:64
	v_mul_f32_e32 v68, v68, v191
	v_mul_f32_e32 v69, v69, v191
	v_mul_f32_e32 v70, v70, v191
	v_mul_f32_e32 v71, v71, v191
	v_pk_mul_f32 v[68:69], v[216:217], v[68:69]
	v_pk_mul_f32 v[70:71], v[218:219], v[70:71]
	global_store_dwordx4 v[146:147], v[68:71], off offset:512
; template <bool FINAL>
; __device__ __forceinline__ void norm_rows(const float* xp, const float* xs, const float* X, const float* g, const float* sh, const float* sc, bf16_t* XN, float* out, int gw, int NGW, int lane, const float* part, int nsplit) {
;     ...
;         for (int j = 0; j < 4; ++j) { const int col = 4 * lane + 256 * j; const f32x4 gg = *(const f32x4*)(g + col);
;             if (FINAL) { *(f32x4*)(out + (size_t)row * D + col) = v[j] * rstd * gg; }
	v_mul_f32_e32 v64, v64, v191
	v_mul_f32_e32 v65, v65, v191
	v_mul_f32_e32 v66, v66, v191
	v_mul_f32_e32 v67, v67, v191
	v_pk_mul_f32 v[64:65], v[220:221], v[64:65]
	v_pk_mul_f32 v[66:67], v[222:223], v[66:67]
	global_store_dwordx4 v[146:147], v[64:67], off offset:576
	v_lshl_add_u64 v[146:147], v[146:147], 0, s[68:69]
	v_mul_f32_e32 v60, v60, v192
	v_mul_f32_e32 v61, v61, v192
	v_mul_f32_e32 v62, v62, v192
	v_mul_f32_e32 v63, v63, v192
	v_pk_mul_f32 v[60:61], v[208:209], v[60:61]
	v_pk_mul_f32 v[62:63], v[210:211], v[62:63]
	global_store_dwordx4 v[146:147], v[60:63], off
	v_mul_f32_e32 v56, v56, v192
	v_mul_f32_e32 v57, v57, v192
	v_mul_f32_e32 v58, v58, v192
	v_mul_f32_e32 v59, v59, v192
	v_pk_mul_f32 v[56:57], v[212:213], v[56:57]
	v_pk_mul_f32 v[58:59], v[214:215], v[58:59]
	global_store_dwordx4 v[146:147], v[56:59], off offset:64
	v_mul_f32_e32 v52, v52, v192
	v_mul_f32_e32 v53, v53, v192
	v_mul_f32_e32 v54, v54, v192
	v_mul_f32_e32 v55, v55, v192
	v_pk_mul_f32 v[52:53], v[216:217], v[52:53]
	v_pk_mul_f32 v[54:55], v[218:219], v[54:55]
	global_store_dwordx4 v[146:147], v[52:55], off offset:512
	v_mul_f32_e32 v48, v48, v192
	v_mul_f32_e32 v49, v49, v192
	v_mul_f32_e32 v50, v50, v192
	v_mul_f32_e32 v51, v51, v192
	v_pk_mul_f32 v[48:49], v[220:221], v[48:49]
	v_pk_mul_f32 v[50:51], v[222:223], v[50:51]
	global_store_dwordx4 v[146:147], v[48:51], off offset:576
	v_lshl_add_u64 v[146:147], v[146:147], 0, s[66:67]
	v_mul_f32_e32 v44, v44, v193
	v_mul_f32_e32 v45, v45, v193
	v_mul_f32_e32 v46, v46, v193
	v_mul_f32_e32 v47, v47, v193
	v_pk_mul_f32 v[44:45], v[208:209], v[44:45]
	v_pk_mul_f32 v[46:47], v[210:211], v[46:47]
	global_store_dwordx4 v[146:147], v[44:47], off
	v_mul_f32_e32 v40, v40, v193
	v_mul_f32_e32 v41, v41, v193
	v_mul_f32_e32 v42, v42, v193
	v_mul_f32_e32 v43, v43, v193
	v_pk_mul_f32 v[40:41], v[212:213], v[40:41]
	v_pk_mul_f32 v[42:43], v[214:215], v[42:43]
	global_store_dwordx4 v[146:147], v[40:43], off offset:64
	v_mul_f32_e32 v36, v36, v193
	v_mul_f32_e32 v37, v37, v193
	v_mul_f32_e32 v38, v38, v193
	v_mul_f32_e32 v39, v39, v193
	v_pk_mul_f32 v[36:37], v[216:217], v[36:37]
	v_pk_mul_f32 v[38:39], v[218:219], v[38:39]
	global_store_dwordx4 v[146:147], v[36:39], off offset:512
	v_mul_f32_e32 v32, v32, v193
	v_mul_f32_e32 v33, v33, v193
	v_mul_f32_e32 v34, v34, v193
	v_mul_f32_e32 v35, v35, v193
	v_pk_mul_f32 v[32:33], v[220:221], v[32:33]
	v_pk_mul_f32 v[34:35], v[222:223], v[34:35]
	global_store_dwordx4 v[146:147], v[32:35], off offset:576
	v_lshl_add_u64 v[146:147], v[146:147], 0, s[66:67]
	v_mul_f32_e32 v28, v28, v194
	v_mul_f32_e32 v29, v29, v194
	v_mul_f32_e32 v30, v30, v194
	v_mul_f32_e32 v31, v31, v194
	v_pk_mul_f32 v[28:29], v[208:209], v[28:29]
	v_pk_mul_f32 v[30:31], v[210:211], v[30:31]
	global_store_dwordx4 v[146:147], v[28:31], off
	v_mul_f32_e32 v24, v24, v194
	v_mul_f32_e32 v25, v25, v194
	v_mul_f32_e32 v26, v26, v194
	v_mul_f32_e32 v27, v27, v194
	v_pk_mul_f32 v[24:25], v[212:213], v[24:25]
	v_pk_mul_f32 v[26:27], v[214:215], v[26:27]
	global_store_dwordx4 v[146:147], v[24:27], off offset:64
	v_mul_f32_e32 v20, v20, v194
	v_mul_f32_e32 v21, v21, v194
	v_mul_f32_e32 v22, v22, v194
	v_mul_f32_e32 v23, v23, v194
	v_pk_mul_f32 v[20:21], v[216:217], v[20:21]
	v_pk_mul_f32 v[22:23], v[218:219], v[22:23]
	global_store_dwordx4 v[146:147], v[20:23], off offset:512
	v_mul_f32_e32 v16, v16, v194
	v_mul_f32_e32 v17, v17, v194
	v_mul_f32_e32 v18, v18, v194
	v_mul_f32_e32 v19, v19, v194
	v_pk_mul_f32 v[16:17], v[220:221], v[16:17]
	v_pk_mul_f32 v[18:19], v[222:223], v[18:19]
	global_store_dwordx4 v[146:147], v[16:19], off offset:576
	v_lshl_add_u64 v[146:147], v[146:147], 0, s[66:67]
	v_mul_f32_e32 v12, v12, v195
	v_mul_f32_e32 v13, v13, v195
	v_mul_f32_e32 v14, v14, v195
	v_mul_f32_e32 v15, v15, v195
	v_pk_mul_f32 v[12:13], v[208:209], v[12:13]
	v_pk_mul_f32 v[14:15], v[210:211], v[14:15]
	global_store_dwordx4 v[146:147], v[12:15], off
	v_mul_f32_e32 v8, v8, v195
	v_mul_f32_e32 v9, v9, v195
	v_mul_f32_e32 v10, v10, v195
	v_mul_f32_e32 v11, v11, v195
	v_pk_mul_f32 v[8:9], v[212:213], v[8:9]
	v_pk_mul_f32 v[10:11], v[214:215], v[10:11]
	global_store_dwordx4 v[146:147], v[8:11], off offset:64
	v_mul_f32_e32 v4, v4, v195
	v_mul_f32_e32 v5, v5, v195
	v_mul_f32_e32 v6, v6, v195
	v_mul_f32_e32 v7, v7, v195
	v_pk_mul_f32 v[4:5], v[216:217], v[4:5]
	v_pk_mul_f32 v[6:7], v[218:219], v[6:7]
	global_store_dwordx4 v[146:147], v[4:7], off offset:512
	v_mul_f32_e32 v0, v0, v195
	v_mul_f32_e32 v1, v1, v195
	v_mul_f32_e32 v2, v2, v195
	v_mul_f32_e32 v3, v3, v195
	v_pk_mul_f32 v[0:1], v[220:221], v[0:1]
	v_pk_mul_f32 v[2:3], v[222:223], v[2:3]
	global_store_dwordx4 v[146:147], v[0:3], off offset:576
	s_branch .Lepi_dn_done

; #define INP(i) ((const float*)ld_ptr(pb, (i)))
; template <bool FINAL>
; __device__ __forceinline__ void norm_rows(const float* xp, const float* xs, const float* X, const float* g, const float* sh, const float* sc, bf16_t* XN, float* out, int gw, int NGW, int lane, const float* part, int nsplit) {
;     f32x4 vnext[4];
;     if (gw < M) { const float* xr0 = xp ? (gw < MP ? xp + (size_t)gw * D : xs + (size_t)(gw - MP) * D) : X + (size_t)gw * D;
; #pragma unroll
;         for (int j = 0; j < 4; ++j) vnext[j] = *(const f32x4*)(xr0 + 4 * lane + 256 * j); }
;     for (int row = gw; row < M; row += NGW) {
;         f32x4 v[4]; float s = 0.f;
; #pragma unroll
;         for (int j = 0; j < 4; ++j) v[j] = vnext[j];
;         { const int rn = row + NGW; if (rn < M) { const float* xrn = xp ? (rn < MP ? xp + (size_t)rn * D : xs + (size_t)(rn - MP) * D) : X + (size_t)rn * D;
; #pragma unroll
;             for (int j = 0; j < 4; ++j) vnext[j] = *(const f32x4*)(xrn + 4 * lane + 256 * j); } }
; __global__ void __launch_bounds__(512, 2) hybrid_fwd(Params P) {
;     ...
;         if (l + 1 < DEPTH) norm_rows<false>(nullptr, nullptr, X, INP(9) + (l + 1) * D, (MOD + (size_t)l * NMODROWS * 6144) + (size_t)NMODROWS * 6144, (MOD + (size_t)l * NMODROWS * 6144) + (size_t)NMODROWS * 6144 + 1024, XN, nullptr, gw, NGW, lane, (const float*)(ws + WS_PART), DFF / 256);
;         else norm_rows<true>(nullptr, nullptr, X, INP(33), nullptr, nullptr, nullptr, out, gw, NGW, lane, (const float*)(ws + WS_PART), DFF / 256);
.LBB0_2087:
	v_readlane_b32 s1, v253, 7
	v_readlane_b32 s18, v253, 1
	v_readlane_b32 s0, v253, 0
	v_readlane_b32 s14, v253, 2
	v_mov_b32_e32 v207, s1
	v_mbcnt_lo_u32_b32 v160, -1, 0
	v_mbcnt_hi_u32_b32 v160, -1, v160
	ds_read2_b64 v[0:3], v207 offset0:34 offset1:35
	s_lshl_b32 s0, s0, 3
	s_lshl_b32 s4, s18, 3
	s_add_i32 s6, s0, s14
	s_add_i32 s6, s6, 0x4000
	s_cmp_eq_u32 s96, 3
	s_waitcnt lgkmcnt(0)
	v_readfirstlane_b32 s3, v3
	v_readfirstlane_b32 s2, v2
	v_readfirstlane_b32 s15, v1
	v_readfirstlane_b32 s16, v0
	s_mov_b64 s[0:1], -1
	s_mov_b32 s17, 0x200000
	s_mov_b32 s19, 0x600000
	s_mov_b32 s22, 0x800000
	s_cbranch_scc1 .LBB0_2096
	ds_read_b64 v[0:1], v207 offset:72
	s_cmpk_gt_i32 s6, 0x41ff
	s_waitcnt lgkmcnt(0)
	v_readfirstlane_b32 s0, v1
	v_readfirstlane_b32 s1, v0
	s_cbranch_scc1 .LBB0_2095
	s_mul_i32 s74, s96, 0xc6000
	s_lshl_b64 s[8:9], s[74:75], 2
	s_add_u32 s8, s2, s8
	s_addc_u32 s9, s3, s9
	s_add_u32 s10, s2, 0x7e00000
	s_addc_u32 s11, s3, 0
	s_lshl_b32 s74, s96, 10
	s_lshl_b64 s[12:13], s[74:75], 2
	s_add_u32 s12, s1, s12
	s_addc_u32 s13, s0, s13
	s_ashr_i32 s7, s6, 31
	s_lshl_b64 s[0:1], s[6:7], 12
	v_lshlrev_b32_e32 v0, 2, v160
	s_add_u32 s0, s10, s0
	v_ashrrev_i32_e32 v1, 31, v0
	s_addc_u32 s1, s11, s1
	v_lshlrev_b64 v[2:3], 2, v[0:1]
	v_lshl_add_u64 v[4:5], s[0:1], 0, v[2:3]
	global_load_dwordx4 v[24:27], v[4:5], off
	global_load_dwordx4 v[20:23], v[4:5], off offset:1024
	global_load_dwordx4 v[16:19], v[4:5], off offset:2048
	global_load_dwordx4 v[28:31], v[4:5], off offset:3072
	v_lshl_add_u64 v[4:5], s[2:3], 0, v[2:3]
	s_mov_b64 s[0:1], 0x13c00000
	v_lshl_add_u64 v[184:185], v[4:5], 0, s[0:1]
	v_lshl_add_u64 v[4:5], s[12:13], 0, v[2:3]
	s_mov_b64 s[0:1], 0x1000
	v_lshl_add_u64 v[186:187], s[10:11], 0, v[2:3]
	v_lshl_add_u64 v[188:189], v[4:5], 0, s[0:1]
	v_lshl_add_u64 v[2:3], s[8:9], 0, v[2:3]
	s_mov_b64 s[0:1], 0xb19000
	v_lshl_add_u64 v[190:191], v[2:3], 0, s[0:1]
	s_mov_b64 s[0:1], 0xb18000
	v_lshl_add_u64 v[192:193], v[2:3], 0, s[0:1]
	s_lshl_b64 s[0:1], s[6:7], 11
	s_add_u32 s0, s2, s0
	s_addc_u32 s1, s3, s1
	v_lshl_add_u64 v[0:1], v[0:1], 1, s[0:1]
	s_mov_b64 s[0:1], 0xc000000
	s_ashr_i32 s5, s4, 31
	v_lshl_add_u64 v[194:195], v[0:1], 0, s[0:1]
	s_lshl_b64 s[8:9], s[4:5], 11
	s_mov_b32 s0, s6
	s_branch .LBB0_2091
